# tile start: first K iteration's 16 LDS operand reads issued before the scalar next-unit coordinate code
# speedup vs baseline: 1.0060x; 1.0060x over previous
; #define PG8_STAGE(bufoff, gbase, voff) do { _Pragma("unroll") for (int _i = 0; _i < 2; ++_i) \
;         __builtin_amdgcn_global_load_lds((const unsigned*)((const char*)(gbase) + (voff)[_i]), (PG8_LAS unsigned*)(lds + (bufoff) + ldsw + _i * 8192), 16, 0, 0); } while (0)
; #define PG8_LDA(dst, b, h) do { _Pragma("unroll") for (int m = 0; m < 4; ++m) _Pragma("unroll") for (int k = 0; k < 2; ++k) dst[m][k] = *(const PG8_LAS bf16x8*)(lds + PG8_SA(b, h) + aoff + m * 2048 + k * 1024); } while (0)
; #define PG8_LDB(dst, b, h) do { _Pragma("unroll") for (int n = 0; n < 2; ++n) _Pragma("unroll") for (int k = 0; k < 2; ++k) dst[n][k] = *(const PG8_LAS bf16x8*)(lds + PG8_SB(b, h) + boff + n * 2048 + k * 1024); } while (0)
; #define PG8_BAR __builtin_amdgcn_s_barrier()
;     __host__ __device__ bool next(int i, Unit& u) const {
;         const long L = (long)i * G + c; if (L >= nwg) return false;
;         int wgid = (int)L; { const int q = nwg / NXCD, r = nwg % NXCD, xcd = wgid % NXCD, off = wgid / NXCD; wgid = (xcd < r ? xcd * (q + 1) : r * (q + 1) + (xcd - r) * q) + off; }
;         const int nig = WGM * nN, gid = wgid / nig, fm = gid * WGM, gsz = (nM - fm) < WGM ? (nM - fm) : WGM;
;         u.pm = fm + ((wgid % nig) % gsz); u.pn = (wgid % nig) / gsz; return true;
; template <class Epi, class Sched, bool ALIGN_EPI = false, bool SP2 = false>
; __device__ __forceinline__ void gemm_phase(PG8_LAS unsigned char* lds, const Gemm g, const Sched& S, const Epi& E) {
;     ...
;         const bool has_next = S.next(ui + 1, nxt);
;         const char* nA = has_next ? (const char*)g.A + (size_t)nxt.pm * tstep : cA; const char* nB = has_next ? (const char*)g.Bt + (size_t)nxt.pn * tstep : cB;
;         for (int t = 0; t < nt; t += 2) {
;             const bool last = (t == nt - 2);
;             const char* a1 = cA + (size_t)(t + 1) * kstep;
;             const char* a2 = last ? nA : cA + (size_t)(t + 2) * kstep; const char* b2 = last ? nB : cB + (size_t)(t + 2) * kstep;
;             const char* a3 = a2 + kstep; const char* b3 = b2 + kstep;
;             if (last && has_next) S.a_ready(nxt);
;             if constexpr (SP2) {
;             PG8_LDB(B0, 0, 0); PG8_LDB(B1, 0, 1); PG8_SCHED; PG8_LDA(At, 0, 0); PG8_STAGE(PG8_SA(1, 1), a1 + hstep, voffA);
;             PG8_WAIT_V(8); PG8_WAIT_L(0); PG8_BAR; PG8_MMA(0, 0, At, B0); PG8_MMA(0, 1, At, B1); PG8_BAR; PG8_SCHED;
.LBB0_221:
	ds_read_b128 v[154:157], v150
	ds_read_b128 v[158:161], v150 offset:1024
	ds_read_b128 v[162:165], v150 offset:2048
	ds_read_b128 v[166:169], v150 offset:3072
	ds_read_b128 v[170:173], v151
	ds_read_b128 v[174:177], v151 offset:1024
	ds_read_b128 v[178:181], v151 offset:2048
	ds_read_b128 v[182:185], v151 offset:3072
	ds_read_b128 v[186:189], v152
	ds_read_b128 v[190:193], v152 offset:1024
	ds_read_b128 v[198:201], v152 offset:2048
	ds_read_b128 v[202:205], v152 offset:3072
	ds_read_b128 v[206:209], v152 offset:4096
	ds_read_b128 v[210:213], v152 offset:5120
	ds_read_b128 v[214:217], v152 offset:6144
	ds_read_b128 v[218:221], v152 offset:7168
	s_add_i32 s60, s60, 1
	s_mul_i32 s4, s60, s48
	s_mul_hi_u32 s5, s60, s49
	s_add_i32 s5, s5, s4
	s_mul_i32 s4, s60, s49
	s_add_u32 s16, s4, s2
	s_addc_u32 s17, s5, s3
	v_cmp_gt_i64_e32 vcc, s[16:17], v[142:143]
	v_cmp_lt_i64_e64 s[4:5], s[16:17], v[140:141]
	s_cbranch_vccnz .LBB0_223
	s_ashr_i32 s12, s16, 31
	s_lshr_b32 s12, s12, 29
	s_add_i32 s12, s16, s12
	s_ashr_i32 s13, s12, 3
	s_and_b32 s12, s12, -8
	s_sub_i32 s12, s16, s12
	s_cmp_lt_i32 s12, 0
	s_cselect_b32 s14, s56, 0x160
	s_mul_i32 s12, s14, s12
	s_add_i32 s12, s12, s13
	s_mul_hi_i32 s13, s12, 0x2e8ba2e9
	s_lshr_b32 s14, s13, 31
	s_ashr_i32 s13, s13, 5
	s_add_i32 s13, s13, s14
	s_lshl_b32 s14, s13, 3
	s_sub_i32 s15, 0x80, s14
	s_min_i32 s15, s15, 8
	s_mulk_i32 s13, 0xb0
	s_sub_i32 s13, s12, s13
	s_lshr_b32 s12, s13, 3
	s_mul_i32 s15, s12, s15
	s_sub_i32 s13, s13, s15
	s_add_i32 s14, s13, s14
.LBB0_223:
	s_ashr_i32 s15, s14, 31
	s_lshl_b64 s[16:17], s[14:15], 19
	s_add_u32 s16, s36, s16
	s_addc_u32 s17, s37, s17
	s_and_b64 s[18:19], s[4:5], exec
	s_cselect_b32 s15, s17, s21
	s_cselect_b32 s68, s16, s20
	s_ashr_i32 s13, s12, 31
	s_lshl_b64 s[18:19], s[12:13], 19
	s_add_u32 s18, s53, s18
	s_addc_u32 s19, s54, s19
	s_and_b64 s[46:47], s[4:5], exec
	s_cselect_b32 s13, s19, s43
	s_cselect_b32 s69, s18, s42
	s_add_u32 s20, s20, 0x40080
	s_addc_u32 s21, s21, 0
	s_add_u32 s70, s42, 0x100
	s_addc_u32 s71, s43, 0
	s_mov_b32 s72, -2
	s_add_u32 s42, s20, 0xfffc0080
	s_addc_u32 s43, s21, -1
	s_cmp_eq_u32 s72, 12
	s_cselect_b32 s47, s15, s43
	s_cselect_b32 s46, s68, s42
	s_cselect_b32 s43, s13, s71
	s_cselect_b32 s42, s69, s70
	s_add_i32 m0, s35, 0xc000
	global_load_lds_dwordx4 v136, s[20:21]
	s_add_i32 m0, s35, 0xe000
	s_nop 0
	global_load_lds_dwordx4 v138, s[20:21]
	s_waitcnt vmcnt(8)
	s_waitcnt lgkmcnt(0)
	s_barrier
	v_mfma_f32_16x16x32_bf16 v[124:127], v[154:157], v[186:189], 0
	v_mfma_f32_16x16x32_bf16 v[116:119], v[162:165], v[186:189], 0
	v_mfma_f32_16x16x32_bf16 v[108:111], v[154:157], v[198:201], 0
	v_mfma_f32_16x16x32_bf16 v[100:103], v[162:165], v[198:201], 0
	v_mfma_f32_16x16x32_bf16 v[92:95], v[154:157], v[206:209], 0
	v_mfma_f32_16x16x32_bf16 v[84:87], v[162:165], v[206:209], 0
	v_mfma_f32_16x16x32_bf16 v[76:79], v[154:157], v[214:217], 0
	v_mfma_f32_16x16x32_bf16 v[68:71], v[162:165], v[214:217], 0
	v_mfma_f32_16x16x32_bf16 v[124:127], v[158:161], v[190:193], v[124:127]
	v_mfma_f32_16x16x32_bf16 v[116:119], v[166:169], v[190:193], v[116:119]
	v_mfma_f32_16x16x32_bf16 v[108:111], v[158:161], v[202:205], v[108:111]
	v_mfma_f32_16x16x32_bf16 v[100:103], v[166:169], v[202:205], v[100:103]
	v_mfma_f32_16x16x32_bf16 v[92:95], v[158:161], v[210:213], v[92:95]
	v_mfma_f32_16x16x32_bf16 v[84:87], v[166:169], v[210:213], v[84:87]
	v_mfma_f32_16x16x32_bf16 v[76:79], v[158:161], v[218:221], v[76:79]
	v_mfma_f32_16x16x32_bf16 v[68:71], v[166:169], v[218:221], v[68:71]
	v_mfma_f32_16x16x32_bf16 v[120:123], v[170:173], v[186:189], 0
	v_mfma_f32_16x16x32_bf16 v[112:115], v[178:181], v[186:189], 0
	v_mfma_f32_16x16x32_bf16 v[104:107], v[170:173], v[198:201], 0
	v_mfma_f32_16x16x32_bf16 v[96:99], v[178:181], v[198:201], 0
	v_mfma_f32_16x16x32_bf16 v[88:91], v[170:173], v[206:209], 0
	v_mfma_f32_16x16x32_bf16 v[80:83], v[178:181], v[206:209], 0
	v_mfma_f32_16x16x32_bf16 v[72:75], v[170:173], v[214:217], 0
	v_mfma_f32_16x16x32_bf16 v[64:67], v[178:181], v[214:217], 0
	v_mfma_f32_16x16x32_bf16 v[120:123], v[174:177], v[190:193], v[120:123]
	v_mfma_f32_16x16x32_bf16 v[112:115], v[182:185], v[190:193], v[112:115]
	v_mfma_f32_16x16x32_bf16 v[104:107], v[174:177], v[202:205], v[104:107]
	v_mfma_f32_16x16x32_bf16 v[96:99], v[182:185], v[202:205], v[96:99]
	v_mfma_f32_16x16x32_bf16 v[88:91], v[174:177], v[210:213], v[88:91]
	v_mfma_f32_16x16x32_bf16 v[80:83], v[182:185], v[210:213], v[80:83]
	v_mfma_f32_16x16x32_bf16 v[72:75], v[174:177], v[218:221], v[72:75]
	v_mfma_f32_16x16x32_bf16 v[64:67], v[182:185], v[218:221], v[64:67]
	s_barrier
	s_add_i32 s73, s63, s55
	s_add_u32 s98, s42, s8
	s_addc_u32 s99, s43, s9
	s_add_u32 s100, s46, s8
	s_addc_u32 s101, s47, s9
	s_mov_b32 m0, s73
	ds_read_b128 v[186:189], v152 offset:16384
	ds_read_b128 v[190:193], v152 offset:17408
	ds_read_b128 v[198:201], v152 offset:18432
	ds_read_b128 v[202:205], v152 offset:19456
	ds_read_b128 v[206:209], v152 offset:20480
	ds_read_b128 v[210:213], v152 offset:21504
	ds_read_b128 v[214:217], v152 offset:22528
	ds_read_b128 v[218:221], v152 offset:23552
	global_load_lds_dwordx4 v132, s[42:43]
	s_add_i32 m0, s73, 0x2000
	s_add_u32 s74, s42, 0x40000
	s_addc_u32 s75, s43, 0
	s_add_i32 s73, s64, s55
	global_load_lds_dwordx4 v128, s[42:43]
	s_mov_b32 m0, s73
	s_nop 0
	global_load_lds_dwordx4 v132, s[74:75]
	s_add_i32 m0, s73, 0x2000
	s_nop 0
	global_load_lds_dwordx4 v128, s[74:75]
	s_mov_b32 m0, s35
	s_nop 0
	global_load_lds_dwordx4 v134, s[46:47]
	s_mov_b32 m0, s57
	s_nop 0
	global_load_lds_dwordx4 v130, s[46:47]
	s_waitcnt vmcnt(8)
	s_waitcnt lgkmcnt(0)
	s_barrier
; #define PG8_STAGE(bufoff, gbase, voff) do { _Pragma("unroll") for (int _i = 0; _i < 2; ++_i) \
;         __builtin_amdgcn_global_load_lds((const unsigned*)((const char*)(gbase) + (voff)[_i]), (PG8_LAS unsigned*)(lds + (bufoff) + ldsw + _i * 8192), 16, 0, 0); } while (0)
; #define PG8_LDA(dst, b, h) do { _Pragma("unroll") for (int m = 0; m < 4; ++m) _Pragma("unroll") for (int k = 0; k < 2; ++k) dst[m][k] = *(const PG8_LAS bf16x8*)(lds + PG8_SA(b, h) + aoff + m * 2048 + k * 1024); } while (0)
; #define PG8_LDB(dst, b, h) do { _Pragma("unroll") for (int n = 0; n < 2; ++n) _Pragma("unroll") for (int k = 0; k < 2; ++k) dst[n][k] = *(const PG8_LAS bf16x8*)(lds + PG8_SB(b, h) + boff + n * 2048 + k * 1024); } while (0)
; #define PG8_MMA(ai, bj, At, Bt) do { __builtin_amdgcn_s_setprio(1); _Pragma("unroll") for (int m = 0; m < 4; ++m) _Pragma("unroll") for (int n = 0; n < 2; ++n) _Pragma("unroll") for (int k = 0; k < 2; ++k) \
;         acc[ai][bj][m][n] = __builtin_amdgcn_mfma_f32_16x16x32_bf16(Bt[n][k], At[m][k], acc[ai][bj][m][n], 0, 0, 0); __builtin_amdgcn_s_setprio(0); } while (0)
; #define PG8_WAIT_V(n) asm volatile("s_waitcnt vmcnt(" #n ")" ::: "memory")
; #define PG8_WAIT_L(n) asm volatile("s_waitcnt lgkmcnt(" #n ")" ::: "memory")
; #define PG8_BAR __builtin_amdgcn_s_barrier()
; #define PG8_SCHED __builtin_amdgcn_sched_barrier(0)
; template <class Epi, class Sched, bool ALIGN_EPI = false, bool SP2 = false>
; __device__ __forceinline__ void gemm_phase(PG8_LAS unsigned char* lds, const Gemm g, const Sched& S, const Epi& E) {
;     ...
;             PG8_WAIT_V(8); PG8_WAIT_L(0); PG8_BAR; PG8_MMA(1, 0, At, B0); PG8_MMA(1, 1, At, B1); PG8_BAR; PG8_SCHED;
;             PG8_LDB(B0, 1, 0); PG8_LDB(B1, 1, 1); PG8_SCHED; PG8_LDA(At, 1, 0); PG8_STAGE(PG8_SA(0, 1), a2 + hstep, voffA);
;             PG8_WAIT_V(8); PG8_WAIT_L(0); PG8_BAR; PG8_MMA(0, 0, At, B0); PG8_MMA(0, 1, At, B1); PG8_BAR; PG8_SCHED;
	v_mfma_f32_16x16x32_bf16 v[60:63], v[154:157], v[186:189], 0
	v_mfma_f32_16x16x32_bf16 v[52:55], v[162:165], v[186:189], 0
	v_mfma_f32_16x16x32_bf16 v[44:47], v[154:157], v[198:201], 0
	v_mfma_f32_16x16x32_bf16 v[36:39], v[162:165], v[198:201], 0
	v_mfma_f32_16x16x32_bf16 v[28:31], v[154:157], v[206:209], 0
	v_mfma_f32_16x16x32_bf16 v[20:23], v[162:165], v[206:209], 0
	v_mfma_f32_16x16x32_bf16 v[12:15], v[154:157], v[214:217], 0
	v_mfma_f32_16x16x32_bf16 v[4:7], v[162:165], v[214:217], 0
	v_mfma_f32_16x16x32_bf16 v[60:63], v[158:161], v[190:193], v[60:63]
	v_mfma_f32_16x16x32_bf16 v[52:55], v[166:169], v[190:193], v[52:55]
	v_mfma_f32_16x16x32_bf16 v[44:47], v[158:161], v[202:205], v[44:47]
	v_mfma_f32_16x16x32_bf16 v[36:39], v[166:169], v[202:205], v[36:39]
	v_mfma_f32_16x16x32_bf16 v[28:31], v[158:161], v[210:213], v[28:31]
	v_mfma_f32_16x16x32_bf16 v[20:23], v[166:169], v[210:213], v[20:23]
	v_mfma_f32_16x16x32_bf16 v[12:15], v[158:161], v[218:221], v[12:15]
	v_mfma_f32_16x16x32_bf16 v[4:7], v[166:169], v[218:221], v[4:7]
	v_mfma_f32_16x16x32_bf16 v[56:59], v[170:173], v[186:189], 0
	v_mfma_f32_16x16x32_bf16 v[48:51], v[178:181], v[186:189], 0
	v_mfma_f32_16x16x32_bf16 v[40:43], v[170:173], v[198:201], 0
	v_mfma_f32_16x16x32_bf16 v[32:35], v[178:181], v[198:201], 0
	v_mfma_f32_16x16x32_bf16 v[24:27], v[170:173], v[206:209], 0
	v_mfma_f32_16x16x32_bf16 v[16:19], v[178:181], v[206:209], 0
	v_mfma_f32_16x16x32_bf16 v[8:11], v[170:173], v[214:217], 0
	v_mfma_f32_16x16x32_bf16 v[0:3], v[178:181], v[214:217], 0
	v_mfma_f32_16x16x32_bf16 v[56:59], v[174:177], v[190:193], v[56:59]
	v_mfma_f32_16x16x32_bf16 v[48:51], v[182:185], v[190:193], v[48:51]
	v_mfma_f32_16x16x32_bf16 v[40:43], v[174:177], v[202:205], v[40:43]
	v_mfma_f32_16x16x32_bf16 v[32:35], v[182:185], v[202:205], v[32:35]
	v_mfma_f32_16x16x32_bf16 v[24:27], v[174:177], v[210:213], v[24:27]
	v_mfma_f32_16x16x32_bf16 v[16:19], v[182:185], v[210:213], v[16:19]
	v_mfma_f32_16x16x32_bf16 v[8:11], v[174:177], v[218:221], v[8:11]
	v_mfma_f32_16x16x32_bf16 v[0:3], v[182:185], v[218:221], v[0:3]
	s_barrier
	s_add_i32 s73, 0, 0x18000
	v_add_u32_e32 v153, s73, v147
	s_add_i32 s74, 0, 0x1c000
	ds_read_b128 v[154:157], v153
	ds_read_b128 v[158:161], v153 offset:1024
	ds_read_b128 v[162:165], v153 offset:2048
	ds_read_b128 v[166:169], v153 offset:3072
	v_add_u32_e32 v153, s74, v147
	ds_read_b128 v[170:173], v153
	ds_read_b128 v[174:177], v153 offset:1024
	ds_read_b128 v[178:181], v153 offset:2048
	ds_read_b128 v[182:185], v153 offset:3072
	s_add_u32 s46, s46, 0x40000
	s_addc_u32 s47, s47, 0
	s_mov_b32 m0, s58
	ds_read_b128 v[186:189], v152 offset:32768
	ds_read_b128 v[190:193], v152 offset:33792
	ds_read_b128 v[198:201], v152 offset:34816
	ds_read_b128 v[202:205], v152 offset:35840
	ds_read_b128 v[206:209], v152 offset:36864
	ds_read_b128 v[210:213], v152 offset:37888
	ds_read_b128 v[214:217], v152 offset:38912
	ds_read_b128 v[218:221], v152 offset:39936
	global_load_lds_dwordx4 v134, s[46:47]
	s_mov_b32 m0, s59
	s_nop 0
	global_load_lds_dwordx4 v130, s[46:47]
	s_waitcnt vmcnt(8)
	s_waitcnt lgkmcnt(0)
	s_barrier
	v_mfma_f32_16x16x32_bf16 v[124:127], v[154:157], v[186:189], v[124:127]
	v_mfma_f32_16x16x32_bf16 v[116:119], v[162:165], v[186:189], v[116:119]
	v_mfma_f32_16x16x32_bf16 v[108:111], v[154:157], v[198:201], v[108:111]
	v_mfma_f32_16x16x32_bf16 v[100:103], v[162:165], v[198:201], v[100:103]
	v_mfma_f32_16x16x32_bf16 v[92:95], v[154:157], v[206:209], v[92:95]
	v_mfma_f32_16x16x32_bf16 v[84:87], v[162:165], v[206:209], v[84:87]
	v_mfma_f32_16x16x32_bf16 v[76:79], v[154:157], v[214:217], v[76:79]
	v_mfma_f32_16x16x32_bf16 v[68:71], v[162:165], v[214:217], v[68:71]
	v_mfma_f32_16x16x32_bf16 v[124:127], v[158:161], v[190:193], v[124:127]
	v_mfma_f32_16x16x32_bf16 v[116:119], v[166:169], v[190:193], v[116:119]
	v_mfma_f32_16x16x32_bf16 v[108:111], v[158:161], v[202:205], v[108:111]
	v_mfma_f32_16x16x32_bf16 v[100:103], v[166:169], v[202:205], v[100:103]
	v_mfma_f32_16x16x32_bf16 v[92:95], v[158:161], v[210:213], v[92:95]
	v_mfma_f32_16x16x32_bf16 v[84:87], v[166:169], v[210:213], v[84:87]
	v_mfma_f32_16x16x32_bf16 v[76:79], v[158:161], v[218:221], v[76:79]
	v_mfma_f32_16x16x32_bf16 v[68:71], v[166:169], v[218:221], v[68:71]
	v_mfma_f32_16x16x32_bf16 v[120:123], v[170:173], v[186:189], v[120:123]
	v_mfma_f32_16x16x32_bf16 v[112:115], v[178:181], v[186:189], v[112:115]
	v_mfma_f32_16x16x32_bf16 v[104:107], v[170:173], v[198:201], v[104:107]
	v_mfma_f32_16x16x32_bf16 v[96:99], v[178:181], v[198:201], v[96:99]
	v_mfma_f32_16x16x32_bf16 v[88:91], v[170:173], v[206:209], v[88:91]
	v_mfma_f32_16x16x32_bf16 v[80:83], v[178:181], v[206:209], v[80:83]
	v_mfma_f32_16x16x32_bf16 v[72:75], v[170:173], v[214:217], v[72:75]
	v_mfma_f32_16x16x32_bf16 v[64:67], v[178:181], v[214:217], v[64:67]
	v_mfma_f32_16x16x32_bf16 v[120:123], v[174:177], v[190:193], v[120:123]
	v_mfma_f32_16x16x32_bf16 v[112:115], v[182:185], v[190:193], v[112:115]
	v_mfma_f32_16x16x32_bf16 v[104:107], v[174:177], v[202:205], v[104:107]
	v_mfma_f32_16x16x32_bf16 v[96:99], v[182:185], v[202:205], v[96:99]
	v_mfma_f32_16x16x32_bf16 v[88:91], v[174:177], v[210:213], v[88:91]
	v_mfma_f32_16x16x32_bf16 v[80:83], v[182:185], v[210:213], v[80:83]
	v_mfma_f32_16x16x32_bf16 v[72:75], v[174:177], v[218:221], v[72:75]
	v_mfma_f32_16x16x32_bf16 v[64:67], v[182:185], v[218:221], v[64:67]
	s_barrier
; #define PG8_STAGE(bufoff, gbase, voff) do { _Pragma("unroll") for (int _i = 0; _i < 2; ++_i) \
;         __builtin_amdgcn_global_load_lds((const unsigned*)((const char*)(gbase) + (voff)[_i]), (PG8_LAS unsigned*)(lds + (bufoff) + ldsw + _i * 8192), 16, 0, 0); } while (0)
; #define PG8_LDA(dst, b, h) do { _Pragma("unroll") for (int m = 0; m < 4; ++m) _Pragma("unroll") for (int k = 0; k < 2; ++k) dst[m][k] = *(const PG8_LAS bf16x8*)(lds + PG8_SA(b, h) + aoff + m * 2048 + k * 1024); } while (0)
; #define PG8_MMA(ai, bj, At, Bt) do { __builtin_amdgcn_s_setprio(1); _Pragma("unroll") for (int m = 0; m < 4; ++m) _Pragma("unroll") for (int n = 0; n < 2; ++n) _Pragma("unroll") for (int k = 0; k < 2; ++k) \
;         acc[ai][bj][m][n] = __builtin_amdgcn_mfma_f32_16x16x32_bf16(Bt[n][k], At[m][k], acc[ai][bj][m][n], 0, 0, 0); __builtin_amdgcn_s_setprio(0); } while (0)
; #define PG8_WAIT_V(n) asm volatile("s_waitcnt vmcnt(" #n ")" ::: "memory")
; #define PG8_WAIT_L(n) asm volatile("s_waitcnt lgkmcnt(" #n ")" ::: "memory")
; #define PG8_BAR __builtin_amdgcn_s_barrier()
; #define PG8_SCHED __builtin_amdgcn_sched_barrier(0)
; template <class Epi, class Sched, bool ALIGN_EPI = false, bool SP2 = false>
; __device__ __forceinline__ void gemm_phase(PG8_LAS unsigned char* lds, const Gemm g, const Sched& S, const Epi& E) {
;     ...
;             PG8_LDA(At, 1, 1); PG8_STAGE(PG8_SB(1, 0), b3, voffB); PG8_STAGE(PG8_SB(1, 1), b3 + hstep, voffB); PG8_STAGE(PG8_SA(1, 0), a3, voffA);
;             PG8_WAIT_V(8); PG8_WAIT_L(0); PG8_BAR; PG8_MMA(1, 0, At, B0); PG8_MMA(1, 1, At, B1); PG8_BAR; PG8_SCHED;
	s_add_i32 s46, s73, s55
	s_mov_b32 m0, s46
	ds_read_b128 v[186:189], v152 offset:49152
	ds_read_b128 v[190:193], v152 offset:50176
	ds_read_b128 v[198:201], v152 offset:51200
	ds_read_b128 v[202:205], v152 offset:52224
	ds_read_b128 v[206:209], v152 offset:53248
	ds_read_b128 v[210:213], v152 offset:54272
	ds_read_b128 v[214:217], v152 offset:55296
	ds_read_b128 v[218:221], v152 offset:56320
	global_load_lds_dwordx4 v132, s[98:99]
	s_add_i32 m0, s46, 0x2000
	s_add_u32 s42, s42, 0x40080
	s_addc_u32 s43, s43, 0
	s_add_i32 s46, s74, s55
	global_load_lds_dwordx4 v128, s[98:99]
	s_mov_b32 m0, s46
	s_nop 0
	global_load_lds_dwordx4 v132, s[42:43]
	s_add_i32 m0, s46, 0x2000
	s_nop 0
	global_load_lds_dwordx4 v128, s[42:43]
	s_mov_b32 m0, s61
	s_nop 0
	global_load_lds_dwordx4 v134, s[100:101]
	s_mov_b32 m0, s62
	s_nop 0
	global_load_lds_dwordx4 v130, s[100:101]
	s_waitcnt vmcnt(8)
	s_waitcnt lgkmcnt(0)
	s_barrier
	v_mfma_f32_16x16x32_bf16 v[60:63], v[154:157], v[186:189], v[60:63]
	v_mfma_f32_16x16x32_bf16 v[52:55], v[162:165], v[186:189], v[52:55]
	v_mfma_f32_16x16x32_bf16 v[44:47], v[154:157], v[198:201], v[44:47]
	v_mfma_f32_16x16x32_bf16 v[36:39], v[162:165], v[198:201], v[36:39]
	v_mfma_f32_16x16x32_bf16 v[28:31], v[154:157], v[206:209], v[28:31]
	v_mfma_f32_16x16x32_bf16 v[20:23], v[162:165], v[206:209], v[20:23]
	v_mfma_f32_16x16x32_bf16 v[12:15], v[154:157], v[214:217], v[12:15]
	v_mfma_f32_16x16x32_bf16 v[4:7], v[162:165], v[214:217], v[4:7]
	v_mfma_f32_16x16x32_bf16 v[60:63], v[158:161], v[190:193], v[60:63]
	v_mfma_f32_16x16x32_bf16 v[52:55], v[166:169], v[190:193], v[52:55]
	v_mfma_f32_16x16x32_bf16 v[44:47], v[158:161], v[202:205], v[44:47]
	v_mfma_f32_16x16x32_bf16 v[36:39], v[166:169], v[202:205], v[36:39]
	v_mfma_f32_16x16x32_bf16 v[28:31], v[158:161], v[210:213], v[28:31]
	v_mfma_f32_16x16x32_bf16 v[20:23], v[166:169], v[210:213], v[20:23]
	v_mfma_f32_16x16x32_bf16 v[12:15], v[158:161], v[218:221], v[12:15]
	v_mfma_f32_16x16x32_bf16 v[4:7], v[166:169], v[218:221], v[4:7]
	v_mfma_f32_16x16x32_bf16 v[56:59], v[170:173], v[186:189], v[56:59]
	v_mfma_f32_16x16x32_bf16 v[48:51], v[178:181], v[186:189], v[48:51]
	v_mfma_f32_16x16x32_bf16 v[40:43], v[170:173], v[198:201], v[40:43]
	v_mfma_f32_16x16x32_bf16 v[32:35], v[178:181], v[198:201], v[32:35]
	v_mfma_f32_16x16x32_bf16 v[24:27], v[170:173], v[206:209], v[24:27]
	v_mfma_f32_16x16x32_bf16 v[16:19], v[178:181], v[206:209], v[16:19]
	v_mfma_f32_16x16x32_bf16 v[8:11], v[170:173], v[214:217], v[8:11]
	v_mfma_f32_16x16x32_bf16 v[0:3], v[178:181], v[214:217], v[0:3]
	v_mfma_f32_16x16x32_bf16 v[56:59], v[174:177], v[190:193], v[56:59]
	v_mfma_f32_16x16x32_bf16 v[48:51], v[182:185], v[190:193], v[48:51]
	v_mfma_f32_16x16x32_bf16 v[40:43], v[174:177], v[202:205], v[40:43]
	v_mfma_f32_16x16x32_bf16 v[32:35], v[182:185], v[202:205], v[32:35]
	v_mfma_f32_16x16x32_bf16 v[24:27], v[174:177], v[210:213], v[24:27]
	v_mfma_f32_16x16x32_bf16 v[16:19], v[182:185], v[210:213], v[16:19]
	v_mfma_f32_16x16x32_bf16 v[8:11], v[174:177], v[218:221], v[8:11]
	v_mfma_f32_16x16x32_bf16 v[0:3], v[182:185], v[218:221], v[0:3]
	s_barrier
	s_add_i32 s72, s72, 2
	s_add_u32 s20, s20, 0x100
	s_addc_u32 s21, s21, 0
	s_add_u32 s70, s70, 0x100
	s_addc_u32 s71, s71, 0
	s_cmp_gt_u32 s72, 13

; #define PG8_STAGE(bufoff, gbase, voff) do { _Pragma("unroll") for (int _i = 0; _i < 2; ++_i) \
;         __builtin_amdgcn_global_load_lds((const unsigned*)((const char*)(gbase) + (voff)[_i]), (PG8_LAS unsigned*)(lds + (bufoff) + ldsw + _i * 8192), 16, 0, 0); } while (0)
; #define PG8_LDA(dst, b, h) do { _Pragma("unroll") for (int m = 0; m < 4; ++m) _Pragma("unroll") for (int k = 0; k < 2; ++k) dst[m][k] = *(const PG8_LAS bf16x8*)(lds + PG8_SA(b, h) + aoff + m * 2048 + k * 1024); } while (0)
; #define PG8_LDB(dst, b, h) do { _Pragma("unroll") for (int n = 0; n < 2; ++n) _Pragma("unroll") for (int k = 0; k < 2; ++k) dst[n][k] = *(const PG8_LAS bf16x8*)(lds + PG8_SB(b, h) + boff + n * 2048 + k * 1024); } while (0)
; #define PG8_MMA(ai, bj, At, Bt) do { __builtin_amdgcn_s_setprio(1); _Pragma("unroll") for (int m = 0; m < 4; ++m) _Pragma("unroll") for (int n = 0; n < 2; ++n) _Pragma("unroll") for (int k = 0; k < 2; ++k) \
;         acc[ai][bj][m][n] = __builtin_amdgcn_mfma_f32_16x16x32_bf16(Bt[n][k], At[m][k], acc[ai][bj][m][n], 0, 0, 0); __builtin_amdgcn_s_setprio(0); } while (0)
; #define PG8_WAIT_V(n) asm volatile("s_waitcnt vmcnt(" #n ")" ::: "memory")
; #define PG8_BAR __builtin_amdgcn_s_barrier()
; template <class Epi, class Sched, bool ALIGN_EPI = false, bool SP2 = false>
; __device__ __forceinline__ void gemm_phase(PG8_LAS unsigned char* lds, const Gemm g, const Sched& S, const Epi& E) {
;     ...
;         for (int t = 0; t < nt; t += 2) {
;             const bool last = (t == nt - 2);
;             const char* a1 = cA + (size_t)(t + 1) * kstep;
;             const char* a2 = last ? nA : cA + (size_t)(t + 2) * kstep; const char* b2 = last ? nB : cB + (size_t)(t + 2) * kstep;
;             const char* a3 = a2 + kstep; const char* b3 = b2 + kstep;
;             if (last && has_next) S.a_ready(nxt);
;             if constexpr (SP2) {
;             PG8_LDB(B0, 0, 0); PG8_LDB(B1, 0, 1); PG8_SCHED; PG8_LDA(At, 0, 0); PG8_STAGE(PG8_SA(1, 1), a1 + hstep, voffA);
;             PG8_WAIT_V(8); PG8_WAIT_L(0); PG8_BAR; PG8_MMA(0, 0, At, B0); PG8_MMA(0, 1, At, B1); PG8_BAR; PG8_SCHED;
;             PG8_LDA(At, 0, 1); PG8_STAGE(PG8_SB(0, 0), b2, voffB); PG8_STAGE(PG8_SB(0, 1), b2 + hstep, voffB); PG8_STAGE(PG8_SA(0, 0), a2, voffA);
;             PG8_WAIT_V(8); PG8_WAIT_L(0); PG8_BAR; PG8_MMA(1, 0, At, B0); PG8_MMA(1, 1, At, B1); PG8_BAR; PG8_SCHED;
.LBB0_308:
	s_add_u32 s20, s20, 0xb0080
	s_addc_u32 s21, s21, 0
	s_add_u32 s73, s34, 0x100
	s_addc_u32 s74, s35, 0
	s_mov_b32 s75, -2
	s_waitcnt lgkmcnt(0)
	s_waitcnt lgkmcnt(0)
	ds_read_b128 v[96:99], v223
	ds_read_b128 v[108:111], v223 offset:1024
	ds_read_b128 v[120:123], v223 offset:2048
	ds_read_b128 v[128:131], v223 offset:3072
	ds_read_b128 v[144:147], v224
	ds_read_b128 v[148:151], v224 offset:1024
	ds_read_b128 v[152:155], v224 offset:2048
	ds_read_b128 v[156:159], v224 offset:3072
	ds_read_b128 v[160:163], v225
	ds_read_b128 v[164:167], v225 offset:1024
	ds_read_b128 v[168:171], v225 offset:2048
	ds_read_b128 v[172:175], v225 offset:3072
	ds_read_b128 v[176:179], v225 offset:4096
	ds_read_b128 v[180:183], v225 offset:5120
	ds_read_b128 v[202:205], v225 offset:6144
	ds_read_b128 v[206:209], v225 offset:7168
	s_add_u32 s34, s20, 0xfff50080
	s_addc_u32 s35, s21, -1
	s_cmp_eq_u32 s75, 40
	s_cselect_b32 s51, s1, s35
	s_cselect_b32 s50, s0, s34
	s_cselect_b32 s35, s49, s74
	s_cselect_b32 s34, s48, s73
	s_add_i32 m0, s54, 0xc000
	global_load_lds_dwordx4 v192, s[20:21]
	s_add_i32 m0, s54, 0xe000
	s_nop 0
	global_load_lds_dwordx4 v194, s[20:21]
	s_waitcnt vmcnt(8)
	s_waitcnt lgkmcnt(0)
	s_barrier
	v_mfma_f32_16x16x32_bf16 v[140:143], v[96:99], v[160:163], 0
	v_mfma_f32_16x16x32_bf16 v[136:139], v[120:123], v[160:163], 0
	v_mfma_f32_16x16x32_bf16 v[116:119], v[96:99], v[168:171], 0
	v_mfma_f32_16x16x32_bf16 v[112:115], v[120:123], v[168:171], 0
	v_mfma_f32_16x16x32_bf16 v[92:95], v[96:99], v[176:179], 0
	v_mfma_f32_16x16x32_bf16 v[88:91], v[120:123], v[176:179], 0
	v_mfma_f32_16x16x32_bf16 v[76:79], v[96:99], v[202:205], 0
	v_mfma_f32_16x16x32_bf16 v[72:75], v[120:123], v[202:205], 0
	v_mfma_f32_16x16x32_bf16 v[140:143], v[108:111], v[164:167], v[140:143]
	v_mfma_f32_16x16x32_bf16 v[136:139], v[128:131], v[164:167], v[136:139]
	v_mfma_f32_16x16x32_bf16 v[116:119], v[108:111], v[172:175], v[116:119]
	v_mfma_f32_16x16x32_bf16 v[112:115], v[128:131], v[172:175], v[112:115]
	v_mfma_f32_16x16x32_bf16 v[92:95], v[108:111], v[180:183], v[92:95]
	v_mfma_f32_16x16x32_bf16 v[88:91], v[128:131], v[180:183], v[88:91]
	v_mfma_f32_16x16x32_bf16 v[76:79], v[108:111], v[206:209], v[76:79]
	v_mfma_f32_16x16x32_bf16 v[72:75], v[128:131], v[206:209], v[72:75]
	v_mfma_f32_16x16x32_bf16 v[132:135], v[144:147], v[160:163], 0
	v_mfma_f32_16x16x32_bf16 v[124:127], v[152:155], v[160:163], 0
	v_mfma_f32_16x16x32_bf16 v[104:107], v[144:147], v[168:171], 0
	v_mfma_f32_16x16x32_bf16 v[100:103], v[152:155], v[168:171], 0
	v_mfma_f32_16x16x32_bf16 v[84:87], v[144:147], v[176:179], 0
	v_mfma_f32_16x16x32_bf16 v[80:83], v[152:155], v[176:179], 0
	v_mfma_f32_16x16x32_bf16 v[68:71], v[144:147], v[202:205], 0
	v_mfma_f32_16x16x32_bf16 v[64:67], v[152:155], v[202:205], 0
	v_mfma_f32_16x16x32_bf16 v[132:135], v[148:151], v[164:167], v[132:135]
	v_mfma_f32_16x16x32_bf16 v[124:127], v[156:159], v[164:167], v[124:127]
	v_mfma_f32_16x16x32_bf16 v[104:107], v[148:151], v[172:175], v[104:107]
	v_mfma_f32_16x16x32_bf16 v[100:103], v[156:159], v[172:175], v[100:103]
	v_mfma_f32_16x16x32_bf16 v[84:87], v[148:151], v[180:183], v[84:87]
	v_mfma_f32_16x16x32_bf16 v[80:83], v[156:159], v[180:183], v[80:83]
	v_mfma_f32_16x16x32_bf16 v[68:71], v[148:151], v[206:209], v[68:71]
	v_mfma_f32_16x16x32_bf16 v[64:67], v[156:159], v[206:209], v[64:67]
	s_barrier
	s_add_i32 s76, s67, s53
	s_add_u32 s98, s34, s12
	s_addc_u32 s99, s35, s13
	s_add_u32 s100, s50, s12
	s_addc_u32 s101, s51, s13
	s_mov_b32 m0, s76
	ds_read_b128 v[160:163], v225 offset:16384
	ds_read_b128 v[164:167], v225 offset:17408
	ds_read_b128 v[168:171], v225 offset:18432
	ds_read_b128 v[172:175], v225 offset:19456
	ds_read_b128 v[176:179], v225 offset:20480
	ds_read_b128 v[180:183], v225 offset:21504
	ds_read_b128 v[202:205], v225 offset:22528
	ds_read_b128 v[206:209], v225 offset:23552
	global_load_lds_dwordx4 v186, s[34:35]
	s_add_i32 m0, s76, 0x2000
	s_add_u32 s76, s34, 0xb0000
	s_addc_u32 s77, s35, 0
	s_add_i32 s78, s68, s53
	global_load_lds_dwordx4 v190, s[34:35]
	s_mov_b32 m0, s78
	s_nop 0
	global_load_lds_dwordx4 v186, s[76:77]
	s_add_i32 m0, s78, 0x2000
	s_nop 0
	global_load_lds_dwordx4 v190, s[76:77]
	s_mov_b32 m0, s54
	s_nop 0
	global_load_lds_dwordx4 v184, s[50:51]
	s_mov_b32 m0, s55
	s_nop 0
	global_load_lds_dwordx4 v188, s[50:51]
	s_waitcnt vmcnt(8)
	s_waitcnt lgkmcnt(0)
	s_barrier
	v_mfma_f32_16x16x32_bf16 v[60:63], v[96:99], v[160:163], 0
	v_mfma_f32_16x16x32_bf16 v[56:59], v[120:123], v[160:163], 0
	v_mfma_f32_16x16x32_bf16 v[44:47], v[96:99], v[168:171], 0
	v_mfma_f32_16x16x32_bf16 v[40:43], v[120:123], v[168:171], 0
	v_mfma_f32_16x16x32_bf16 v[28:31], v[96:99], v[176:179], 0
	v_mfma_f32_16x16x32_bf16 v[24:27], v[120:123], v[176:179], 0
	v_mfma_f32_16x16x32_bf16 v[12:15], v[96:99], v[202:205], 0
	v_mfma_f32_16x16x32_bf16 v[8:11], v[120:123], v[202:205], 0
	v_mfma_f32_16x16x32_bf16 v[60:63], v[108:111], v[164:167], v[60:63]
	v_mfma_f32_16x16x32_bf16 v[56:59], v[128:131], v[164:167], v[56:59]
	v_mfma_f32_16x16x32_bf16 v[44:47], v[108:111], v[172:175], v[44:47]
	v_mfma_f32_16x16x32_bf16 v[40:43], v[128:131], v[172:175], v[40:43]
	v_mfma_f32_16x16x32_bf16 v[28:31], v[108:111], v[180:183], v[28:31]
	v_mfma_f32_16x16x32_bf16 v[24:27], v[128:131], v[180:183], v[24:27]
	v_mfma_f32_16x16x32_bf16 v[12:15], v[108:111], v[206:209], v[12:15]
	v_mfma_f32_16x16x32_bf16 v[8:11], v[128:131], v[206:209], v[8:11]
	v_mfma_f32_16x16x32_bf16 v[52:55], v[144:147], v[160:163], 0
	v_mfma_f32_16x16x32_bf16 v[48:51], v[152:155], v[160:163], 0
	v_mfma_f32_16x16x32_bf16 v[36:39], v[144:147], v[168:171], 0
	v_mfma_f32_16x16x32_bf16 v[32:35], v[152:155], v[168:171], 0
	v_mfma_f32_16x16x32_bf16 v[20:23], v[144:147], v[176:179], 0
	v_mfma_f32_16x16x32_bf16 v[16:19], v[152:155], v[176:179], 0
	v_mfma_f32_16x16x32_bf16 v[4:7], v[144:147], v[202:205], 0
	v_mfma_f32_16x16x32_bf16 v[0:3], v[152:155], v[202:205], 0
	v_mfma_f32_16x16x32_bf16 v[52:55], v[148:151], v[164:167], v[52:55]
	v_mfma_f32_16x16x32_bf16 v[48:51], v[156:159], v[164:167], v[48:51]
	v_mfma_f32_16x16x32_bf16 v[36:39], v[148:151], v[172:175], v[36:39]
	v_mfma_f32_16x16x32_bf16 v[32:35], v[156:159], v[172:175], v[32:35]
	v_mfma_f32_16x16x32_bf16 v[20:23], v[148:151], v[180:183], v[20:23]
	v_mfma_f32_16x16x32_bf16 v[16:19], v[156:159], v[180:183], v[16:19]
	v_mfma_f32_16x16x32_bf16 v[4:7], v[148:151], v[206:209], v[4:7]
	v_mfma_f32_16x16x32_bf16 v[0:3], v[156:159], v[206:209], v[0:3]
	s_barrier
; #define PG8_STAGE(bufoff, gbase, voff) do { _Pragma("unroll") for (int _i = 0; _i < 2; ++_i) \
;         __builtin_amdgcn_global_load_lds((const unsigned*)((const char*)(gbase) + (voff)[_i]), (PG8_LAS unsigned*)(lds + (bufoff) + ldsw + _i * 8192), 16, 0, 0); } while (0)
; #define PG8_LDA(dst, b, h) do { _Pragma("unroll") for (int m = 0; m < 4; ++m) _Pragma("unroll") for (int k = 0; k < 2; ++k) dst[m][k] = *(const PG8_LAS bf16x8*)(lds + PG8_SA(b, h) + aoff + m * 2048 + k * 1024); } while (0)
; #define PG8_LDB(dst, b, h) do { _Pragma("unroll") for (int n = 0; n < 2; ++n) _Pragma("unroll") for (int k = 0; k < 2; ++k) dst[n][k] = *(const PG8_LAS bf16x8*)(lds + PG8_SB(b, h) + boff + n * 2048 + k * 1024); } while (0)
; #define PG8_MMA(ai, bj, At, Bt) do { __builtin_amdgcn_s_setprio(1); _Pragma("unroll") for (int m = 0; m < 4; ++m) _Pragma("unroll") for (int n = 0; n < 2; ++n) _Pragma("unroll") for (int k = 0; k < 2; ++k) \
;         acc[ai][bj][m][n] = __builtin_amdgcn_mfma_f32_16x16x32_bf16(Bt[n][k], At[m][k], acc[ai][bj][m][n], 0, 0, 0); __builtin_amdgcn_s_setprio(0); } while (0)
; #define PG8_WAIT_V(n) asm volatile("s_waitcnt vmcnt(" #n ")" ::: "memory")
; #define PG8_WAIT_L(n) asm volatile("s_waitcnt lgkmcnt(" #n ")" ::: "memory")
; #define PG8_BAR __builtin_amdgcn_s_barrier()
; #define PG8_SCHED __builtin_amdgcn_sched_barrier(0)
; template <class Epi, class Sched, bool ALIGN_EPI = false, bool SP2 = false>
; __device__ __forceinline__ void gemm_phase(PG8_LAS unsigned char* lds, const Gemm g, const Sched& S, const Epi& E) {
;     ...
;             PG8_LDB(B0, 1, 0); PG8_LDB(B1, 1, 1); PG8_SCHED; PG8_LDA(At, 1, 0); PG8_STAGE(PG8_SA(0, 1), a2 + hstep, voffA);
;             PG8_WAIT_V(8); PG8_WAIT_L(0); PG8_BAR; PG8_MMA(0, 0, At, B0); PG8_MMA(0, 1, At, B1); PG8_BAR; PG8_SCHED;
;             PG8_LDA(At, 1, 1); PG8_STAGE(PG8_SB(1, 0), b3, voffB); PG8_STAGE(PG8_SB(1, 1), b3 + hstep, voffB); PG8_STAGE(PG8_SA(1, 0), a3, voffA);
;             PG8_WAIT_V(8); PG8_WAIT_L(0); PG8_BAR; PG8_MMA(1, 0, At, B0); PG8_MMA(1, 1, At, B1); PG8_BAR; PG8_SCHED;
	s_add_i32 s76, 0, 0x18000
	s_add_i32 s77, 0, 0x1c000
	v_add_u32_e32 v128, s76, v221
	v_add_u32_e32 v156, s77, v221
	ds_read_b128 v[96:99], v128
	ds_read_b128 v[108:111], v128 offset:1024
	ds_read_b128 v[120:123], v128 offset:2048
	ds_read_b128 v[128:131], v128 offset:3072
	ds_read_b128 v[144:147], v156
	ds_read_b128 v[148:151], v156 offset:1024
	ds_read_b128 v[152:155], v156 offset:2048
	ds_read_b128 v[156:159], v156 offset:3072
	s_add_u32 s50, s50, 0xb0000
	s_addc_u32 s51, s51, 0
	s_mov_b32 m0, s56
	ds_read_b128 v[160:163], v225 offset:32768
	ds_read_b128 v[164:167], v225 offset:33792
	ds_read_b128 v[168:171], v225 offset:34816
	ds_read_b128 v[172:175], v225 offset:35840
	ds_read_b128 v[176:179], v225 offset:36864
	ds_read_b128 v[180:183], v225 offset:37888
	ds_read_b128 v[202:205], v225 offset:38912
	ds_read_b128 v[206:209], v225 offset:39936
	global_load_lds_dwordx4 v184, s[50:51]
	s_mov_b32 m0, s57
	s_nop 0
	global_load_lds_dwordx4 v188, s[50:51]
	s_waitcnt vmcnt(8)
	s_waitcnt lgkmcnt(0)
	s_barrier
	v_mfma_f32_16x16x32_bf16 v[140:143], v[96:99], v[160:163], v[140:143]
	v_mfma_f32_16x16x32_bf16 v[136:139], v[120:123], v[160:163], v[136:139]
	v_mfma_f32_16x16x32_bf16 v[116:119], v[96:99], v[168:171], v[116:119]
	v_mfma_f32_16x16x32_bf16 v[112:115], v[120:123], v[168:171], v[112:115]
	v_mfma_f32_16x16x32_bf16 v[92:95], v[96:99], v[176:179], v[92:95]
	v_mfma_f32_16x16x32_bf16 v[88:91], v[120:123], v[176:179], v[88:91]
	v_mfma_f32_16x16x32_bf16 v[76:79], v[96:99], v[202:205], v[76:79]
	v_mfma_f32_16x16x32_bf16 v[72:75], v[120:123], v[202:205], v[72:75]
	v_mfma_f32_16x16x32_bf16 v[140:143], v[108:111], v[164:167], v[140:143]
	v_mfma_f32_16x16x32_bf16 v[136:139], v[128:131], v[164:167], v[136:139]
	v_mfma_f32_16x16x32_bf16 v[116:119], v[108:111], v[172:175], v[116:119]
	v_mfma_f32_16x16x32_bf16 v[112:115], v[128:131], v[172:175], v[112:115]
	v_mfma_f32_16x16x32_bf16 v[92:95], v[108:111], v[180:183], v[92:95]
	v_mfma_f32_16x16x32_bf16 v[88:91], v[128:131], v[180:183], v[88:91]
	v_mfma_f32_16x16x32_bf16 v[76:79], v[108:111], v[206:209], v[76:79]
	v_mfma_f32_16x16x32_bf16 v[72:75], v[128:131], v[206:209], v[72:75]
	v_mfma_f32_16x16x32_bf16 v[132:135], v[144:147], v[160:163], v[132:135]
	v_mfma_f32_16x16x32_bf16 v[124:127], v[152:155], v[160:163], v[124:127]
	v_mfma_f32_16x16x32_bf16 v[104:107], v[144:147], v[168:171], v[104:107]
	v_mfma_f32_16x16x32_bf16 v[100:103], v[152:155], v[168:171], v[100:103]
	v_mfma_f32_16x16x32_bf16 v[84:87], v[144:147], v[176:179], v[84:87]
	v_mfma_f32_16x16x32_bf16 v[80:83], v[152:155], v[176:179], v[80:83]
	v_mfma_f32_16x16x32_bf16 v[68:71], v[144:147], v[202:205], v[68:71]
	v_mfma_f32_16x16x32_bf16 v[64:67], v[152:155], v[202:205], v[64:67]
	v_mfma_f32_16x16x32_bf16 v[132:135], v[148:151], v[164:167], v[132:135]
	v_mfma_f32_16x16x32_bf16 v[124:127], v[156:159], v[164:167], v[124:127]
	v_mfma_f32_16x16x32_bf16 v[104:107], v[148:151], v[172:175], v[104:107]
	v_mfma_f32_16x16x32_bf16 v[100:103], v[156:159], v[172:175], v[100:103]
	v_mfma_f32_16x16x32_bf16 v[84:87], v[148:151], v[180:183], v[84:87]
	v_mfma_f32_16x16x32_bf16 v[80:83], v[156:159], v[180:183], v[80:83]
	v_mfma_f32_16x16x32_bf16 v[68:71], v[148:151], v[206:209], v[68:71]
	v_mfma_f32_16x16x32_bf16 v[64:67], v[156:159], v[206:209], v[64:67]
	s_barrier
	s_add_i32 s50, s76, s53
	s_mov_b32 m0, s50
	ds_read_b128 v[160:163], v225 offset:49152
	ds_read_b128 v[164:167], v225 offset:50176
	ds_read_b128 v[168:171], v225 offset:51200
	ds_read_b128 v[172:175], v225 offset:52224
	ds_read_b128 v[176:179], v225 offset:53248
	ds_read_b128 v[180:183], v225 offset:54272
	ds_read_b128 v[202:205], v225 offset:55296
	ds_read_b128 v[206:209], v225 offset:56320
	global_load_lds_dwordx4 v186, s[98:99]
	s_add_i32 m0, s50, 0x2000
	s_add_u32 s34, s34, 0xb0080
	s_addc_u32 s35, s35, 0
	s_add_i32 s50, s77, s53
	global_load_lds_dwordx4 v190, s[98:99]
	s_mov_b32 m0, s50
	s_nop 0
	global_load_lds_dwordx4 v186, s[34:35]
	s_add_i32 m0, s50, 0x2000
	s_nop 0
	global_load_lds_dwordx4 v190, s[34:35]
	s_mov_b32 m0, s62
	s_nop 0
	global_load_lds_dwordx4 v184, s[100:101]
	s_mov_b32 m0, s63
	s_nop 0
	global_load_lds_dwordx4 v188, s[100:101]
	s_waitcnt vmcnt(8)
	s_waitcnt lgkmcnt(0)
	s_barrier
	v_mfma_f32_16x16x32_bf16 v[60:63], v[96:99], v[160:163], v[60:63]
	v_mfma_f32_16x16x32_bf16 v[56:59], v[120:123], v[160:163], v[56:59]
	v_mfma_f32_16x16x32_bf16 v[44:47], v[96:99], v[168:171], v[44:47]
	v_mfma_f32_16x16x32_bf16 v[40:43], v[120:123], v[168:171], v[40:43]
	v_mfma_f32_16x16x32_bf16 v[28:31], v[96:99], v[176:179], v[28:31]
	v_mfma_f32_16x16x32_bf16 v[24:27], v[120:123], v[176:179], v[24:27]
	v_mfma_f32_16x16x32_bf16 v[12:15], v[96:99], v[202:205], v[12:15]
	v_mfma_f32_16x16x32_bf16 v[8:11], v[120:123], v[202:205], v[8:11]
	v_mfma_f32_16x16x32_bf16 v[60:63], v[108:111], v[164:167], v[60:63]
	v_mfma_f32_16x16x32_bf16 v[56:59], v[128:131], v[164:167], v[56:59]
	v_mfma_f32_16x16x32_bf16 v[44:47], v[108:111], v[172:175], v[44:47]
	v_mfma_f32_16x16x32_bf16 v[40:43], v[128:131], v[172:175], v[40:43]
	v_mfma_f32_16x16x32_bf16 v[28:31], v[108:111], v[180:183], v[28:31]
	v_mfma_f32_16x16x32_bf16 v[24:27], v[128:131], v[180:183], v[24:27]
	v_mfma_f32_16x16x32_bf16 v[12:15], v[108:111], v[206:209], v[12:15]
	v_mfma_f32_16x16x32_bf16 v[8:11], v[128:131], v[206:209], v[8:11]
	v_mfma_f32_16x16x32_bf16 v[52:55], v[144:147], v[160:163], v[52:55]
	v_mfma_f32_16x16x32_bf16 v[48:51], v[152:155], v[160:163], v[48:51]
	v_mfma_f32_16x16x32_bf16 v[36:39], v[144:147], v[168:171], v[36:39]
	v_mfma_f32_16x16x32_bf16 v[32:35], v[152:155], v[168:171], v[32:35]
	v_mfma_f32_16x16x32_bf16 v[20:23], v[144:147], v[176:179], v[20:23]
	v_mfma_f32_16x16x32_bf16 v[16:19], v[152:155], v[176:179], v[16:19]
	v_mfma_f32_16x16x32_bf16 v[4:7], v[144:147], v[202:205], v[4:7]
	v_mfma_f32_16x16x32_bf16 v[0:3], v[152:155], v[202:205], v[0:3]
	v_mfma_f32_16x16x32_bf16 v[52:55], v[148:151], v[164:167], v[52:55]
	v_mfma_f32_16x16x32_bf16 v[48:51], v[156:159], v[164:167], v[48:51]
	v_mfma_f32_16x16x32_bf16 v[36:39], v[148:151], v[172:175], v[36:39]
	v_mfma_f32_16x16x32_bf16 v[32:35], v[156:159], v[172:175], v[32:35]
	v_mfma_f32_16x16x32_bf16 v[20:23], v[148:151], v[180:183], v[20:23]
	v_mfma_f32_16x16x32_bf16 v[16:19], v[156:159], v[180:183], v[16:19]
	v_mfma_f32_16x16x32_bf16 v[4:7], v[148:151], v[206:209], v[4:7]
	v_mfma_f32_16x16x32_bf16 v[0:3], v[156:159], v[206:209], v[0:3]
	s_barrier
	s_add_i32 s75, s75, 2
	s_add_u32 s20, s20, 0x100
	s_addc_u32 s21, s21, 0
	s_add_u32 s73, s73, 0x100
	s_addc_u32 s74, s74, 0
	s_cmp_gt_u32 s75, 41

; #define PG8_STAGE(bufoff, gbase, voff) do { _Pragma("unroll") for (int _i = 0; _i < 2; ++_i) \
;         __builtin_amdgcn_global_load_lds((const unsigned*)((const char*)(gbase) + (voff)[_i]), (PG8_LAS unsigned*)(lds + (bufoff) + ldsw + _i * 8192), 16, 0, 0); } while (0)
; #define PG8_LDA(dst, b, h) do { _Pragma("unroll") for (int m = 0; m < 4; ++m) _Pragma("unroll") for (int k = 0; k < 2; ++k) dst[m][k] = *(const PG8_LAS bf16x8*)(lds + PG8_SA(b, h) + aoff + m * 2048 + k * 1024); } while (0)
; #define PG8_WAIT_V(n) asm volatile("s_waitcnt vmcnt(" #n ")" ::: "memory")
; #define PG8_BAR __builtin_amdgcn_s_barrier()
;     __host__ __device__ bool next(int i, Unit& u) const {
;         const long L = (long)i * G + c; if (L >= nwg) return false;
;         int wgid = (int)L; { const int q = nwg / NXCD, r = nwg % NXCD, xcd = wgid % NXCD, off = wgid / NXCD; wgid = (xcd < r ? xcd * (q + 1) : r * (q + 1) + (xcd - r) * q) + off; }
;         const int nig = WGM * nN, gid = wgid / nig, fm = gid * WGM, gsz = (nM - fm) < WGM ? (nM - fm) : WGM;
;         u.pm = fm + ((wgid % nig) % gsz); u.pn = (wgid % nig) / gsz; return true;
;     }
; template <class Epi, class Sched, bool ALIGN_EPI = false, bool SP2 = false>
; __device__ __forceinline__ void gemm_phase(PG8_LAS unsigned char* lds, const Gemm g, const Sched& S, const Epi& E) {
;     ...
;         const bool has_next = S.next(ui + 1, nxt);
;         const char* nA = has_next ? (const char*)g.A + (size_t)nxt.pm * tstep : cA; const char* nB = has_next ? (const char*)g.Bt + (size_t)nxt.pn * tstep : cB;
;         for (int t = 0; t < nt; t += 2) {
;             const bool last = (t == nt - 2);
;             const char* a1 = cA + (size_t)(t + 1) * kstep;
;             const char* a2 = last ? nA : cA + (size_t)(t + 2) * kstep; const char* b2 = last ? nB : cB + (size_t)(t + 2) * kstep;
;             const char* a3 = a2 + kstep; const char* b3 = b2 + kstep;
;             if (last && has_next) S.a_ready(nxt);
;             if constexpr (SP2) {
;             PG8_LDB(B0, 0, 0); PG8_LDB(B1, 0, 1); PG8_SCHED; PG8_LDA(At, 0, 0); PG8_STAGE(PG8_SA(1, 1), a1 + hstep, voffA);
;             PG8_WAIT_V(8); PG8_WAIT_L(0); PG8_BAR; PG8_MMA(0, 0, At, B0); PG8_MMA(0, 1, At, B1); PG8_BAR; PG8_SCHED;
;             PG8_LDA(At, 0, 1); PG8_STAGE(PG8_SB(0, 0), b2, voffB); PG8_STAGE(PG8_SB(0, 1), b2 + hstep, voffB); PG8_STAGE(PG8_SA(0, 0), a2, voffA);
.LBB0_411:
	ds_read_b128 v[146:149], v165
	ds_read_b128 v[150:153], v165 offset:1024
	ds_read_b128 v[154:157], v165 offset:2048
	ds_read_b128 v[168:171], v165 offset:3072
	ds_read_b128 v[172:175], v166
	ds_read_b128 v[176:179], v166 offset:1024
	ds_read_b128 v[180:183], v166 offset:2048
	ds_read_b128 v[184:187], v166 offset:3072
	ds_read_b128 v[188:191], v167
	ds_read_b128 v[192:195], v167 offset:1024
	ds_read_b128 v[198:201], v167 offset:2048
	ds_read_b128 v[202:205], v167 offset:3072
	ds_read_b128 v[206:209], v167 offset:4096
	ds_read_b128 v[210:213], v167 offset:5120
	ds_read_b128 v[214:217], v167 offset:6144
	ds_read_b128 v[218:221], v167 offset:7168
	s_add_i32 s68, s68, 1
	s_mul_i32 s4, s68, s56
	s_mul_hi_u32 s5, s68, s57
	s_add_i32 s5, s5, s4
	s_mul_i32 s4, s68, s57
	s_add_u32 s48, s4, s2
	s_addc_u32 s49, s5, s3
	v_cmp_gt_i64_e32 vcc, s[48:49], v[144:145]
	v_cmp_lt_i64_e64 s[4:5], s[48:49], v[142:143]
	s_cbranch_vccnz .LBB0_413
	s_ashr_i32 s18, s48, 31
	s_lshr_b32 s18, s18, 29
	s_add_i32 s18, s48, s18
	s_ashr_i32 s19, s18, 3
	s_and_b32 s18, s18, -8
	s_sub_i32 s18, s48, s18
	s_cmp_lt_i32 s18, 0
	s_cselect_b32 s42, s64, 0x60
	s_mul_i32 s18, s42, s18
	s_add_i32 s18, s18, s19
	s_mul_hi_i32 s19, s18, 0x2aaaaaab
	s_lshr_b32 s42, s19, 31
	s_ashr_i32 s19, s19, 3
	s_add_i32 s19, s19, s42
	s_lshl_b32 s42, s19, 3
	s_sub_i32 s43, 0x80, s42
	s_min_i32 s43, s43, 8
	s_mul_i32 s19, s19, 48
	s_sub_i32 s19, s18, s19
	s_lshr_b32 s18, s19, 3
	s_mul_i32 s43, s18, s43
	s_sub_i32 s19, s19, s43
	s_add_i32 s42, s19, s42
.LBB0_413:
	s_ashr_i32 s43, s42, 31
	s_lshl_b64 s[48:49], s[42:43], 19
	s_add_u32 s48, s36, s48
	s_addc_u32 s49, s37, s49
	s_and_b64 s[50:51], s[4:5], exec
	s_cselect_b32 s43, s49, s21
	s_cselect_b32 s78, s48, s20
	s_ashr_i32 s19, s18, 31
	s_lshl_b64 s[50:51], s[18:19], 19
	s_add_u32 s50, s61, s50
	s_addc_u32 s51, s62, s51
	s_and_b64 s[54:55], s[4:5], exec
	s_cselect_b32 s19, s51, s53
	s_cselect_b32 s79, s50, s52
	s_add_u32 s20, s20, 0x40080
	s_addc_u32 s21, s21, 0
	s_add_u32 s80, s52, 0x100
	s_addc_u32 s81, s53, 0
	s_mov_b32 s84, -2
	s_add_u32 s52, s20, 0xfffc0080
	s_addc_u32 s53, s21, -1
	s_cmp_eq_u32 s84, 12
	s_cselect_b32 s55, s43, s53
	s_cselect_b32 s54, s78, s52
	s_cselect_b32 s53, s19, s81
	s_cselect_b32 s52, s79, s80
	s_add_i32 m0, s35, 0xc000
	global_load_lds_dwordx4 v138, s[20:21]
	s_add_i32 m0, s35, 0xe000
	s_nop 0
	global_load_lds_dwordx4 v140, s[20:21]
	s_waitcnt vmcnt(8)
	s_waitcnt lgkmcnt(0)
	s_barrier
	v_mfma_f32_16x16x32_bf16 v[124:127], v[146:149], v[188:191], 0
	v_mfma_f32_16x16x32_bf16 v[120:123], v[154:157], v[188:191], 0
	v_mfma_f32_16x16x32_bf16 v[108:111], v[146:149], v[198:201], 0
	v_mfma_f32_16x16x32_bf16 v[104:107], v[154:157], v[198:201], 0
	v_mfma_f32_16x16x32_bf16 v[92:95], v[146:149], v[206:209], 0
	v_mfma_f32_16x16x32_bf16 v[88:91], v[154:157], v[206:209], 0
	v_mfma_f32_16x16x32_bf16 v[76:79], v[146:149], v[214:217], 0
	v_mfma_f32_16x16x32_bf16 v[72:75], v[154:157], v[214:217], 0
	v_mfma_f32_16x16x32_bf16 v[124:127], v[150:153], v[192:195], v[124:127]
	v_mfma_f32_16x16x32_bf16 v[120:123], v[168:171], v[192:195], v[120:123]
	v_mfma_f32_16x16x32_bf16 v[108:111], v[150:153], v[202:205], v[108:111]
	v_mfma_f32_16x16x32_bf16 v[104:107], v[168:171], v[202:205], v[104:107]
	v_mfma_f32_16x16x32_bf16 v[92:95], v[150:153], v[210:213], v[92:95]
	v_mfma_f32_16x16x32_bf16 v[88:91], v[168:171], v[210:213], v[88:91]
	v_mfma_f32_16x16x32_bf16 v[76:79], v[150:153], v[218:221], v[76:79]
	v_mfma_f32_16x16x32_bf16 v[72:75], v[168:171], v[218:221], v[72:75]
	v_mfma_f32_16x16x32_bf16 v[116:119], v[172:175], v[188:191], 0
	v_mfma_f32_16x16x32_bf16 v[112:115], v[180:183], v[188:191], 0
	v_mfma_f32_16x16x32_bf16 v[100:103], v[172:175], v[198:201], 0
	v_mfma_f32_16x16x32_bf16 v[96:99], v[180:183], v[198:201], 0
	v_mfma_f32_16x16x32_bf16 v[84:87], v[172:175], v[206:209], 0
	v_mfma_f32_16x16x32_bf16 v[80:83], v[180:183], v[206:209], 0
	v_mfma_f32_16x16x32_bf16 v[68:71], v[172:175], v[214:217], 0
	v_mfma_f32_16x16x32_bf16 v[64:67], v[180:183], v[214:217], 0
	v_mfma_f32_16x16x32_bf16 v[116:119], v[176:179], v[192:195], v[116:119]
	v_mfma_f32_16x16x32_bf16 v[112:115], v[184:187], v[192:195], v[112:115]
	v_mfma_f32_16x16x32_bf16 v[100:103], v[176:179], v[202:205], v[100:103]
	v_mfma_f32_16x16x32_bf16 v[96:99], v[184:187], v[202:205], v[96:99]
	v_mfma_f32_16x16x32_bf16 v[84:87], v[176:179], v[210:213], v[84:87]
	v_mfma_f32_16x16x32_bf16 v[80:83], v[184:187], v[210:213], v[80:83]
	v_mfma_f32_16x16x32_bf16 v[68:71], v[176:179], v[218:221], v[68:71]
	v_mfma_f32_16x16x32_bf16 v[64:67], v[184:187], v[218:221], v[64:67]
	s_barrier
	s_add_i32 s85, s72, s63
	s_add_u32 s98, s52, s8
	s_addc_u32 s99, s53, s9
	s_add_u32 s100, s54, s8
	s_addc_u32 s101, s55, s9
	s_mov_b32 m0, s85
	ds_read_b128 v[188:191], v167 offset:16384
	ds_read_b128 v[192:195], v167 offset:17408
	ds_read_b128 v[198:201], v167 offset:18432
	ds_read_b128 v[202:205], v167 offset:19456
	ds_read_b128 v[206:209], v167 offset:20480
	ds_read_b128 v[210:213], v167 offset:21504
	ds_read_b128 v[214:217], v167 offset:22528
	ds_read_b128 v[218:221], v167 offset:23552
	global_load_lds_dwordx4 v132, s[52:53]
	s_add_i32 m0, s85, 0x2000
	s_add_u32 s86, s52, 0x40000
	s_addc_u32 s87, s53, 0
	s_add_i32 s85, s73, s63
	global_load_lds_dwordx4 v128, s[52:53]
	s_mov_b32 m0, s85
	s_nop 0
	global_load_lds_dwordx4 v132, s[86:87]
	s_add_i32 m0, s85, 0x2000
	s_nop 0
	global_load_lds_dwordx4 v128, s[86:87]
	s_mov_b32 m0, s35
	s_nop 0
	global_load_lds_dwordx4 v134, s[54:55]
	s_mov_b32 m0, s65
	s_nop 0
	global_load_lds_dwordx4 v130, s[54:55]
	s_waitcnt vmcnt(8)
	s_waitcnt lgkmcnt(0)
	s_barrier
; #define PG8_STAGE(bufoff, gbase, voff) do { _Pragma("unroll") for (int _i = 0; _i < 2; ++_i) \
;         __builtin_amdgcn_global_load_lds((const unsigned*)((const char*)(gbase) + (voff)[_i]), (PG8_LAS unsigned*)(lds + (bufoff) + ldsw + _i * 8192), 16, 0, 0); } while (0)
; #define PG8_LDA(dst, b, h) do { _Pragma("unroll") for (int m = 0; m < 4; ++m) _Pragma("unroll") for (int k = 0; k < 2; ++k) dst[m][k] = *(const PG8_LAS bf16x8*)(lds + PG8_SA(b, h) + aoff + m * 2048 + k * 1024); } while (0)
; #define PG8_LDB(dst, b, h) do { _Pragma("unroll") for (int n = 0; n < 2; ++n) _Pragma("unroll") for (int k = 0; k < 2; ++k) dst[n][k] = *(const PG8_LAS bf16x8*)(lds + PG8_SB(b, h) + boff + n * 2048 + k * 1024); } while (0)
; #define PG8_MMA(ai, bj, At, Bt) do { __builtin_amdgcn_s_setprio(1); _Pragma("unroll") for (int m = 0; m < 4; ++m) _Pragma("unroll") for (int n = 0; n < 2; ++n) _Pragma("unroll") for (int k = 0; k < 2; ++k) \
;         acc[ai][bj][m][n] = __builtin_amdgcn_mfma_f32_16x16x32_bf16(Bt[n][k], At[m][k], acc[ai][bj][m][n], 0, 0, 0); __builtin_amdgcn_s_setprio(0); } while (0)
; #define PG8_WAIT_V(n) asm volatile("s_waitcnt vmcnt(" #n ")" ::: "memory")
; #define PG8_WAIT_L(n) asm volatile("s_waitcnt lgkmcnt(" #n ")" ::: "memory")
; #define PG8_BAR __builtin_amdgcn_s_barrier()
; #define PG8_SCHED __builtin_amdgcn_sched_barrier(0)
; template <class Epi, class Sched, bool ALIGN_EPI = false, bool SP2 = false>
; __device__ __forceinline__ void gemm_phase(PG8_LAS unsigned char* lds, const Gemm g, const Sched& S, const Epi& E) {
;     ...
;             PG8_WAIT_V(8); PG8_WAIT_L(0); PG8_BAR; PG8_MMA(1, 0, At, B0); PG8_MMA(1, 1, At, B1); PG8_BAR; PG8_SCHED;
;             PG8_LDB(B0, 1, 0); PG8_LDB(B1, 1, 1); PG8_SCHED; PG8_LDA(At, 1, 0); PG8_STAGE(PG8_SA(0, 1), a2 + hstep, voffA);
;             PG8_WAIT_V(8); PG8_WAIT_L(0); PG8_BAR; PG8_MMA(0, 0, At, B0); PG8_MMA(0, 1, At, B1); PG8_BAR; PG8_SCHED;
	v_mfma_f32_16x16x32_bf16 v[60:63], v[146:149], v[188:191], 0
	v_mfma_f32_16x16x32_bf16 v[56:59], v[154:157], v[188:191], 0
	v_mfma_f32_16x16x32_bf16 v[44:47], v[146:149], v[198:201], 0
	v_mfma_f32_16x16x32_bf16 v[40:43], v[154:157], v[198:201], 0
	v_mfma_f32_16x16x32_bf16 v[28:31], v[146:149], v[206:209], 0
	v_mfma_f32_16x16x32_bf16 v[24:27], v[154:157], v[206:209], 0
	v_mfma_f32_16x16x32_bf16 v[12:15], v[146:149], v[214:217], 0
	v_mfma_f32_16x16x32_bf16 v[8:11], v[154:157], v[214:217], 0
	v_mfma_f32_16x16x32_bf16 v[60:63], v[150:153], v[192:195], v[60:63]
	v_mfma_f32_16x16x32_bf16 v[56:59], v[168:171], v[192:195], v[56:59]
	v_mfma_f32_16x16x32_bf16 v[44:47], v[150:153], v[202:205], v[44:47]
	v_mfma_f32_16x16x32_bf16 v[40:43], v[168:171], v[202:205], v[40:43]
	v_mfma_f32_16x16x32_bf16 v[28:31], v[150:153], v[210:213], v[28:31]
	v_mfma_f32_16x16x32_bf16 v[24:27], v[168:171], v[210:213], v[24:27]
	v_mfma_f32_16x16x32_bf16 v[12:15], v[150:153], v[218:221], v[12:15]
	v_mfma_f32_16x16x32_bf16 v[8:11], v[168:171], v[218:221], v[8:11]
	v_mfma_f32_16x16x32_bf16 v[52:55], v[172:175], v[188:191], 0
	v_mfma_f32_16x16x32_bf16 v[48:51], v[180:183], v[188:191], 0
	v_mfma_f32_16x16x32_bf16 v[36:39], v[172:175], v[198:201], 0
	v_mfma_f32_16x16x32_bf16 v[32:35], v[180:183], v[198:201], 0
	v_mfma_f32_16x16x32_bf16 v[20:23], v[172:175], v[206:209], 0
	v_mfma_f32_16x16x32_bf16 v[16:19], v[180:183], v[206:209], 0
	v_mfma_f32_16x16x32_bf16 v[4:7], v[172:175], v[214:217], 0
	v_mfma_f32_16x16x32_bf16 v[0:3], v[180:183], v[214:217], 0
	v_mfma_f32_16x16x32_bf16 v[52:55], v[176:179], v[192:195], v[52:55]
	v_mfma_f32_16x16x32_bf16 v[48:51], v[184:187], v[192:195], v[48:51]
	v_mfma_f32_16x16x32_bf16 v[36:39], v[176:179], v[202:205], v[36:39]
	v_mfma_f32_16x16x32_bf16 v[32:35], v[184:187], v[202:205], v[32:35]
	v_mfma_f32_16x16x32_bf16 v[20:23], v[176:179], v[210:213], v[20:23]
	v_mfma_f32_16x16x32_bf16 v[16:19], v[184:187], v[210:213], v[16:19]
	v_mfma_f32_16x16x32_bf16 v[4:7], v[176:179], v[218:221], v[4:7]
	v_mfma_f32_16x16x32_bf16 v[0:3], v[184:187], v[218:221], v[0:3]
	s_barrier
	s_add_i32 s85, 0, 0x18000
	v_add_u32_e32 v136, s85, v161
	s_add_i32 s86, 0, 0x1c000
	ds_read_b128 v[146:149], v136
	ds_read_b128 v[150:153], v136 offset:1024
	ds_read_b128 v[154:157], v136 offset:2048
	ds_read_b128 v[168:171], v136 offset:3072
	v_add_u32_e32 v136, s86, v161
	ds_read_b128 v[172:175], v136
	ds_read_b128 v[176:179], v136 offset:1024
	ds_read_b128 v[180:183], v136 offset:2048
	ds_read_b128 v[184:187], v136 offset:3072
	s_add_u32 s54, s54, 0x40000
	s_addc_u32 s55, s55, 0
	s_mov_b32 m0, s66
	ds_read_b128 v[188:191], v167 offset:32768
	ds_read_b128 v[192:195], v167 offset:33792
	ds_read_b128 v[198:201], v167 offset:34816
	ds_read_b128 v[202:205], v167 offset:35840
	ds_read_b128 v[206:209], v167 offset:36864
	ds_read_b128 v[210:213], v167 offset:37888
	ds_read_b128 v[214:217], v167 offset:38912
	ds_read_b128 v[218:221], v167 offset:39936
	global_load_lds_dwordx4 v134, s[54:55]
	s_mov_b32 m0, s67
	s_nop 0
	global_load_lds_dwordx4 v130, s[54:55]
	s_waitcnt vmcnt(8)
	s_waitcnt lgkmcnt(0)
	s_barrier
	v_mfma_f32_16x16x32_bf16 v[124:127], v[146:149], v[188:191], v[124:127]
	v_mfma_f32_16x16x32_bf16 v[120:123], v[154:157], v[188:191], v[120:123]
	v_mfma_f32_16x16x32_bf16 v[108:111], v[146:149], v[198:201], v[108:111]
	v_mfma_f32_16x16x32_bf16 v[104:107], v[154:157], v[198:201], v[104:107]
	v_mfma_f32_16x16x32_bf16 v[92:95], v[146:149], v[206:209], v[92:95]
	v_mfma_f32_16x16x32_bf16 v[88:91], v[154:157], v[206:209], v[88:91]
	v_mfma_f32_16x16x32_bf16 v[76:79], v[146:149], v[214:217], v[76:79]
	v_mfma_f32_16x16x32_bf16 v[72:75], v[154:157], v[214:217], v[72:75]
	v_mfma_f32_16x16x32_bf16 v[124:127], v[150:153], v[192:195], v[124:127]
	v_mfma_f32_16x16x32_bf16 v[120:123], v[168:171], v[192:195], v[120:123]
	v_mfma_f32_16x16x32_bf16 v[108:111], v[150:153], v[202:205], v[108:111]
	v_mfma_f32_16x16x32_bf16 v[104:107], v[168:171], v[202:205], v[104:107]
	v_mfma_f32_16x16x32_bf16 v[92:95], v[150:153], v[210:213], v[92:95]
	v_mfma_f32_16x16x32_bf16 v[88:91], v[168:171], v[210:213], v[88:91]
	v_mfma_f32_16x16x32_bf16 v[76:79], v[150:153], v[218:221], v[76:79]
	v_mfma_f32_16x16x32_bf16 v[72:75], v[168:171], v[218:221], v[72:75]
	v_mfma_f32_16x16x32_bf16 v[116:119], v[172:175], v[188:191], v[116:119]
	v_mfma_f32_16x16x32_bf16 v[112:115], v[180:183], v[188:191], v[112:115]
	v_mfma_f32_16x16x32_bf16 v[100:103], v[172:175], v[198:201], v[100:103]
	v_mfma_f32_16x16x32_bf16 v[96:99], v[180:183], v[198:201], v[96:99]
	v_mfma_f32_16x16x32_bf16 v[84:87], v[172:175], v[206:209], v[84:87]
	v_mfma_f32_16x16x32_bf16 v[80:83], v[180:183], v[206:209], v[80:83]
	v_mfma_f32_16x16x32_bf16 v[68:71], v[172:175], v[214:217], v[68:71]
	v_mfma_f32_16x16x32_bf16 v[64:67], v[180:183], v[214:217], v[64:67]
	v_mfma_f32_16x16x32_bf16 v[116:119], v[176:179], v[192:195], v[116:119]
	v_mfma_f32_16x16x32_bf16 v[112:115], v[184:187], v[192:195], v[112:115]
	v_mfma_f32_16x16x32_bf16 v[100:103], v[176:179], v[202:205], v[100:103]
	v_mfma_f32_16x16x32_bf16 v[96:99], v[184:187], v[202:205], v[96:99]
	v_mfma_f32_16x16x32_bf16 v[84:87], v[176:179], v[210:213], v[84:87]
	v_mfma_f32_16x16x32_bf16 v[80:83], v[184:187], v[210:213], v[80:83]
	v_mfma_f32_16x16x32_bf16 v[68:71], v[176:179], v[218:221], v[68:71]
	v_mfma_f32_16x16x32_bf16 v[64:67], v[184:187], v[218:221], v[64:67]
	s_barrier
; #define PG8_STAGE(bufoff, gbase, voff) do { _Pragma("unroll") for (int _i = 0; _i < 2; ++_i) \
;         __builtin_amdgcn_global_load_lds((const unsigned*)((const char*)(gbase) + (voff)[_i]), (PG8_LAS unsigned*)(lds + (bufoff) + ldsw + _i * 8192), 16, 0, 0); } while (0)
; #define PG8_LDA(dst, b, h) do { _Pragma("unroll") for (int m = 0; m < 4; ++m) _Pragma("unroll") for (int k = 0; k < 2; ++k) dst[m][k] = *(const PG8_LAS bf16x8*)(lds + PG8_SA(b, h) + aoff + m * 2048 + k * 1024); } while (0)
; #define PG8_MMA(ai, bj, At, Bt) do { __builtin_amdgcn_s_setprio(1); _Pragma("unroll") for (int m = 0; m < 4; ++m) _Pragma("unroll") for (int n = 0; n < 2; ++n) _Pragma("unroll") for (int k = 0; k < 2; ++k) \
;         acc[ai][bj][m][n] = __builtin_amdgcn_mfma_f32_16x16x32_bf16(Bt[n][k], At[m][k], acc[ai][bj][m][n], 0, 0, 0); __builtin_amdgcn_s_setprio(0); } while (0)
; #define PG8_WAIT_V(n) asm volatile("s_waitcnt vmcnt(" #n ")" ::: "memory")
; #define PG8_WAIT_L(n) asm volatile("s_waitcnt lgkmcnt(" #n ")" ::: "memory")
; #define PG8_BAR __builtin_amdgcn_s_barrier()
; #define PG8_SCHED __builtin_amdgcn_sched_barrier(0)
; template <class Epi, class Sched, bool ALIGN_EPI = false, bool SP2 = false>
; __device__ __forceinline__ void gemm_phase(PG8_LAS unsigned char* lds, const Gemm g, const Sched& S, const Epi& E) {
;     ...
;             PG8_LDA(At, 1, 1); PG8_STAGE(PG8_SB(1, 0), b3, voffB); PG8_STAGE(PG8_SB(1, 1), b3 + hstep, voffB); PG8_STAGE(PG8_SA(1, 0), a3, voffA);
;             PG8_WAIT_V(8); PG8_WAIT_L(0); PG8_BAR; PG8_MMA(1, 0, At, B0); PG8_MMA(1, 1, At, B1); PG8_BAR; PG8_SCHED;
	s_add_i32 s54, s85, s63
	s_mov_b32 m0, s54
	ds_read_b128 v[188:191], v167 offset:49152
	ds_read_b128 v[192:195], v167 offset:50176
	ds_read_b128 v[198:201], v167 offset:51200
	ds_read_b128 v[202:205], v167 offset:52224
	ds_read_b128 v[206:209], v167 offset:53248
	ds_read_b128 v[210:213], v167 offset:54272
	ds_read_b128 v[214:217], v167 offset:55296
	ds_read_b128 v[218:221], v167 offset:56320
	global_load_lds_dwordx4 v132, s[98:99]
	s_add_i32 m0, s54, 0x2000
	s_add_u32 s52, s52, 0x40080
	s_addc_u32 s53, s53, 0
	s_add_i32 s54, s86, s63
	global_load_lds_dwordx4 v128, s[98:99]
	s_mov_b32 m0, s54
	s_nop 0
	global_load_lds_dwordx4 v132, s[52:53]
	s_add_i32 m0, s54, 0x2000
	s_nop 0
	global_load_lds_dwordx4 v128, s[52:53]
	s_mov_b32 m0, s69
	s_nop 0
	global_load_lds_dwordx4 v134, s[100:101]
	s_mov_b32 m0, s70
	s_nop 0
	global_load_lds_dwordx4 v130, s[100:101]
	s_waitcnt vmcnt(8)
	s_waitcnt lgkmcnt(0)
	s_barrier
	v_mfma_f32_16x16x32_bf16 v[60:63], v[146:149], v[188:191], v[60:63]
	v_mfma_f32_16x16x32_bf16 v[56:59], v[154:157], v[188:191], v[56:59]
	v_mfma_f32_16x16x32_bf16 v[44:47], v[146:149], v[198:201], v[44:47]
	v_mfma_f32_16x16x32_bf16 v[40:43], v[154:157], v[198:201], v[40:43]
	v_mfma_f32_16x16x32_bf16 v[28:31], v[146:149], v[206:209], v[28:31]
	v_mfma_f32_16x16x32_bf16 v[24:27], v[154:157], v[206:209], v[24:27]
	v_mfma_f32_16x16x32_bf16 v[12:15], v[146:149], v[214:217], v[12:15]
	v_mfma_f32_16x16x32_bf16 v[8:11], v[154:157], v[214:217], v[8:11]
	v_mfma_f32_16x16x32_bf16 v[60:63], v[150:153], v[192:195], v[60:63]
	v_mfma_f32_16x16x32_bf16 v[56:59], v[168:171], v[192:195], v[56:59]
	v_mfma_f32_16x16x32_bf16 v[44:47], v[150:153], v[202:205], v[44:47]
	v_mfma_f32_16x16x32_bf16 v[40:43], v[168:171], v[202:205], v[40:43]
	v_mfma_f32_16x16x32_bf16 v[28:31], v[150:153], v[210:213], v[28:31]
	v_mfma_f32_16x16x32_bf16 v[24:27], v[168:171], v[210:213], v[24:27]
	v_mfma_f32_16x16x32_bf16 v[12:15], v[150:153], v[218:221], v[12:15]
	v_mfma_f32_16x16x32_bf16 v[8:11], v[168:171], v[218:221], v[8:11]
	v_mfma_f32_16x16x32_bf16 v[52:55], v[172:175], v[188:191], v[52:55]
	v_mfma_f32_16x16x32_bf16 v[48:51], v[180:183], v[188:191], v[48:51]
	v_mfma_f32_16x16x32_bf16 v[36:39], v[172:175], v[198:201], v[36:39]
	v_mfma_f32_16x16x32_bf16 v[32:35], v[180:183], v[198:201], v[32:35]
	v_mfma_f32_16x16x32_bf16 v[20:23], v[172:175], v[206:209], v[20:23]
	v_mfma_f32_16x16x32_bf16 v[16:19], v[180:183], v[206:209], v[16:19]
	v_mfma_f32_16x16x32_bf16 v[4:7], v[172:175], v[214:217], v[4:7]
	v_mfma_f32_16x16x32_bf16 v[0:3], v[180:183], v[214:217], v[0:3]
	v_mfma_f32_16x16x32_bf16 v[52:55], v[176:179], v[192:195], v[52:55]
	v_mfma_f32_16x16x32_bf16 v[48:51], v[184:187], v[192:195], v[48:51]
	v_mfma_f32_16x16x32_bf16 v[36:39], v[176:179], v[202:205], v[36:39]
	v_mfma_f32_16x16x32_bf16 v[32:35], v[184:187], v[202:205], v[32:35]
	v_mfma_f32_16x16x32_bf16 v[20:23], v[176:179], v[210:213], v[20:23]
	v_mfma_f32_16x16x32_bf16 v[16:19], v[184:187], v[210:213], v[16:19]
	v_mfma_f32_16x16x32_bf16 v[4:7], v[176:179], v[218:221], v[4:7]
	v_mfma_f32_16x16x32_bf16 v[0:3], v[184:187], v[218:221], v[0:3]
	s_barrier
	s_add_i32 s84, s84, 2
	s_add_u32 s20, s20, 0x100
	s_addc_u32 s21, s21, 0
	s_add_u32 s80, s80, 0x100
	s_addc_u32 s81, s81, 0
	s_cmp_gt_u32 s84, 13

; #define PG8_STAGE(bufoff, gbase, voff) do { _Pragma("unroll") for (int _i = 0; _i < 2; ++_i) \
;         __builtin_amdgcn_global_load_lds((const unsigned*)((const char*)(gbase) + (voff)[_i]), (PG8_LAS unsigned*)(lds + (bufoff) + ldsw + _i * 8192), 16, 0, 0); } while (0)
; #define PG8_LDA(dst, b, h) do { _Pragma("unroll") for (int m = 0; m < 4; ++m) _Pragma("unroll") for (int k = 0; k < 2; ++k) dst[m][k] = *(const PG8_LAS bf16x8*)(lds + PG8_SA(b, h) + aoff + m * 2048 + k * 1024); } while (0)
; #define PG8_LDB(dst, b, h) do { _Pragma("unroll") for (int n = 0; n < 2; ++n) _Pragma("unroll") for (int k = 0; k < 2; ++k) dst[n][k] = *(const PG8_LAS bf16x8*)(lds + PG8_SB(b, h) + boff + n * 2048 + k * 1024); } while (0)
; #define PG8_SCHED __builtin_amdgcn_sched_barrier(0)
;     __host__ __device__ bool next(int i, Unit& u) const {
;         const long L = (long)i * G + c; if (L >= nwg) return false;
;         int wgid = (int)L; { const int q = nwg / NXCD, r = nwg % NXCD, xcd = wgid % NXCD, off = wgid / NXCD; wgid = (xcd < r ? xcd * (q + 1) : r * (q + 1) + (xcd - r) * q) + off; }
; template <class Epi, class Sched, bool ALIGN_EPI = false, bool SP2 = false>
; __device__ __forceinline__ void gemm_phase(PG8_LAS unsigned char* lds, const Gemm g, const Sched& S, const Epi& E) {
;     ...
;         const bool has_next = S.next(ui + 1, nxt);
;         const char* nA = has_next ? (const char*)g.A + (size_t)nxt.pm * tstep : cA; const char* nB = has_next ? (const char*)g.Bt + (size_t)nxt.pn * tstep : cB;
;         for (int t = 0; t < nt; t += 2) {
;             const bool last = (t == nt - 2);
;             const char* a1 = cA + (size_t)(t + 1) * kstep;
;             const char* a2 = last ? nA : cA + (size_t)(t + 2) * kstep; const char* b2 = last ? nB : cB + (size_t)(t + 2) * kstep;
;             const char* a3 = a2 + kstep; const char* b3 = b2 + kstep;
;             if (last && has_next) S.a_ready(nxt);
;             if constexpr (SP2) {
;             PG8_LDB(B0, 0, 0); PG8_LDB(B1, 0, 1); PG8_SCHED; PG8_LDA(At, 0, 0); PG8_STAGE(PG8_SA(1, 1), a1 + hstep, voffA);
.LBB0_617:
	ds_read_b128 v[112:115], v167
	ds_read_b128 v[116:119], v167 offset:1024
	ds_read_b128 v[152:155], v167 offset:2048
	ds_read_b128 v[156:159], v167 offset:3072
	ds_read_b128 v[160:163], v168
	ds_read_b128 v[170:173], v168 offset:1024
	ds_read_b128 v[174:177], v168 offset:2048
	ds_read_b128 v[178:181], v168 offset:3072
	ds_read_b128 v[182:185], v169
	ds_read_b128 v[186:189], v169 offset:1024
	ds_read_b128 v[190:193], v169 offset:2048
	ds_read_b128 v[198:201], v169 offset:3072
	ds_read_b128 v[202:205], v169 offset:4096
	ds_read_b128 v[206:209], v169 offset:5120
	ds_read_b128 v[210:213], v169 offset:6144
	ds_read_b128 v[214:217], v169 offset:7168
	s_add_i32 s55, s55, 1
	s_mul_i32 s4, s55, s58
	s_mul_hi_u32 s5, s55, s59
	s_add_i32 s5, s5, s4
	s_mul_i32 s4, s55, s59
	s_add_u32 s18, s4, s2
	s_addc_u32 s19, s5, s3
	v_cmp_gt_i64_e32 vcc, s[18:19], v[150:151]
	v_cmp_lt_i64_e64 s[4:5], s[18:19], v[148:149]
	s_cbranch_vccnz .LBB0_623
	s_ashr_i32 s14, s18, 31
	s_lshr_b32 s14, s14, 29
	s_add_i32 s16, s18, s14
	s_and_b32 s14, s16, -8
	s_sub_i32 s17, s18, s14
	s_cmp_gt_i32 s17, -1
	s_mov_b64 s[14:15], -1
	s_cbranch_scc0 .LBB0_620
	s_lshl_b32 s18, s17, 5
	s_mov_b64 s[14:15], 0

; #define PG8_STAGE(bufoff, gbase, voff) do { _Pragma("unroll") for (int _i = 0; _i < 2; ++_i) \
;         __builtin_amdgcn_global_load_lds((const unsigned*)((const char*)(gbase) + (voff)[_i]), (PG8_LAS unsigned*)(lds + (bufoff) + ldsw + _i * 8192), 16, 0, 0); } while (0)
; #define PG8_LDA(dst, b, h) do { _Pragma("unroll") for (int m = 0; m < 4; ++m) _Pragma("unroll") for (int k = 0; k < 2; ++k) dst[m][k] = *(const PG8_LAS bf16x8*)(lds + PG8_SA(b, h) + aoff + m * 2048 + k * 1024); } while (0)
; #define PG8_LDB(dst, b, h) do { _Pragma("unroll") for (int n = 0; n < 2; ++n) _Pragma("unroll") for (int k = 0; k < 2; ++k) dst[n][k] = *(const PG8_LAS bf16x8*)(lds + PG8_SB(b, h) + boff + n * 2048 + k * 1024); } while (0)
; #define PG8_MMA(ai, bj, At, Bt) do { __builtin_amdgcn_s_setprio(1); _Pragma("unroll") for (int m = 0; m < 4; ++m) _Pragma("unroll") for (int n = 0; n < 2; ++n) _Pragma("unroll") for (int k = 0; k < 2; ++k) \
;         acc[ai][bj][m][n] = __builtin_amdgcn_mfma_f32_16x16x32_bf16(Bt[n][k], At[m][k], acc[ai][bj][m][n], 0, 0, 0); __builtin_amdgcn_s_setprio(0); } while (0)
; #define PG8_WAIT_V(n) asm volatile("s_waitcnt vmcnt(" #n ")" ::: "memory")
; template <class Epi, class Sched, bool ALIGN_EPI = false, bool SP2 = false>
; __device__ __forceinline__ void gemm_phase(PG8_LAS unsigned char* lds, const Gemm g, const Sched& S, const Epi& E) {
;     ...
;         const char* nA = has_next ? (const char*)g.A + (size_t)nxt.pm * tstep : cA; const char* nB = has_next ? (const char*)g.Bt + (size_t)nxt.pn * tstep : cB;
;         for (int t = 0; t < nt; t += 2) {
;             const bool last = (t == nt - 2);
;             const char* a1 = cA + (size_t)(t + 1) * kstep;
;             const char* a2 = last ? nA : cA + (size_t)(t + 2) * kstep; const char* b2 = last ? nB : cB + (size_t)(t + 2) * kstep;
;             const char* a3 = a2 + kstep; const char* b3 = b2 + kstep;
;             if (last && has_next) S.a_ready(nxt);
;             if constexpr (SP2) {
;             PG8_LDB(B0, 0, 0); PG8_LDB(B1, 0, 1); PG8_SCHED; PG8_LDA(At, 0, 0); PG8_STAGE(PG8_SA(1, 1), a1 + hstep, voffA);
;             PG8_WAIT_V(8); PG8_WAIT_L(0); PG8_BAR; PG8_MMA(0, 0, At, B0); PG8_MMA(0, 1, At, B1); PG8_BAR; PG8_SCHED;
;             PG8_LDA(At, 0, 1); PG8_STAGE(PG8_SB(0, 0), b2, voffB); PG8_STAGE(PG8_SB(0, 1), b2 + hstep, voffB); PG8_STAGE(PG8_SA(0, 0), a2, voffA);
.LBB0_623:
	s_ashr_i32 s17, s16, 31
	s_lshl_b64 s[18:19], s[16:17], 18
	s_add_u32 s18, s0, s18
	s_addc_u32 s19, s1, s19
	s_and_b64 s[38:39], s[4:5], exec
	s_cselect_b32 s17, s19, s21
	s_cselect_b32 s63, s18, s20
	s_ashr_i32 s15, s14, 31
	s_lshl_b64 s[38:39], s[14:15], 18
	s_add_u32 s38, s33, s38
	s_addc_u32 s39, s50, s39
	s_and_b64 s[48:49], s[4:5], exec
	s_cselect_b32 s15, s39, s47
	s_cselect_b32 s64, s38, s46
	s_add_u32 s20, s20, 0x20080
	s_addc_u32 s21, s21, 0
	s_add_u32 s65, s46, 0x100
	s_addc_u32 s66, s47, 0
	s_mov_b32 s67, -2
	s_add_u32 s46, s20, 0xfffe0080
	s_addc_u32 s47, s21, -1
	s_cmp_eq_u32 s67, 4
	s_cselect_b32 s49, s17, s47
	s_cselect_b32 s48, s63, s46
	s_cselect_b32 s47, s15, s66
	s_cselect_b32 s46, s64, s65
	s_add_i32 m0, s35, 0xc000
	global_load_lds_dwordx4 v144, s[20:21]
	s_add_i32 m0, s35, 0xe000
	s_nop 0
	global_load_lds_dwordx4 v146, s[20:21]
	s_waitcnt vmcnt(8)
	s_waitcnt lgkmcnt(0)
	s_barrier
	v_mfma_f32_16x16x32_bf16 v[132:135], v[112:115], v[182:185], 0
	v_mfma_f32_16x16x32_bf16 v[128:131], v[152:155], v[182:185], 0
	v_mfma_f32_16x16x32_bf16 v[124:127], v[112:115], v[190:193], 0
	v_mfma_f32_16x16x32_bf16 v[120:123], v[152:155], v[190:193], 0
	v_mfma_f32_16x16x32_bf16 v[108:111], v[112:115], v[202:205], 0
	v_mfma_f32_16x16x32_bf16 v[104:107], v[152:155], v[202:205], 0
	v_mfma_f32_16x16x32_bf16 v[100:103], v[112:115], v[210:213], 0
	v_mfma_f32_16x16x32_bf16 v[96:99], v[152:155], v[210:213], 0
	v_mfma_f32_16x16x32_bf16 v[132:135], v[116:119], v[186:189], v[132:135]
	v_mfma_f32_16x16x32_bf16 v[128:131], v[156:159], v[186:189], v[128:131]
	v_mfma_f32_16x16x32_bf16 v[124:127], v[116:119], v[198:201], v[124:127]
	v_mfma_f32_16x16x32_bf16 v[120:123], v[156:159], v[198:201], v[120:123]
	v_mfma_f32_16x16x32_bf16 v[108:111], v[116:119], v[206:209], v[108:111]
	v_mfma_f32_16x16x32_bf16 v[104:107], v[156:159], v[206:209], v[104:107]
	v_mfma_f32_16x16x32_bf16 v[100:103], v[116:119], v[214:217], v[100:103]
	v_mfma_f32_16x16x32_bf16 v[96:99], v[156:159], v[214:217], v[96:99]
	v_mfma_f32_16x16x32_bf16 v[60:63], v[160:163], v[182:185], 0
	v_mfma_f32_16x16x32_bf16 v[56:59], v[174:177], v[182:185], 0
	v_mfma_f32_16x16x32_bf16 v[52:55], v[160:163], v[190:193], 0
	v_mfma_f32_16x16x32_bf16 v[48:51], v[174:177], v[190:193], 0
	v_mfma_f32_16x16x32_bf16 v[44:47], v[160:163], v[202:205], 0
	v_mfma_f32_16x16x32_bf16 v[40:43], v[174:177], v[202:205], 0
	v_mfma_f32_16x16x32_bf16 v[36:39], v[160:163], v[210:213], 0
	v_mfma_f32_16x16x32_bf16 v[32:35], v[174:177], v[210:213], 0
	v_mfma_f32_16x16x32_bf16 v[60:63], v[170:173], v[186:189], v[60:63]
	v_mfma_f32_16x16x32_bf16 v[56:59], v[178:181], v[186:189], v[56:59]
	v_mfma_f32_16x16x32_bf16 v[52:55], v[170:173], v[198:201], v[52:55]
	v_mfma_f32_16x16x32_bf16 v[48:51], v[178:181], v[198:201], v[48:51]
	v_mfma_f32_16x16x32_bf16 v[44:47], v[170:173], v[206:209], v[44:47]
	v_mfma_f32_16x16x32_bf16 v[40:43], v[178:181], v[206:209], v[40:43]
	v_mfma_f32_16x16x32_bf16 v[36:39], v[170:173], v[214:217], v[36:39]
	v_mfma_f32_16x16x32_bf16 v[32:35], v[178:181], v[214:217], v[32:35]
	s_barrier
	s_add_i32 s68, s60, s51
	s_add_u32 s98, s46, s10
	s_addc_u32 s99, s47, s11
	s_add_u32 s100, s48, s10
	s_addc_u32 s101, s49, s11
	s_mov_b32 m0, s68
	ds_read_b128 v[182:185], v169 offset:16384
	ds_read_b128 v[186:189], v169 offset:17408
	ds_read_b128 v[190:193], v169 offset:18432
	ds_read_b128 v[198:201], v169 offset:19456
	ds_read_b128 v[202:205], v169 offset:20480
	ds_read_b128 v[206:209], v169 offset:21504
	ds_read_b128 v[210:213], v169 offset:22528
	ds_read_b128 v[214:217], v169 offset:23552
	global_load_lds_dwordx4 v138, s[46:47]
	s_add_i32 m0, s68, 0x2000
	s_add_u32 s68, s46, 0x20000
	s_addc_u32 s69, s47, 0
	s_add_i32 s70, s61, s51
	global_load_lds_dwordx4 v142, s[46:47]
	s_mov_b32 m0, s70
	s_nop 0
	global_load_lds_dwordx4 v138, s[68:69]
	s_add_i32 m0, s70, 0x2000
	s_nop 0
	global_load_lds_dwordx4 v142, s[68:69]
	s_mov_b32 m0, s35
	s_nop 0
	global_load_lds_dwordx4 v136, s[48:49]
	s_mov_b32 m0, s52
	s_nop 0
	global_load_lds_dwordx4 v140, s[48:49]
	s_waitcnt vmcnt(8)
	s_waitcnt lgkmcnt(0)
	s_barrier
	v_mfma_f32_16x16x32_bf16 v[92:95], v[112:115], v[182:185], 0
	v_mfma_f32_16x16x32_bf16 v[88:91], v[152:155], v[182:185], 0
	v_mfma_f32_16x16x32_bf16 v[84:87], v[112:115], v[190:193], 0
	v_mfma_f32_16x16x32_bf16 v[80:83], v[152:155], v[190:193], 0
	v_mfma_f32_16x16x32_bf16 v[76:79], v[112:115], v[202:205], 0
	v_mfma_f32_16x16x32_bf16 v[72:75], v[152:155], v[202:205], 0
	v_mfma_f32_16x16x32_bf16 v[68:71], v[112:115], v[210:213], 0
	v_mfma_f32_16x16x32_bf16 v[64:67], v[152:155], v[210:213], 0
	v_mfma_f32_16x16x32_bf16 v[92:95], v[116:119], v[186:189], v[92:95]
	v_mfma_f32_16x16x32_bf16 v[88:91], v[156:159], v[186:189], v[88:91]
	v_mfma_f32_16x16x32_bf16 v[84:87], v[116:119], v[198:201], v[84:87]
	v_mfma_f32_16x16x32_bf16 v[80:83], v[156:159], v[198:201], v[80:83]
	v_mfma_f32_16x16x32_bf16 v[76:79], v[116:119], v[206:209], v[76:79]
	v_mfma_f32_16x16x32_bf16 v[72:75], v[156:159], v[206:209], v[72:75]
	v_mfma_f32_16x16x32_bf16 v[68:71], v[116:119], v[214:217], v[68:71]
	v_mfma_f32_16x16x32_bf16 v[64:67], v[156:159], v[214:217], v[64:67]
	v_mfma_f32_16x16x32_bf16 v[28:31], v[160:163], v[182:185], 0
	v_mfma_f32_16x16x32_bf16 v[24:27], v[174:177], v[182:185], 0
	v_mfma_f32_16x16x32_bf16 v[20:23], v[160:163], v[190:193], 0
	v_mfma_f32_16x16x32_bf16 v[16:19], v[174:177], v[190:193], 0
	v_mfma_f32_16x16x32_bf16 v[12:15], v[160:163], v[202:205], 0
	v_mfma_f32_16x16x32_bf16 v[8:11], v[174:177], v[202:205], 0
	v_mfma_f32_16x16x32_bf16 v[4:7], v[160:163], v[210:213], 0
	v_mfma_f32_16x16x32_bf16 v[0:3], v[174:177], v[210:213], 0
	v_mfma_f32_16x16x32_bf16 v[28:31], v[170:173], v[186:189], v[28:31]
	v_mfma_f32_16x16x32_bf16 v[24:27], v[178:181], v[186:189], v[24:27]
	v_mfma_f32_16x16x32_bf16 v[20:23], v[170:173], v[198:201], v[20:23]
	v_mfma_f32_16x16x32_bf16 v[16:19], v[178:181], v[198:201], v[16:19]
	v_mfma_f32_16x16x32_bf16 v[12:15], v[170:173], v[206:209], v[12:15]
	v_mfma_f32_16x16x32_bf16 v[8:11], v[178:181], v[206:209], v[8:11]
	v_mfma_f32_16x16x32_bf16 v[4:7], v[170:173], v[214:217], v[4:7]
	v_mfma_f32_16x16x32_bf16 v[0:3], v[178:181], v[214:217], v[0:3]
	s_barrier
; #define PG8_STAGE(bufoff, gbase, voff) do { _Pragma("unroll") for (int _i = 0; _i < 2; ++_i) \
;         __builtin_amdgcn_global_load_lds((const unsigned*)((const char*)(gbase) + (voff)[_i]), (PG8_LAS unsigned*)(lds + (bufoff) + ldsw + _i * 8192), 16, 0, 0); } while (0)
; #define PG8_LDA(dst, b, h) do { _Pragma("unroll") for (int m = 0; m < 4; ++m) _Pragma("unroll") for (int k = 0; k < 2; ++k) dst[m][k] = *(const PG8_LAS bf16x8*)(lds + PG8_SA(b, h) + aoff + m * 2048 + k * 1024); } while (0)
; #define PG8_LDB(dst, b, h) do { _Pragma("unroll") for (int n = 0; n < 2; ++n) _Pragma("unroll") for (int k = 0; k < 2; ++k) dst[n][k] = *(const PG8_LAS bf16x8*)(lds + PG8_SB(b, h) + boff + n * 2048 + k * 1024); } while (0)
; #define PG8_MMA(ai, bj, At, Bt) do { __builtin_amdgcn_s_setprio(1); _Pragma("unroll") for (int m = 0; m < 4; ++m) _Pragma("unroll") for (int n = 0; n < 2; ++n) _Pragma("unroll") for (int k = 0; k < 2; ++k) \
;         acc[ai][bj][m][n] = __builtin_amdgcn_mfma_f32_16x16x32_bf16(Bt[n][k], At[m][k], acc[ai][bj][m][n], 0, 0, 0); __builtin_amdgcn_s_setprio(0); } while (0)
; #define PG8_WAIT_V(n) asm volatile("s_waitcnt vmcnt(" #n ")" ::: "memory")
; #define PG8_WAIT_L(n) asm volatile("s_waitcnt lgkmcnt(" #n ")" ::: "memory")
; #define PG8_BAR __builtin_amdgcn_s_barrier()
; #define PG8_SCHED __builtin_amdgcn_sched_barrier(0)
; template <class Epi, class Sched, bool ALIGN_EPI = false, bool SP2 = false>
; __device__ __forceinline__ void gemm_phase(PG8_LAS unsigned char* lds, const Gemm g, const Sched& S, const Epi& E) {
;     ...
;             PG8_LDB(B0, 1, 0); PG8_LDB(B1, 1, 1); PG8_SCHED; PG8_LDA(At, 1, 0); PG8_STAGE(PG8_SA(0, 1), a2 + hstep, voffA);
;             PG8_WAIT_V(8); PG8_WAIT_L(0); PG8_BAR; PG8_MMA(0, 0, At, B0); PG8_MMA(0, 1, At, B1); PG8_BAR; PG8_SCHED;
;             PG8_LDA(At, 1, 1); PG8_STAGE(PG8_SB(1, 0), b3, voffB); PG8_STAGE(PG8_SB(1, 1), b3 + hstep, voffB); PG8_STAGE(PG8_SA(1, 0), a3, voffA);
;             PG8_WAIT_V(8); PG8_WAIT_L(0); PG8_BAR; PG8_MMA(1, 0, At, B0); PG8_MMA(1, 1, At, B1); PG8_BAR; PG8_SCHED;
	s_add_i32 s68, 0, 0x18000
	s_add_i32 s69, 0, 0x1c000
	v_add_u32_e32 v156, s68, v165
	v_add_u32_e32 v178, s69, v165
	ds_read_b128 v[112:115], v156
	ds_read_b128 v[116:119], v156 offset:1024
	ds_read_b128 v[152:155], v156 offset:2048
	ds_read_b128 v[156:159], v156 offset:3072
	ds_read_b128 v[160:163], v178
	ds_read_b128 v[170:173], v178 offset:1024
	ds_read_b128 v[174:177], v178 offset:2048
	ds_read_b128 v[178:181], v178 offset:3072
	s_add_u32 s48, s48, 0x20000
	s_addc_u32 s49, s49, 0
	s_mov_b32 m0, s53
	ds_read_b128 v[182:185], v169 offset:32768
	ds_read_b128 v[186:189], v169 offset:33792
	ds_read_b128 v[190:193], v169 offset:34816
	ds_read_b128 v[198:201], v169 offset:35840
	ds_read_b128 v[202:205], v169 offset:36864
	ds_read_b128 v[206:209], v169 offset:37888
	ds_read_b128 v[210:213], v169 offset:38912
	ds_read_b128 v[214:217], v169 offset:39936
	global_load_lds_dwordx4 v136, s[48:49]
	s_mov_b32 m0, s54
	s_nop 0
	global_load_lds_dwordx4 v140, s[48:49]
	s_waitcnt vmcnt(8)
	s_waitcnt lgkmcnt(0)
	s_barrier
	v_mfma_f32_16x16x32_bf16 v[132:135], v[112:115], v[182:185], v[132:135]
	v_mfma_f32_16x16x32_bf16 v[128:131], v[152:155], v[182:185], v[128:131]
	v_mfma_f32_16x16x32_bf16 v[124:127], v[112:115], v[190:193], v[124:127]
	v_mfma_f32_16x16x32_bf16 v[120:123], v[152:155], v[190:193], v[120:123]
	v_mfma_f32_16x16x32_bf16 v[108:111], v[112:115], v[202:205], v[108:111]
	v_mfma_f32_16x16x32_bf16 v[104:107], v[152:155], v[202:205], v[104:107]
	v_mfma_f32_16x16x32_bf16 v[100:103], v[112:115], v[210:213], v[100:103]
	v_mfma_f32_16x16x32_bf16 v[96:99], v[152:155], v[210:213], v[96:99]
	v_mfma_f32_16x16x32_bf16 v[132:135], v[116:119], v[186:189], v[132:135]
	v_mfma_f32_16x16x32_bf16 v[128:131], v[156:159], v[186:189], v[128:131]
	v_mfma_f32_16x16x32_bf16 v[124:127], v[116:119], v[198:201], v[124:127]
	v_mfma_f32_16x16x32_bf16 v[120:123], v[156:159], v[198:201], v[120:123]
	v_mfma_f32_16x16x32_bf16 v[108:111], v[116:119], v[206:209], v[108:111]
	v_mfma_f32_16x16x32_bf16 v[104:107], v[156:159], v[206:209], v[104:107]
	v_mfma_f32_16x16x32_bf16 v[100:103], v[116:119], v[214:217], v[100:103]
	v_mfma_f32_16x16x32_bf16 v[96:99], v[156:159], v[214:217], v[96:99]
	v_mfma_f32_16x16x32_bf16 v[60:63], v[160:163], v[182:185], v[60:63]
	v_mfma_f32_16x16x32_bf16 v[56:59], v[174:177], v[182:185], v[56:59]
	v_mfma_f32_16x16x32_bf16 v[52:55], v[160:163], v[190:193], v[52:55]
	v_mfma_f32_16x16x32_bf16 v[48:51], v[174:177], v[190:193], v[48:51]
	v_mfma_f32_16x16x32_bf16 v[44:47], v[160:163], v[202:205], v[44:47]
	v_mfma_f32_16x16x32_bf16 v[40:43], v[174:177], v[202:205], v[40:43]
	v_mfma_f32_16x16x32_bf16 v[36:39], v[160:163], v[210:213], v[36:39]
	v_mfma_f32_16x16x32_bf16 v[32:35], v[174:177], v[210:213], v[32:35]
	v_mfma_f32_16x16x32_bf16 v[60:63], v[170:173], v[186:189], v[60:63]
	v_mfma_f32_16x16x32_bf16 v[56:59], v[178:181], v[186:189], v[56:59]
	v_mfma_f32_16x16x32_bf16 v[52:55], v[170:173], v[198:201], v[52:55]
	v_mfma_f32_16x16x32_bf16 v[48:51], v[178:181], v[198:201], v[48:51]
	v_mfma_f32_16x16x32_bf16 v[44:47], v[170:173], v[206:209], v[44:47]
	v_mfma_f32_16x16x32_bf16 v[40:43], v[178:181], v[206:209], v[40:43]
	v_mfma_f32_16x16x32_bf16 v[36:39], v[170:173], v[214:217], v[36:39]
	v_mfma_f32_16x16x32_bf16 v[32:35], v[178:181], v[214:217], v[32:35]
	s_barrier
	s_add_i32 s48, s68, s51
	s_mov_b32 m0, s48
	ds_read_b128 v[182:185], v169 offset:49152
	ds_read_b128 v[186:189], v169 offset:50176
	ds_read_b128 v[190:193], v169 offset:51200
	ds_read_b128 v[198:201], v169 offset:52224
	ds_read_b128 v[202:205], v169 offset:53248
	ds_read_b128 v[206:209], v169 offset:54272
	ds_read_b128 v[210:213], v169 offset:55296
	ds_read_b128 v[214:217], v169 offset:56320
	global_load_lds_dwordx4 v138, s[98:99]
	s_add_i32 m0, s48, 0x2000
	s_add_u32 s46, s46, 0x20080
	s_addc_u32 s47, s47, 0
	s_add_i32 s48, s69, s51
	global_load_lds_dwordx4 v142, s[98:99]
	s_mov_b32 m0, s48
	s_nop 0
	global_load_lds_dwordx4 v138, s[46:47]
	s_add_i32 m0, s48, 0x2000
	s_nop 0
	global_load_lds_dwordx4 v142, s[46:47]
	s_mov_b32 m0, s56
	s_nop 0
	global_load_lds_dwordx4 v136, s[100:101]
	s_mov_b32 m0, s57
	s_nop 0
	global_load_lds_dwordx4 v140, s[100:101]
	s_waitcnt vmcnt(8)
	s_waitcnt lgkmcnt(0)
	s_barrier
	v_mfma_f32_16x16x32_bf16 v[92:95], v[112:115], v[182:185], v[92:95]
	v_mfma_f32_16x16x32_bf16 v[88:91], v[152:155], v[182:185], v[88:91]
	v_mfma_f32_16x16x32_bf16 v[84:87], v[112:115], v[190:193], v[84:87]
	v_mfma_f32_16x16x32_bf16 v[80:83], v[152:155], v[190:193], v[80:83]
	v_mfma_f32_16x16x32_bf16 v[76:79], v[112:115], v[202:205], v[76:79]
	v_mfma_f32_16x16x32_bf16 v[72:75], v[152:155], v[202:205], v[72:75]
	v_mfma_f32_16x16x32_bf16 v[68:71], v[112:115], v[210:213], v[68:71]
	v_mfma_f32_16x16x32_bf16 v[64:67], v[152:155], v[210:213], v[64:67]
	v_mfma_f32_16x16x32_bf16 v[92:95], v[116:119], v[186:189], v[92:95]
	v_mfma_f32_16x16x32_bf16 v[88:91], v[156:159], v[186:189], v[88:91]
	v_mfma_f32_16x16x32_bf16 v[84:87], v[116:119], v[198:201], v[84:87]
	v_mfma_f32_16x16x32_bf16 v[80:83], v[156:159], v[198:201], v[80:83]
	v_mfma_f32_16x16x32_bf16 v[76:79], v[116:119], v[206:209], v[76:79]
	v_mfma_f32_16x16x32_bf16 v[72:75], v[156:159], v[206:209], v[72:75]
	v_mfma_f32_16x16x32_bf16 v[68:71], v[116:119], v[214:217], v[68:71]
	v_mfma_f32_16x16x32_bf16 v[64:67], v[156:159], v[214:217], v[64:67]
	v_mfma_f32_16x16x32_bf16 v[28:31], v[160:163], v[182:185], v[28:31]
	v_mfma_f32_16x16x32_bf16 v[24:27], v[174:177], v[182:185], v[24:27]
	v_mfma_f32_16x16x32_bf16 v[20:23], v[160:163], v[190:193], v[20:23]
	v_mfma_f32_16x16x32_bf16 v[16:19], v[174:177], v[190:193], v[16:19]
	v_mfma_f32_16x16x32_bf16 v[12:15], v[160:163], v[202:205], v[12:15]
	v_mfma_f32_16x16x32_bf16 v[8:11], v[174:177], v[202:205], v[8:11]
	v_mfma_f32_16x16x32_bf16 v[4:7], v[160:163], v[210:213], v[4:7]
	v_mfma_f32_16x16x32_bf16 v[0:3], v[174:177], v[210:213], v[0:3]
	v_mfma_f32_16x16x32_bf16 v[28:31], v[170:173], v[186:189], v[28:31]
	v_mfma_f32_16x16x32_bf16 v[24:27], v[178:181], v[186:189], v[24:27]
	v_mfma_f32_16x16x32_bf16 v[20:23], v[170:173], v[198:201], v[20:23]
	v_mfma_f32_16x16x32_bf16 v[16:19], v[178:181], v[198:201], v[16:19]
	v_mfma_f32_16x16x32_bf16 v[12:15], v[170:173], v[206:209], v[12:15]
	v_mfma_f32_16x16x32_bf16 v[8:11], v[178:181], v[206:209], v[8:11]
	v_mfma_f32_16x16x32_bf16 v[4:7], v[170:173], v[214:217], v[4:7]
	v_mfma_f32_16x16x32_bf16 v[0:3], v[178:181], v[214:217], v[0:3]
	s_barrier
	s_add_i32 s67, s67, 2
	s_add_u32 s20, s20, 0x100
	s_addc_u32 s21, s21, 0
	s_add_u32 s65, s65, 0x100
	s_addc_u32 s66, s66, 0
	s_cmp_gt_u32 s67, 5

; #define PG8_STAGE(bufoff, gbase, voff) do { _Pragma("unroll") for (int _i = 0; _i < 2; ++_i) \
;         __builtin_amdgcn_global_load_lds((const unsigned*)((const char*)(gbase) + (voff)[_i]), (PG8_LAS unsigned*)(lds + (bufoff) + ldsw + _i * 8192), 16, 0, 0); } while (0)
; #define PG8_LDA(dst, b, h) do { _Pragma("unroll") for (int m = 0; m < 4; ++m) _Pragma("unroll") for (int k = 0; k < 2; ++k) dst[m][k] = *(const PG8_LAS bf16x8*)(lds + PG8_SA(b, h) + aoff + m * 2048 + k * 1024); } while (0)
; #define PG8_LDB(dst, b, h) do { _Pragma("unroll") for (int n = 0; n < 2; ++n) _Pragma("unroll") for (int k = 0; k < 2; ++k) dst[n][k] = *(const PG8_LAS bf16x8*)(lds + PG8_SB(b, h) + boff + n * 2048 + k * 1024); } while (0)
; #define PG8_MMA(ai, bj, At, Bt) do { __builtin_amdgcn_s_setprio(1); _Pragma("unroll") for (int m = 0; m < 4; ++m) _Pragma("unroll") for (int n = 0; n < 2; ++n) _Pragma("unroll") for (int k = 0; k < 2; ++k) \
;         acc[ai][bj][m][n] = __builtin_amdgcn_mfma_f32_16x16x32_bf16(Bt[n][k], At[m][k], acc[ai][bj][m][n], 0, 0, 0); __builtin_amdgcn_s_setprio(0); } while (0)
; #define PG8_WAIT_V(n) asm volatile("s_waitcnt vmcnt(" #n ")" ::: "memory")
; template <class Epi, class Sched, bool ALIGN_EPI = false, bool SP2 = false>
; __device__ __forceinline__ void gemm_phase(PG8_LAS unsigned char* lds, const Gemm g, const Sched& S, const Epi& E) {
;     ...
;         const char* nA = has_next ? (const char*)g.A + (size_t)nxt.pm * tstep : cA; const char* nB = has_next ? (const char*)g.Bt + (size_t)nxt.pn * tstep : cB;
;         for (int t = 0; t < nt; t += 2) {
;             const bool last = (t == nt - 2);
;             const char* a1 = cA + (size_t)(t + 1) * kstep;
;             const char* a2 = last ? nA : cA + (size_t)(t + 2) * kstep; const char* b2 = last ? nB : cB + (size_t)(t + 2) * kstep;
;             const char* a3 = a2 + kstep; const char* b3 = b2 + kstep;
;             if (last && has_next) S.a_ready(nxt);
;             if constexpr (SP2) {
;             PG8_LDB(B0, 0, 0); PG8_LDB(B1, 0, 1); PG8_SCHED; PG8_LDA(At, 0, 0); PG8_STAGE(PG8_SA(1, 1), a1 + hstep, voffA);
;             PG8_WAIT_V(8); PG8_WAIT_L(0); PG8_BAR; PG8_MMA(0, 0, At, B0); PG8_MMA(0, 1, At, B1); PG8_BAR; PG8_SCHED;
;             PG8_LDA(At, 0, 1); PG8_STAGE(PG8_SB(0, 0), b2, voffB); PG8_STAGE(PG8_SB(0, 1), b2 + hstep, voffB); PG8_STAGE(PG8_SA(0, 0), a2, voffA);
.LBB0_704:
	s_ashr_i32 s47, s46, 31
	s_lshl_b64 s[48:49], s[46:47], 19
	s_add_u32 s48, s42, s48
	s_addc_u32 s49, s43, s49
	s_and_b64 s[50:51], s[6:7], exec
	s_cselect_b32 s35, s49, s21
	s_cselect_b32 s47, s48, s20
	s_ashr_i32 s45, s44, 31
	s_lshl_b64 s[50:51], s[44:45], 19
	s_add_u32 s50, s3, s50
	s_addc_u32 s51, s33, s51
	s_and_b64 s[56:57], s[6:7], exec
	s_cselect_b32 s45, s51, s55
	s_cselect_b32 s73, s50, s54
	s_add_u32 s20, s20, 0x40080
	s_addc_u32 s21, s21, 0
	s_add_u32 s74, s54, 0x100
	s_addc_u32 s75, s55, 0
	s_mov_b32 s76, -2
	s_waitcnt lgkmcnt(0)
	ds_read_b128 v[96:99], v223
	ds_read_b128 v[108:111], v223 offset:1024
	ds_read_b128 v[120:123], v223 offset:2048
	ds_read_b128 v[128:131], v223 offset:3072
	ds_read_b128 v[144:147], v224
	ds_read_b128 v[148:151], v224 offset:1024
	ds_read_b128 v[152:155], v224 offset:2048
	ds_read_b128 v[156:159], v224 offset:3072
	ds_read_b128 v[160:163], v225
	ds_read_b128 v[164:167], v225 offset:1024
	ds_read_b128 v[168:171], v225 offset:2048
	ds_read_b128 v[172:175], v225 offset:3072
	ds_read_b128 v[176:179], v225 offset:4096
	ds_read_b128 v[180:183], v225 offset:5120
	ds_read_b128 v[202:205], v225 offset:6144
	ds_read_b128 v[206:209], v225 offset:7168
	s_add_u32 s54, s20, 0xfffc0080
	s_addc_u32 s55, s21, -1
	s_cmp_eq_u32 s76, 12
	s_cselect_b32 s57, s35, s55
	s_cselect_b32 s56, s47, s54
	s_cselect_b32 s55, s45, s75
	s_cselect_b32 s54, s73, s74
	s_add_i32 m0, s53, 0xc000
	global_load_lds_dwordx4 v192, s[20:21]
	s_add_i32 m0, s53, 0xe000
	s_nop 0
	global_load_lds_dwordx4 v194, s[20:21]
	s_waitcnt vmcnt(8)
	s_waitcnt lgkmcnt(0)
	s_barrier
	v_mfma_f32_16x16x32_bf16 v[140:143], v[96:99], v[160:163], 0
	v_mfma_f32_16x16x32_bf16 v[136:139], v[120:123], v[160:163], 0
	v_mfma_f32_16x16x32_bf16 v[116:119], v[96:99], v[168:171], 0
	v_mfma_f32_16x16x32_bf16 v[112:115], v[120:123], v[168:171], 0
	v_mfma_f32_16x16x32_bf16 v[92:95], v[96:99], v[176:179], 0
	v_mfma_f32_16x16x32_bf16 v[88:91], v[120:123], v[176:179], 0
	v_mfma_f32_16x16x32_bf16 v[76:79], v[96:99], v[202:205], 0
	v_mfma_f32_16x16x32_bf16 v[72:75], v[120:123], v[202:205], 0
	v_mfma_f32_16x16x32_bf16 v[140:143], v[108:111], v[164:167], v[140:143]
	v_mfma_f32_16x16x32_bf16 v[136:139], v[128:131], v[164:167], v[136:139]
	v_mfma_f32_16x16x32_bf16 v[116:119], v[108:111], v[172:175], v[116:119]
	v_mfma_f32_16x16x32_bf16 v[112:115], v[128:131], v[172:175], v[112:115]
	v_mfma_f32_16x16x32_bf16 v[92:95], v[108:111], v[180:183], v[92:95]
	v_mfma_f32_16x16x32_bf16 v[88:91], v[128:131], v[180:183], v[88:91]
	v_mfma_f32_16x16x32_bf16 v[76:79], v[108:111], v[206:209], v[76:79]
	v_mfma_f32_16x16x32_bf16 v[72:75], v[128:131], v[206:209], v[72:75]
	v_mfma_f32_16x16x32_bf16 v[132:135], v[144:147], v[160:163], 0
	v_mfma_f32_16x16x32_bf16 v[124:127], v[152:155], v[160:163], 0
	v_mfma_f32_16x16x32_bf16 v[104:107], v[144:147], v[168:171], 0
	v_mfma_f32_16x16x32_bf16 v[100:103], v[152:155], v[168:171], 0
	v_mfma_f32_16x16x32_bf16 v[84:87], v[144:147], v[176:179], 0
	v_mfma_f32_16x16x32_bf16 v[80:83], v[152:155], v[176:179], 0
	v_mfma_f32_16x16x32_bf16 v[68:71], v[144:147], v[202:205], 0
	v_mfma_f32_16x16x32_bf16 v[64:67], v[152:155], v[202:205], 0
	v_mfma_f32_16x16x32_bf16 v[132:135], v[148:151], v[164:167], v[132:135]
	v_mfma_f32_16x16x32_bf16 v[124:127], v[156:159], v[164:167], v[124:127]
	v_mfma_f32_16x16x32_bf16 v[104:107], v[148:151], v[172:175], v[104:107]
	v_mfma_f32_16x16x32_bf16 v[100:103], v[156:159], v[172:175], v[100:103]
	v_mfma_f32_16x16x32_bf16 v[84:87], v[148:151], v[180:183], v[84:87]
	v_mfma_f32_16x16x32_bf16 v[80:83], v[156:159], v[180:183], v[80:83]
	v_mfma_f32_16x16x32_bf16 v[68:71], v[148:151], v[206:209], v[68:71]
	v_mfma_f32_16x16x32_bf16 v[64:67], v[156:159], v[206:209], v[64:67]
	s_barrier
	s_add_i32 s77, s71, s58
	s_add_u32 s98, s54, s12
	s_addc_u32 s99, s55, s13
	s_add_u32 s100, s56, s12
	s_addc_u32 s101, s57, s13
	s_mov_b32 m0, s77
	ds_read_b128 v[160:163], v225 offset:16384
	ds_read_b128 v[164:167], v225 offset:17408
	ds_read_b128 v[168:171], v225 offset:18432
	ds_read_b128 v[172:175], v225 offset:19456
	ds_read_b128 v[176:179], v225 offset:20480
	ds_read_b128 v[180:183], v225 offset:21504
	ds_read_b128 v[202:205], v225 offset:22528
	ds_read_b128 v[206:209], v225 offset:23552
	global_load_lds_dwordx4 v186, s[54:55]
	s_add_i32 m0, s77, 0x2000
	s_add_u32 s78, s54, 0x40000
	s_addc_u32 s79, s55, 0
	s_add_i32 s77, s72, s58
	global_load_lds_dwordx4 v190, s[54:55]
	s_mov_b32 m0, s77
	s_nop 0
	global_load_lds_dwordx4 v186, s[78:79]
	s_add_i32 m0, s77, 0x2000
	s_nop 0
	global_load_lds_dwordx4 v190, s[78:79]
	s_mov_b32 m0, s53
	s_nop 0
	global_load_lds_dwordx4 v184, s[56:57]
	s_mov_b32 m0, s59
	s_nop 0
	global_load_lds_dwordx4 v188, s[56:57]
	s_waitcnt vmcnt(8)
	s_waitcnt lgkmcnt(0)
	s_barrier
; #define PG8_STAGE(bufoff, gbase, voff) do { _Pragma("unroll") for (int _i = 0; _i < 2; ++_i) \
;         __builtin_amdgcn_global_load_lds((const unsigned*)((const char*)(gbase) + (voff)[_i]), (PG8_LAS unsigned*)(lds + (bufoff) + ldsw + _i * 8192), 16, 0, 0); } while (0)
; #define PG8_LDA(dst, b, h) do { _Pragma("unroll") for (int m = 0; m < 4; ++m) _Pragma("unroll") for (int k = 0; k < 2; ++k) dst[m][k] = *(const PG8_LAS bf16x8*)(lds + PG8_SA(b, h) + aoff + m * 2048 + k * 1024); } while (0)
; #define PG8_LDB(dst, b, h) do { _Pragma("unroll") for (int n = 0; n < 2; ++n) _Pragma("unroll") for (int k = 0; k < 2; ++k) dst[n][k] = *(const PG8_LAS bf16x8*)(lds + PG8_SB(b, h) + boff + n * 2048 + k * 1024); } while (0)
; #define PG8_MMA(ai, bj, At, Bt) do { __builtin_amdgcn_s_setprio(1); _Pragma("unroll") for (int m = 0; m < 4; ++m) _Pragma("unroll") for (int n = 0; n < 2; ++n) _Pragma("unroll") for (int k = 0; k < 2; ++k) \
;         acc[ai][bj][m][n] = __builtin_amdgcn_mfma_f32_16x16x32_bf16(Bt[n][k], At[m][k], acc[ai][bj][m][n], 0, 0, 0); __builtin_amdgcn_s_setprio(0); } while (0)
; #define PG8_WAIT_V(n) asm volatile("s_waitcnt vmcnt(" #n ")" ::: "memory")
; #define PG8_WAIT_L(n) asm volatile("s_waitcnt lgkmcnt(" #n ")" ::: "memory")
; #define PG8_BAR __builtin_amdgcn_s_barrier()
; #define PG8_SCHED __builtin_amdgcn_sched_barrier(0)
; template <class Epi, class Sched, bool ALIGN_EPI = false, bool SP2 = false>
; __device__ __forceinline__ void gemm_phase(PG8_LAS unsigned char* lds, const Gemm g, const Sched& S, const Epi& E) {
;     ...
;             PG8_WAIT_V(8); PG8_WAIT_L(0); PG8_BAR; PG8_MMA(1, 0, At, B0); PG8_MMA(1, 1, At, B1); PG8_BAR; PG8_SCHED;
;             PG8_LDB(B0, 1, 0); PG8_LDB(B1, 1, 1); PG8_SCHED; PG8_LDA(At, 1, 0); PG8_STAGE(PG8_SA(0, 1), a2 + hstep, voffA);
;             PG8_WAIT_V(8); PG8_WAIT_L(0); PG8_BAR; PG8_MMA(0, 0, At, B0); PG8_MMA(0, 1, At, B1); PG8_BAR; PG8_SCHED;
	v_mfma_f32_16x16x32_bf16 v[60:63], v[96:99], v[160:163], 0
	v_mfma_f32_16x16x32_bf16 v[56:59], v[120:123], v[160:163], 0
	v_mfma_f32_16x16x32_bf16 v[44:47], v[96:99], v[168:171], 0
	v_mfma_f32_16x16x32_bf16 v[40:43], v[120:123], v[168:171], 0
	v_mfma_f32_16x16x32_bf16 v[28:31], v[96:99], v[176:179], 0
	v_mfma_f32_16x16x32_bf16 v[24:27], v[120:123], v[176:179], 0
	v_mfma_f32_16x16x32_bf16 v[12:15], v[96:99], v[202:205], 0
	v_mfma_f32_16x16x32_bf16 v[8:11], v[120:123], v[202:205], 0
	v_mfma_f32_16x16x32_bf16 v[60:63], v[108:111], v[164:167], v[60:63]
	v_mfma_f32_16x16x32_bf16 v[56:59], v[128:131], v[164:167], v[56:59]
	v_mfma_f32_16x16x32_bf16 v[44:47], v[108:111], v[172:175], v[44:47]
	v_mfma_f32_16x16x32_bf16 v[40:43], v[128:131], v[172:175], v[40:43]
	v_mfma_f32_16x16x32_bf16 v[28:31], v[108:111], v[180:183], v[28:31]
	v_mfma_f32_16x16x32_bf16 v[24:27], v[128:131], v[180:183], v[24:27]
	v_mfma_f32_16x16x32_bf16 v[12:15], v[108:111], v[206:209], v[12:15]
	v_mfma_f32_16x16x32_bf16 v[8:11], v[128:131], v[206:209], v[8:11]
	v_mfma_f32_16x16x32_bf16 v[52:55], v[144:147], v[160:163], 0
	v_mfma_f32_16x16x32_bf16 v[48:51], v[152:155], v[160:163], 0
	v_mfma_f32_16x16x32_bf16 v[36:39], v[144:147], v[168:171], 0
	v_mfma_f32_16x16x32_bf16 v[32:35], v[152:155], v[168:171], 0
	v_mfma_f32_16x16x32_bf16 v[20:23], v[144:147], v[176:179], 0
	v_mfma_f32_16x16x32_bf16 v[16:19], v[152:155], v[176:179], 0
	v_mfma_f32_16x16x32_bf16 v[4:7], v[144:147], v[202:205], 0
	v_mfma_f32_16x16x32_bf16 v[0:3], v[152:155], v[202:205], 0
	v_mfma_f32_16x16x32_bf16 v[52:55], v[148:151], v[164:167], v[52:55]
	v_mfma_f32_16x16x32_bf16 v[48:51], v[156:159], v[164:167], v[48:51]
	v_mfma_f32_16x16x32_bf16 v[36:39], v[148:151], v[172:175], v[36:39]
	v_mfma_f32_16x16x32_bf16 v[32:35], v[156:159], v[172:175], v[32:35]
	v_mfma_f32_16x16x32_bf16 v[20:23], v[148:151], v[180:183], v[20:23]
	v_mfma_f32_16x16x32_bf16 v[16:19], v[156:159], v[180:183], v[16:19]
	v_mfma_f32_16x16x32_bf16 v[4:7], v[148:151], v[206:209], v[4:7]
	v_mfma_f32_16x16x32_bf16 v[0:3], v[156:159], v[206:209], v[0:3]
	s_barrier
	s_add_i32 s77, 0, 0x18000
	s_add_i32 s78, 0, 0x1c000
	v_add_u32_e32 v128, s77, v221
	v_add_u32_e32 v156, s78, v221
	ds_read_b128 v[96:99], v128
	ds_read_b128 v[108:111], v128 offset:1024
	ds_read_b128 v[120:123], v128 offset:2048
	ds_read_b128 v[128:131], v128 offset:3072
	ds_read_b128 v[144:147], v156
	ds_read_b128 v[148:151], v156 offset:1024
	ds_read_b128 v[152:155], v156 offset:2048
	ds_read_b128 v[156:159], v156 offset:3072
	s_add_u32 s56, s56, 0x40000
	s_addc_u32 s57, s57, 0
	s_mov_b32 m0, s60
	ds_read_b128 v[160:163], v225 offset:32768
	ds_read_b128 v[164:167], v225 offset:33792
	ds_read_b128 v[168:171], v225 offset:34816
	ds_read_b128 v[172:175], v225 offset:35840
	ds_read_b128 v[176:179], v225 offset:36864
	ds_read_b128 v[180:183], v225 offset:37888
	ds_read_b128 v[202:205], v225 offset:38912
	ds_read_b128 v[206:209], v225 offset:39936
	global_load_lds_dwordx4 v184, s[56:57]
	s_mov_b32 m0, s61
	s_nop 0
	global_load_lds_dwordx4 v188, s[56:57]
	s_waitcnt vmcnt(8)
	s_waitcnt lgkmcnt(0)
	s_barrier
	v_mfma_f32_16x16x32_bf16 v[140:143], v[96:99], v[160:163], v[140:143]
	v_mfma_f32_16x16x32_bf16 v[136:139], v[120:123], v[160:163], v[136:139]
	v_mfma_f32_16x16x32_bf16 v[116:119], v[96:99], v[168:171], v[116:119]
	v_mfma_f32_16x16x32_bf16 v[112:115], v[120:123], v[168:171], v[112:115]
	v_mfma_f32_16x16x32_bf16 v[92:95], v[96:99], v[176:179], v[92:95]
	v_mfma_f32_16x16x32_bf16 v[88:91], v[120:123], v[176:179], v[88:91]
	v_mfma_f32_16x16x32_bf16 v[76:79], v[96:99], v[202:205], v[76:79]
	v_mfma_f32_16x16x32_bf16 v[72:75], v[120:123], v[202:205], v[72:75]
	v_mfma_f32_16x16x32_bf16 v[140:143], v[108:111], v[164:167], v[140:143]
	v_mfma_f32_16x16x32_bf16 v[136:139], v[128:131], v[164:167], v[136:139]
	v_mfma_f32_16x16x32_bf16 v[116:119], v[108:111], v[172:175], v[116:119]
	v_mfma_f32_16x16x32_bf16 v[112:115], v[128:131], v[172:175], v[112:115]
	v_mfma_f32_16x16x32_bf16 v[92:95], v[108:111], v[180:183], v[92:95]
	v_mfma_f32_16x16x32_bf16 v[88:91], v[128:131], v[180:183], v[88:91]
	v_mfma_f32_16x16x32_bf16 v[76:79], v[108:111], v[206:209], v[76:79]
	v_mfma_f32_16x16x32_bf16 v[72:75], v[128:131], v[206:209], v[72:75]
	v_mfma_f32_16x16x32_bf16 v[132:135], v[144:147], v[160:163], v[132:135]
	v_mfma_f32_16x16x32_bf16 v[124:127], v[152:155], v[160:163], v[124:127]
	v_mfma_f32_16x16x32_bf16 v[104:107], v[144:147], v[168:171], v[104:107]
	v_mfma_f32_16x16x32_bf16 v[100:103], v[152:155], v[168:171], v[100:103]
	v_mfma_f32_16x16x32_bf16 v[84:87], v[144:147], v[176:179], v[84:87]
	v_mfma_f32_16x16x32_bf16 v[80:83], v[152:155], v[176:179], v[80:83]
	v_mfma_f32_16x16x32_bf16 v[68:71], v[144:147], v[202:205], v[68:71]
	v_mfma_f32_16x16x32_bf16 v[64:67], v[152:155], v[202:205], v[64:67]
	v_mfma_f32_16x16x32_bf16 v[132:135], v[148:151], v[164:167], v[132:135]
	v_mfma_f32_16x16x32_bf16 v[124:127], v[156:159], v[164:167], v[124:127]
	v_mfma_f32_16x16x32_bf16 v[104:107], v[148:151], v[172:175], v[104:107]
	v_mfma_f32_16x16x32_bf16 v[100:103], v[156:159], v[172:175], v[100:103]
	v_mfma_f32_16x16x32_bf16 v[84:87], v[148:151], v[180:183], v[84:87]
	v_mfma_f32_16x16x32_bf16 v[80:83], v[156:159], v[180:183], v[80:83]
	v_mfma_f32_16x16x32_bf16 v[68:71], v[148:151], v[206:209], v[68:71]
	v_mfma_f32_16x16x32_bf16 v[64:67], v[156:159], v[206:209], v[64:67]
	s_barrier
; #define PG8_STAGE(bufoff, gbase, voff) do { _Pragma("unroll") for (int _i = 0; _i < 2; ++_i) \
;         __builtin_amdgcn_global_load_lds((const unsigned*)((const char*)(gbase) + (voff)[_i]), (PG8_LAS unsigned*)(lds + (bufoff) + ldsw + _i * 8192), 16, 0, 0); } while (0)
; #define PG8_LDA(dst, b, h) do { _Pragma("unroll") for (int m = 0; m < 4; ++m) _Pragma("unroll") for (int k = 0; k < 2; ++k) dst[m][k] = *(const PG8_LAS bf16x8*)(lds + PG8_SA(b, h) + aoff + m * 2048 + k * 1024); } while (0)
; #define PG8_MMA(ai, bj, At, Bt) do { __builtin_amdgcn_s_setprio(1); _Pragma("unroll") for (int m = 0; m < 4; ++m) _Pragma("unroll") for (int n = 0; n < 2; ++n) _Pragma("unroll") for (int k = 0; k < 2; ++k) \
;         acc[ai][bj][m][n] = __builtin_amdgcn_mfma_f32_16x16x32_bf16(Bt[n][k], At[m][k], acc[ai][bj][m][n], 0, 0, 0); __builtin_amdgcn_s_setprio(0); } while (0)
; #define PG8_WAIT_V(n) asm volatile("s_waitcnt vmcnt(" #n ")" ::: "memory")
; #define PG8_WAIT_L(n) asm volatile("s_waitcnt lgkmcnt(" #n ")" ::: "memory")
; #define PG8_BAR __builtin_amdgcn_s_barrier()
; #define PG8_SCHED __builtin_amdgcn_sched_barrier(0)
; template <class Epi, class Sched, bool ALIGN_EPI = false, bool SP2 = false>
; __device__ __forceinline__ void gemm_phase(PG8_LAS unsigned char* lds, const Gemm g, const Sched& S, const Epi& E) {
;     ...
;             PG8_LDA(At, 1, 1); PG8_STAGE(PG8_SB(1, 0), b3, voffB); PG8_STAGE(PG8_SB(1, 1), b3 + hstep, voffB); PG8_STAGE(PG8_SA(1, 0), a3, voffA);
;             PG8_WAIT_V(8); PG8_WAIT_L(0); PG8_BAR; PG8_MMA(1, 0, At, B0); PG8_MMA(1, 1, At, B1); PG8_BAR; PG8_SCHED;
	s_add_i32 s56, s77, s58
	s_mov_b32 m0, s56
	ds_read_b128 v[160:163], v225 offset:49152
	ds_read_b128 v[164:167], v225 offset:50176
	ds_read_b128 v[168:171], v225 offset:51200
	ds_read_b128 v[172:175], v225 offset:52224
	ds_read_b128 v[176:179], v225 offset:53248
	ds_read_b128 v[180:183], v225 offset:54272
	ds_read_b128 v[202:205], v225 offset:55296
	ds_read_b128 v[206:209], v225 offset:56320
	global_load_lds_dwordx4 v186, s[98:99]
	s_add_i32 m0, s56, 0x2000
	s_add_u32 s54, s54, 0x40080
	s_addc_u32 s55, s55, 0
	s_add_i32 s56, s78, s58
	global_load_lds_dwordx4 v190, s[98:99]
	s_mov_b32 m0, s56
	s_nop 0
	global_load_lds_dwordx4 v186, s[54:55]
	s_add_i32 m0, s56, 0x2000
	s_nop 0
	global_load_lds_dwordx4 v190, s[54:55]
	s_mov_b32 m0, s66
	s_nop 0
	global_load_lds_dwordx4 v184, s[100:101]
	s_mov_b32 m0, s67
	s_nop 0
	global_load_lds_dwordx4 v188, s[100:101]
	s_waitcnt vmcnt(8)
	s_waitcnt lgkmcnt(0)
	s_barrier
	v_mfma_f32_16x16x32_bf16 v[60:63], v[96:99], v[160:163], v[60:63]
	v_mfma_f32_16x16x32_bf16 v[56:59], v[120:123], v[160:163], v[56:59]
	v_mfma_f32_16x16x32_bf16 v[44:47], v[96:99], v[168:171], v[44:47]
	v_mfma_f32_16x16x32_bf16 v[40:43], v[120:123], v[168:171], v[40:43]
	v_mfma_f32_16x16x32_bf16 v[28:31], v[96:99], v[176:179], v[28:31]
	v_mfma_f32_16x16x32_bf16 v[24:27], v[120:123], v[176:179], v[24:27]
	v_mfma_f32_16x16x32_bf16 v[12:15], v[96:99], v[202:205], v[12:15]
	v_mfma_f32_16x16x32_bf16 v[8:11], v[120:123], v[202:205], v[8:11]
	v_mfma_f32_16x16x32_bf16 v[60:63], v[108:111], v[164:167], v[60:63]
	v_mfma_f32_16x16x32_bf16 v[56:59], v[128:131], v[164:167], v[56:59]
	v_mfma_f32_16x16x32_bf16 v[44:47], v[108:111], v[172:175], v[44:47]
	v_mfma_f32_16x16x32_bf16 v[40:43], v[128:131], v[172:175], v[40:43]
	v_mfma_f32_16x16x32_bf16 v[28:31], v[108:111], v[180:183], v[28:31]
	v_mfma_f32_16x16x32_bf16 v[24:27], v[128:131], v[180:183], v[24:27]
	v_mfma_f32_16x16x32_bf16 v[12:15], v[108:111], v[206:209], v[12:15]
	v_mfma_f32_16x16x32_bf16 v[8:11], v[128:131], v[206:209], v[8:11]
	v_mfma_f32_16x16x32_bf16 v[52:55], v[144:147], v[160:163], v[52:55]
	v_mfma_f32_16x16x32_bf16 v[48:51], v[152:155], v[160:163], v[48:51]
	v_mfma_f32_16x16x32_bf16 v[36:39], v[144:147], v[168:171], v[36:39]
	v_mfma_f32_16x16x32_bf16 v[32:35], v[152:155], v[168:171], v[32:35]
	v_mfma_f32_16x16x32_bf16 v[20:23], v[144:147], v[176:179], v[20:23]
	v_mfma_f32_16x16x32_bf16 v[16:19], v[152:155], v[176:179], v[16:19]
	v_mfma_f32_16x16x32_bf16 v[4:7], v[144:147], v[202:205], v[4:7]
	v_mfma_f32_16x16x32_bf16 v[0:3], v[152:155], v[202:205], v[0:3]
	v_mfma_f32_16x16x32_bf16 v[52:55], v[148:151], v[164:167], v[52:55]
	v_mfma_f32_16x16x32_bf16 v[48:51], v[156:159], v[164:167], v[48:51]
	v_mfma_f32_16x16x32_bf16 v[36:39], v[148:151], v[172:175], v[36:39]
	v_mfma_f32_16x16x32_bf16 v[32:35], v[156:159], v[172:175], v[32:35]
	v_mfma_f32_16x16x32_bf16 v[20:23], v[148:151], v[180:183], v[20:23]
	v_mfma_f32_16x16x32_bf16 v[16:19], v[156:159], v[180:183], v[16:19]
	v_mfma_f32_16x16x32_bf16 v[4:7], v[148:151], v[206:209], v[4:7]
	v_mfma_f32_16x16x32_bf16 v[0:3], v[156:159], v[206:209], v[0:3]
	s_barrier
	s_add_i32 s76, s76, 2
	s_add_u32 s20, s20, 0x100
	s_addc_u32 s21, s21, 0
	s_add_u32 s74, s74, 0x100
	s_addc_u32 s75, s75, 0
	s_cmp_gt_u32 s76, 13

; #define PG8_STAGE(bufoff, gbase, voff) do { _Pragma("unroll") for (int _i = 0; _i < 2; ++_i) \
;         __builtin_amdgcn_global_load_lds((const unsigned*)((const char*)(gbase) + (voff)[_i]), (PG8_LAS unsigned*)(lds + (bufoff) + ldsw + _i * 8192), 16, 0, 0); } while (0)
; #define PG8_LDA(dst, b, h) do { _Pragma("unroll") for (int m = 0; m < 4; ++m) _Pragma("unroll") for (int k = 0; k < 2; ++k) dst[m][k] = *(const PG8_LAS bf16x8*)(lds + PG8_SA(b, h) + aoff + m * 2048 + k * 1024); } while (0)
; #define PG8_WAIT_V(n) asm volatile("s_waitcnt vmcnt(" #n ")" ::: "memory")
; #define PG8_BAR __builtin_amdgcn_s_barrier()
;     __host__ __device__ bool next(int i, Unit& u) const {
;         const long L = (long)i * G + c; if (L >= nwg) return false;
;         int wgid = (int)L; { const int q = nwg / NXCD, r = nwg % NXCD, xcd = wgid % NXCD, off = wgid / NXCD; wgid = (xcd < r ? xcd * (q + 1) : r * (q + 1) + (xcd - r) * q) + off; }
;         const int nig = WGM * nN, gid = wgid / nig, fm = gid * WGM, gsz = (nM - fm) < WGM ? (nM - fm) : WGM;
;         u.pm = fm + ((wgid % nig) % gsz); u.pn = (wgid % nig) / gsz; return true;
;     }
; template <class Epi, class Sched, bool ALIGN_EPI = false, bool SP2 = false>
; __device__ __forceinline__ void gemm_phase(PG8_LAS unsigned char* lds, const Gemm g, const Sched& S, const Epi& E) {
;     ...
;         const bool has_next = S.next(ui + 1, nxt);
;         const char* nA = has_next ? (const char*)g.A + (size_t)nxt.pm * tstep : cA; const char* nB = has_next ? (const char*)g.Bt + (size_t)nxt.pn * tstep : cB;
;         for (int t = 0; t < nt; t += 2) {
;             const bool last = (t == nt - 2);
;             const char* a1 = cA + (size_t)(t + 1) * kstep;
;             const char* a2 = last ? nA : cA + (size_t)(t + 2) * kstep; const char* b2 = last ? nB : cB + (size_t)(t + 2) * kstep;
;             const char* a3 = a2 + kstep; const char* b3 = b2 + kstep;
;             if (last && has_next) S.a_ready(nxt);
;             if constexpr (SP2) {
;             PG8_LDB(B0, 0, 0); PG8_LDB(B1, 0, 1); PG8_SCHED; PG8_LDA(At, 0, 0); PG8_STAGE(PG8_SA(1, 1), a1 + hstep, voffA);
;             PG8_WAIT_V(8); PG8_WAIT_L(0); PG8_BAR; PG8_MMA(0, 0, At, B0); PG8_MMA(0, 1, At, B1); PG8_BAR; PG8_SCHED;
;             PG8_LDA(At, 0, 1); PG8_STAGE(PG8_SB(0, 0), b2, voffB); PG8_STAGE(PG8_SB(0, 1), b2 + hstep, voffB); PG8_STAGE(PG8_SA(0, 0), a2, voffA);
.LBB0_807:
	ds_read_b128 v[154:157], v150
	ds_read_b128 v[158:161], v150 offset:1024
	ds_read_b128 v[162:165], v150 offset:2048
	ds_read_b128 v[166:169], v150 offset:3072
	ds_read_b128 v[170:173], v151
	ds_read_b128 v[174:177], v151 offset:1024
	ds_read_b128 v[178:181], v151 offset:2048
	ds_read_b128 v[182:185], v151 offset:3072
	ds_read_b128 v[186:189], v152
	ds_read_b128 v[190:193], v152 offset:1024
	ds_read_b128 v[198:201], v152 offset:2048
	ds_read_b128 v[202:205], v152 offset:3072
	ds_read_b128 v[206:209], v152 offset:4096
	ds_read_b128 v[210:213], v152 offset:5120
	ds_read_b128 v[214:217], v152 offset:6144
	ds_read_b128 v[218:221], v152 offset:7168
	s_add_i32 s57, s57, 1
	s_mul_i32 s4, s57, s33
	s_mul_hi_u32 s5, s57, s46
	s_add_i32 s5, s5, s4
	s_mul_i32 s4, s57, s46
	s_add_u32 s16, s4, s2
	s_addc_u32 s17, s5, s3
	v_cmp_gt_i64_e32 vcc, s[16:17], v[142:143]
	v_cmp_lt_i64_e64 s[4:5], s[16:17], v[140:141]
	s_cbranch_vccnz .LBB0_809
	s_ashr_i32 s12, s16, 31
	s_lshr_b32 s12, s12, 29
	s_add_i32 s12, s16, s12
	s_ashr_i32 s13, s12, 3
	s_and_b32 s12, s12, -8
	s_sub_i32 s12, s16, s12
	s_cmp_lt_i32 s12, 0
	s_cselect_b32 s14, s53, 0x160
	s_mul_i32 s12, s14, s12
	s_add_i32 s12, s12, s13
	s_mul_hi_i32 s13, s12, 0x2e8ba2e9
	s_lshr_b32 s14, s13, 31
	s_ashr_i32 s13, s13, 5
	s_add_i32 s13, s13, s14
	s_lshl_b32 s14, s13, 3
	s_sub_i32 s15, 0x80, s14
	s_min_i32 s15, s15, 8
	s_mulk_i32 s13, 0xb0
	s_sub_i32 s13, s12, s13
	s_lshr_b32 s12, s13, 3
	s_mul_i32 s15, s12, s15
	s_sub_i32 s13, s13, s15
	s_add_i32 s14, s13, s14
.LBB0_809:
	s_ashr_i32 s15, s14, 31
	s_lshl_b64 s[16:17], s[14:15], 19
	s_add_u32 s16, s36, s16
	s_addc_u32 s17, s37, s17
	s_and_b64 s[18:19], s[4:5], exec
	s_cselect_b32 s15, s17, s21
	s_cselect_b32 s65, s16, s20
	s_ashr_i32 s13, s12, 31
	s_lshl_b64 s[18:19], s[12:13], 19
	s_add_u32 s18, s50, s18
	s_addc_u32 s19, s51, s19
	s_and_b64 s[44:45], s[4:5], exec
	s_cselect_b32 s13, s19, s39
	s_cselect_b32 s66, s18, s38
	s_add_u32 s20, s20, 0x40080
	s_addc_u32 s21, s21, 0
	s_add_u32 s67, s38, 0x100
	s_addc_u32 s68, s39, 0
	s_mov_b32 s69, -2
	s_add_u32 s38, s20, 0xfffc0080
	s_addc_u32 s39, s21, -1
	s_cmp_eq_u32 s69, 12
	s_cselect_b32 s45, s15, s39
	s_cselect_b32 s44, s65, s38
	s_cselect_b32 s39, s13, s68
	s_cselect_b32 s38, s66, s67
	s_add_i32 m0, s35, 0xc000
	global_load_lds_dwordx4 v136, s[20:21]
	s_add_i32 m0, s35, 0xe000
	s_nop 0
	global_load_lds_dwordx4 v138, s[20:21]
	s_waitcnt vmcnt(8)
	s_waitcnt lgkmcnt(0)
	s_barrier
	v_mfma_f32_16x16x32_bf16 v[124:127], v[154:157], v[186:189], 0
	v_mfma_f32_16x16x32_bf16 v[116:119], v[162:165], v[186:189], 0
	v_mfma_f32_16x16x32_bf16 v[108:111], v[154:157], v[198:201], 0
	v_mfma_f32_16x16x32_bf16 v[100:103], v[162:165], v[198:201], 0
	v_mfma_f32_16x16x32_bf16 v[92:95], v[154:157], v[206:209], 0
	v_mfma_f32_16x16x32_bf16 v[84:87], v[162:165], v[206:209], 0
	v_mfma_f32_16x16x32_bf16 v[76:79], v[154:157], v[214:217], 0
	v_mfma_f32_16x16x32_bf16 v[68:71], v[162:165], v[214:217], 0
	v_mfma_f32_16x16x32_bf16 v[124:127], v[158:161], v[190:193], v[124:127]
	v_mfma_f32_16x16x32_bf16 v[116:119], v[166:169], v[190:193], v[116:119]
	v_mfma_f32_16x16x32_bf16 v[108:111], v[158:161], v[202:205], v[108:111]
	v_mfma_f32_16x16x32_bf16 v[100:103], v[166:169], v[202:205], v[100:103]
	v_mfma_f32_16x16x32_bf16 v[92:95], v[158:161], v[210:213], v[92:95]
	v_mfma_f32_16x16x32_bf16 v[84:87], v[166:169], v[210:213], v[84:87]
	v_mfma_f32_16x16x32_bf16 v[76:79], v[158:161], v[218:221], v[76:79]
	v_mfma_f32_16x16x32_bf16 v[68:71], v[166:169], v[218:221], v[68:71]
	v_mfma_f32_16x16x32_bf16 v[120:123], v[170:173], v[186:189], 0
	v_mfma_f32_16x16x32_bf16 v[112:115], v[178:181], v[186:189], 0
	v_mfma_f32_16x16x32_bf16 v[104:107], v[170:173], v[198:201], 0
	v_mfma_f32_16x16x32_bf16 v[96:99], v[178:181], v[198:201], 0
	v_mfma_f32_16x16x32_bf16 v[88:91], v[170:173], v[206:209], 0
	v_mfma_f32_16x16x32_bf16 v[80:83], v[178:181], v[206:209], 0
	v_mfma_f32_16x16x32_bf16 v[72:75], v[170:173], v[214:217], 0
	v_mfma_f32_16x16x32_bf16 v[64:67], v[178:181], v[214:217], 0
	v_mfma_f32_16x16x32_bf16 v[120:123], v[174:177], v[190:193], v[120:123]
	v_mfma_f32_16x16x32_bf16 v[112:115], v[182:185], v[190:193], v[112:115]
	v_mfma_f32_16x16x32_bf16 v[104:107], v[174:177], v[202:205], v[104:107]
	v_mfma_f32_16x16x32_bf16 v[96:99], v[182:185], v[202:205], v[96:99]
	v_mfma_f32_16x16x32_bf16 v[88:91], v[174:177], v[210:213], v[88:91]
	v_mfma_f32_16x16x32_bf16 v[80:83], v[182:185], v[210:213], v[80:83]
	v_mfma_f32_16x16x32_bf16 v[72:75], v[174:177], v[218:221], v[72:75]
	v_mfma_f32_16x16x32_bf16 v[64:67], v[182:185], v[218:221], v[64:67]
	s_barrier
	s_add_i32 s70, s60, s52
	s_add_u32 s98, s38, s8
	s_addc_u32 s99, s39, s9
	s_add_u32 s100, s44, s8
	s_addc_u32 s101, s45, s9
	s_mov_b32 m0, s70
	ds_read_b128 v[186:189], v152 offset:16384
	ds_read_b128 v[190:193], v152 offset:17408
	ds_read_b128 v[198:201], v152 offset:18432
	ds_read_b128 v[202:205], v152 offset:19456
	ds_read_b128 v[206:209], v152 offset:20480
	ds_read_b128 v[210:213], v152 offset:21504
	ds_read_b128 v[214:217], v152 offset:22528
	ds_read_b128 v[218:221], v152 offset:23552
	global_load_lds_dwordx4 v132, s[38:39]
	s_add_i32 m0, s70, 0x2000
	s_add_u32 s70, s38, 0x40000
	s_addc_u32 s71, s39, 0
	s_add_i32 s72, s61, s52
	global_load_lds_dwordx4 v128, s[38:39]
	s_mov_b32 m0, s72
	s_nop 0
	global_load_lds_dwordx4 v132, s[70:71]
	s_add_i32 m0, s72, 0x2000
	s_nop 0
	global_load_lds_dwordx4 v128, s[70:71]
	s_mov_b32 m0, s35
	s_nop 0
	global_load_lds_dwordx4 v134, s[44:45]
	s_mov_b32 m0, s54
	s_nop 0
	global_load_lds_dwordx4 v130, s[44:45]
	s_waitcnt vmcnt(8)
	s_waitcnt lgkmcnt(0)
	s_barrier
; #define PG8_STAGE(bufoff, gbase, voff) do { _Pragma("unroll") for (int _i = 0; _i < 2; ++_i) \
;         __builtin_amdgcn_global_load_lds((const unsigned*)((const char*)(gbase) + (voff)[_i]), (PG8_LAS unsigned*)(lds + (bufoff) + ldsw + _i * 8192), 16, 0, 0); } while (0)
; #define PG8_LDA(dst, b, h) do { _Pragma("unroll") for (int m = 0; m < 4; ++m) _Pragma("unroll") for (int k = 0; k < 2; ++k) dst[m][k] = *(const PG8_LAS bf16x8*)(lds + PG8_SA(b, h) + aoff + m * 2048 + k * 1024); } while (0)
; #define PG8_LDB(dst, b, h) do { _Pragma("unroll") for (int n = 0; n < 2; ++n) _Pragma("unroll") for (int k = 0; k < 2; ++k) dst[n][k] = *(const PG8_LAS bf16x8*)(lds + PG8_SB(b, h) + boff + n * 2048 + k * 1024); } while (0)
; #define PG8_MMA(ai, bj, At, Bt) do { __builtin_amdgcn_s_setprio(1); _Pragma("unroll") for (int m = 0; m < 4; ++m) _Pragma("unroll") for (int n = 0; n < 2; ++n) _Pragma("unroll") for (int k = 0; k < 2; ++k) \
;         acc[ai][bj][m][n] = __builtin_amdgcn_mfma_f32_16x16x32_bf16(Bt[n][k], At[m][k], acc[ai][bj][m][n], 0, 0, 0); __builtin_amdgcn_s_setprio(0); } while (0)
; #define PG8_WAIT_V(n) asm volatile("s_waitcnt vmcnt(" #n ")" ::: "memory")
; #define PG8_WAIT_L(n) asm volatile("s_waitcnt lgkmcnt(" #n ")" ::: "memory")
; #define PG8_BAR __builtin_amdgcn_s_barrier()
; #define PG8_SCHED __builtin_amdgcn_sched_barrier(0)
; template <class Epi, class Sched, bool ALIGN_EPI = false, bool SP2 = false>
; __device__ __forceinline__ void gemm_phase(PG8_LAS unsigned char* lds, const Gemm g, const Sched& S, const Epi& E) {
;     ...
;             PG8_WAIT_V(8); PG8_WAIT_L(0); PG8_BAR; PG8_MMA(1, 0, At, B0); PG8_MMA(1, 1, At, B1); PG8_BAR; PG8_SCHED;
;             PG8_LDB(B0, 1, 0); PG8_LDB(B1, 1, 1); PG8_SCHED; PG8_LDA(At, 1, 0); PG8_STAGE(PG8_SA(0, 1), a2 + hstep, voffA);
;             PG8_WAIT_V(8); PG8_WAIT_L(0); PG8_BAR; PG8_MMA(0, 0, At, B0); PG8_MMA(0, 1, At, B1); PG8_BAR; PG8_SCHED;
	v_mfma_f32_16x16x32_bf16 v[60:63], v[154:157], v[186:189], 0
	v_mfma_f32_16x16x32_bf16 v[52:55], v[162:165], v[186:189], 0
	v_mfma_f32_16x16x32_bf16 v[44:47], v[154:157], v[198:201], 0
	v_mfma_f32_16x16x32_bf16 v[36:39], v[162:165], v[198:201], 0
	v_mfma_f32_16x16x32_bf16 v[28:31], v[154:157], v[206:209], 0
	v_mfma_f32_16x16x32_bf16 v[20:23], v[162:165], v[206:209], 0
	v_mfma_f32_16x16x32_bf16 v[12:15], v[154:157], v[214:217], 0
	v_mfma_f32_16x16x32_bf16 v[4:7], v[162:165], v[214:217], 0
	v_mfma_f32_16x16x32_bf16 v[60:63], v[158:161], v[190:193], v[60:63]
	v_mfma_f32_16x16x32_bf16 v[52:55], v[166:169], v[190:193], v[52:55]
	v_mfma_f32_16x16x32_bf16 v[44:47], v[158:161], v[202:205], v[44:47]
	v_mfma_f32_16x16x32_bf16 v[36:39], v[166:169], v[202:205], v[36:39]
	v_mfma_f32_16x16x32_bf16 v[28:31], v[158:161], v[210:213], v[28:31]
	v_mfma_f32_16x16x32_bf16 v[20:23], v[166:169], v[210:213], v[20:23]
	v_mfma_f32_16x16x32_bf16 v[12:15], v[158:161], v[218:221], v[12:15]
	v_mfma_f32_16x16x32_bf16 v[4:7], v[166:169], v[218:221], v[4:7]
	v_mfma_f32_16x16x32_bf16 v[56:59], v[170:173], v[186:189], 0
	v_mfma_f32_16x16x32_bf16 v[48:51], v[178:181], v[186:189], 0
	v_mfma_f32_16x16x32_bf16 v[40:43], v[170:173], v[198:201], 0
	v_mfma_f32_16x16x32_bf16 v[32:35], v[178:181], v[198:201], 0
	v_mfma_f32_16x16x32_bf16 v[24:27], v[170:173], v[206:209], 0
	v_mfma_f32_16x16x32_bf16 v[16:19], v[178:181], v[206:209], 0
	v_mfma_f32_16x16x32_bf16 v[8:11], v[170:173], v[214:217], 0
	v_mfma_f32_16x16x32_bf16 v[0:3], v[178:181], v[214:217], 0
	v_mfma_f32_16x16x32_bf16 v[56:59], v[174:177], v[190:193], v[56:59]
	v_mfma_f32_16x16x32_bf16 v[48:51], v[182:185], v[190:193], v[48:51]
	v_mfma_f32_16x16x32_bf16 v[40:43], v[174:177], v[202:205], v[40:43]
	v_mfma_f32_16x16x32_bf16 v[32:35], v[182:185], v[202:205], v[32:35]
	v_mfma_f32_16x16x32_bf16 v[24:27], v[174:177], v[210:213], v[24:27]
	v_mfma_f32_16x16x32_bf16 v[16:19], v[182:185], v[210:213], v[16:19]
	v_mfma_f32_16x16x32_bf16 v[8:11], v[174:177], v[218:221], v[8:11]
	v_mfma_f32_16x16x32_bf16 v[0:3], v[182:185], v[218:221], v[0:3]
	s_barrier
	s_add_i32 s70, 0, 0x18000
	v_add_u32_e32 v153, s70, v147
	s_add_i32 s71, 0, 0x1c000
	ds_read_b128 v[154:157], v153
	ds_read_b128 v[158:161], v153 offset:1024
	ds_read_b128 v[162:165], v153 offset:2048
	ds_read_b128 v[166:169], v153 offset:3072
	v_add_u32_e32 v153, s71, v147
	ds_read_b128 v[170:173], v153
	ds_read_b128 v[174:177], v153 offset:1024
	ds_read_b128 v[178:181], v153 offset:2048
	ds_read_b128 v[182:185], v153 offset:3072
	s_add_u32 s44, s44, 0x40000
	s_addc_u32 s45, s45, 0
	s_mov_b32 m0, s55
	ds_read_b128 v[186:189], v152 offset:32768
	ds_read_b128 v[190:193], v152 offset:33792
	ds_read_b128 v[198:201], v152 offset:34816
	ds_read_b128 v[202:205], v152 offset:35840
	ds_read_b128 v[206:209], v152 offset:36864
	ds_read_b128 v[210:213], v152 offset:37888
	ds_read_b128 v[214:217], v152 offset:38912
	ds_read_b128 v[218:221], v152 offset:39936
	global_load_lds_dwordx4 v134, s[44:45]
	s_mov_b32 m0, s56
	s_nop 0
	global_load_lds_dwordx4 v130, s[44:45]
	s_waitcnt vmcnt(8)
	s_waitcnt lgkmcnt(0)
	s_barrier
	v_mfma_f32_16x16x32_bf16 v[124:127], v[154:157], v[186:189], v[124:127]
	v_mfma_f32_16x16x32_bf16 v[116:119], v[162:165], v[186:189], v[116:119]
	v_mfma_f32_16x16x32_bf16 v[108:111], v[154:157], v[198:201], v[108:111]
	v_mfma_f32_16x16x32_bf16 v[100:103], v[162:165], v[198:201], v[100:103]
	v_mfma_f32_16x16x32_bf16 v[92:95], v[154:157], v[206:209], v[92:95]
	v_mfma_f32_16x16x32_bf16 v[84:87], v[162:165], v[206:209], v[84:87]
	v_mfma_f32_16x16x32_bf16 v[76:79], v[154:157], v[214:217], v[76:79]
	v_mfma_f32_16x16x32_bf16 v[68:71], v[162:165], v[214:217], v[68:71]
	v_mfma_f32_16x16x32_bf16 v[124:127], v[158:161], v[190:193], v[124:127]
	v_mfma_f32_16x16x32_bf16 v[116:119], v[166:169], v[190:193], v[116:119]
	v_mfma_f32_16x16x32_bf16 v[108:111], v[158:161], v[202:205], v[108:111]
	v_mfma_f32_16x16x32_bf16 v[100:103], v[166:169], v[202:205], v[100:103]
	v_mfma_f32_16x16x32_bf16 v[92:95], v[158:161], v[210:213], v[92:95]
	v_mfma_f32_16x16x32_bf16 v[84:87], v[166:169], v[210:213], v[84:87]
	v_mfma_f32_16x16x32_bf16 v[76:79], v[158:161], v[218:221], v[76:79]
	v_mfma_f32_16x16x32_bf16 v[68:71], v[166:169], v[218:221], v[68:71]
	v_mfma_f32_16x16x32_bf16 v[120:123], v[170:173], v[186:189], v[120:123]
	v_mfma_f32_16x16x32_bf16 v[112:115], v[178:181], v[186:189], v[112:115]
	v_mfma_f32_16x16x32_bf16 v[104:107], v[170:173], v[198:201], v[104:107]
	v_mfma_f32_16x16x32_bf16 v[96:99], v[178:181], v[198:201], v[96:99]
	v_mfma_f32_16x16x32_bf16 v[88:91], v[170:173], v[206:209], v[88:91]
	v_mfma_f32_16x16x32_bf16 v[80:83], v[178:181], v[206:209], v[80:83]
	v_mfma_f32_16x16x32_bf16 v[72:75], v[170:173], v[214:217], v[72:75]
	v_mfma_f32_16x16x32_bf16 v[64:67], v[178:181], v[214:217], v[64:67]
	v_mfma_f32_16x16x32_bf16 v[120:123], v[174:177], v[190:193], v[120:123]
	v_mfma_f32_16x16x32_bf16 v[112:115], v[182:185], v[190:193], v[112:115]
	v_mfma_f32_16x16x32_bf16 v[104:107], v[174:177], v[202:205], v[104:107]
	v_mfma_f32_16x16x32_bf16 v[96:99], v[182:185], v[202:205], v[96:99]
	v_mfma_f32_16x16x32_bf16 v[88:91], v[174:177], v[210:213], v[88:91]
	v_mfma_f32_16x16x32_bf16 v[80:83], v[182:185], v[210:213], v[80:83]
	v_mfma_f32_16x16x32_bf16 v[72:75], v[174:177], v[218:221], v[72:75]
	v_mfma_f32_16x16x32_bf16 v[64:67], v[182:185], v[218:221], v[64:67]
	s_barrier
; #define PG8_STAGE(bufoff, gbase, voff) do { _Pragma("unroll") for (int _i = 0; _i < 2; ++_i) \
;         __builtin_amdgcn_global_load_lds((const unsigned*)((const char*)(gbase) + (voff)[_i]), (PG8_LAS unsigned*)(lds + (bufoff) + ldsw + _i * 8192), 16, 0, 0); } while (0)
; #define PG8_LDA(dst, b, h) do { _Pragma("unroll") for (int m = 0; m < 4; ++m) _Pragma("unroll") for (int k = 0; k < 2; ++k) dst[m][k] = *(const PG8_LAS bf16x8*)(lds + PG8_SA(b, h) + aoff + m * 2048 + k * 1024); } while (0)
; #define PG8_MMA(ai, bj, At, Bt) do { __builtin_amdgcn_s_setprio(1); _Pragma("unroll") for (int m = 0; m < 4; ++m) _Pragma("unroll") for (int n = 0; n < 2; ++n) _Pragma("unroll") for (int k = 0; k < 2; ++k) \
;         acc[ai][bj][m][n] = __builtin_amdgcn_mfma_f32_16x16x32_bf16(Bt[n][k], At[m][k], acc[ai][bj][m][n], 0, 0, 0); __builtin_amdgcn_s_setprio(0); } while (0)
; #define PG8_WAIT_V(n) asm volatile("s_waitcnt vmcnt(" #n ")" ::: "memory")
; #define PG8_WAIT_L(n) asm volatile("s_waitcnt lgkmcnt(" #n ")" ::: "memory")
; #define PG8_BAR __builtin_amdgcn_s_barrier()
; #define PG8_SCHED __builtin_amdgcn_sched_barrier(0)
; template <class Epi, class Sched, bool ALIGN_EPI = false, bool SP2 = false>
; __device__ __forceinline__ void gemm_phase(PG8_LAS unsigned char* lds, const Gemm g, const Sched& S, const Epi& E) {
;     ...
;             PG8_LDA(At, 1, 1); PG8_STAGE(PG8_SB(1, 0), b3, voffB); PG8_STAGE(PG8_SB(1, 1), b3 + hstep, voffB); PG8_STAGE(PG8_SA(1, 0), a3, voffA);
;             PG8_WAIT_V(8); PG8_WAIT_L(0); PG8_BAR; PG8_MMA(1, 0, At, B0); PG8_MMA(1, 1, At, B1); PG8_BAR; PG8_SCHED;
	s_add_i32 s44, s70, s52
	s_mov_b32 m0, s44
	ds_read_b128 v[186:189], v152 offset:49152
	ds_read_b128 v[190:193], v152 offset:50176
	ds_read_b128 v[198:201], v152 offset:51200
	ds_read_b128 v[202:205], v152 offset:52224
	ds_read_b128 v[206:209], v152 offset:53248
	ds_read_b128 v[210:213], v152 offset:54272
	ds_read_b128 v[214:217], v152 offset:55296
	ds_read_b128 v[218:221], v152 offset:56320
	global_load_lds_dwordx4 v132, s[98:99]
	s_add_i32 m0, s44, 0x2000
	s_add_u32 s38, s38, 0x40080
	s_addc_u32 s39, s39, 0
	s_add_i32 s44, s71, s52
	global_load_lds_dwordx4 v128, s[98:99]
	s_mov_b32 m0, s44
	s_nop 0
	global_load_lds_dwordx4 v132, s[38:39]
	s_add_i32 m0, s44, 0x2000
	s_nop 0
	global_load_lds_dwordx4 v128, s[38:39]
	s_mov_b32 m0, s58
	s_nop 0
	global_load_lds_dwordx4 v134, s[100:101]
	s_mov_b32 m0, s59
	s_nop 0
	global_load_lds_dwordx4 v130, s[100:101]
	s_waitcnt vmcnt(8)
	s_waitcnt lgkmcnt(0)
	s_barrier
	v_mfma_f32_16x16x32_bf16 v[60:63], v[154:157], v[186:189], v[60:63]
	v_mfma_f32_16x16x32_bf16 v[52:55], v[162:165], v[186:189], v[52:55]
	v_mfma_f32_16x16x32_bf16 v[44:47], v[154:157], v[198:201], v[44:47]
	v_mfma_f32_16x16x32_bf16 v[36:39], v[162:165], v[198:201], v[36:39]
	v_mfma_f32_16x16x32_bf16 v[28:31], v[154:157], v[206:209], v[28:31]
	v_mfma_f32_16x16x32_bf16 v[20:23], v[162:165], v[206:209], v[20:23]
	v_mfma_f32_16x16x32_bf16 v[12:15], v[154:157], v[214:217], v[12:15]
	v_mfma_f32_16x16x32_bf16 v[4:7], v[162:165], v[214:217], v[4:7]
	v_mfma_f32_16x16x32_bf16 v[60:63], v[158:161], v[190:193], v[60:63]
	v_mfma_f32_16x16x32_bf16 v[52:55], v[166:169], v[190:193], v[52:55]
	v_mfma_f32_16x16x32_bf16 v[44:47], v[158:161], v[202:205], v[44:47]
	v_mfma_f32_16x16x32_bf16 v[36:39], v[166:169], v[202:205], v[36:39]
	v_mfma_f32_16x16x32_bf16 v[28:31], v[158:161], v[210:213], v[28:31]
	v_mfma_f32_16x16x32_bf16 v[20:23], v[166:169], v[210:213], v[20:23]
	v_mfma_f32_16x16x32_bf16 v[12:15], v[158:161], v[218:221], v[12:15]
	v_mfma_f32_16x16x32_bf16 v[4:7], v[166:169], v[218:221], v[4:7]
	v_mfma_f32_16x16x32_bf16 v[56:59], v[170:173], v[186:189], v[56:59]
	v_mfma_f32_16x16x32_bf16 v[48:51], v[178:181], v[186:189], v[48:51]
	v_mfma_f32_16x16x32_bf16 v[40:43], v[170:173], v[198:201], v[40:43]
	v_mfma_f32_16x16x32_bf16 v[32:35], v[178:181], v[198:201], v[32:35]
	v_mfma_f32_16x16x32_bf16 v[24:27], v[170:173], v[206:209], v[24:27]
	v_mfma_f32_16x16x32_bf16 v[16:19], v[178:181], v[206:209], v[16:19]
	v_mfma_f32_16x16x32_bf16 v[8:11], v[170:173], v[214:217], v[8:11]
	v_mfma_f32_16x16x32_bf16 v[0:3], v[178:181], v[214:217], v[0:3]
	v_mfma_f32_16x16x32_bf16 v[56:59], v[174:177], v[190:193], v[56:59]
	v_mfma_f32_16x16x32_bf16 v[48:51], v[182:185], v[190:193], v[48:51]
	v_mfma_f32_16x16x32_bf16 v[40:43], v[174:177], v[202:205], v[40:43]
	v_mfma_f32_16x16x32_bf16 v[32:35], v[182:185], v[202:205], v[32:35]
	v_mfma_f32_16x16x32_bf16 v[24:27], v[174:177], v[210:213], v[24:27]
	v_mfma_f32_16x16x32_bf16 v[16:19], v[182:185], v[210:213], v[16:19]
	v_mfma_f32_16x16x32_bf16 v[8:11], v[174:177], v[218:221], v[8:11]
	v_mfma_f32_16x16x32_bf16 v[0:3], v[182:185], v[218:221], v[0:3]
	s_barrier
	s_add_i32 s69, s69, 2
	s_add_u32 s20, s20, 0x100
	s_addc_u32 s21, s21, 0
	s_add_u32 s67, s67, 0x100
	s_addc_u32 s68, s68, 0
	s_cmp_gt_u32 s69, 13

; #define PG8_STAGE(bufoff, gbase, voff) do { _Pragma("unroll") for (int _i = 0; _i < 2; ++_i) \
;         __builtin_amdgcn_global_load_lds((const unsigned*)((const char*)(gbase) + (voff)[_i]), (PG8_LAS unsigned*)(lds + (bufoff) + ldsw + _i * 8192), 16, 0, 0); } while (0)
; #define PG8_LDA(dst, b, h) do { _Pragma("unroll") for (int m = 0; m < 4; ++m) _Pragma("unroll") for (int k = 0; k < 2; ++k) dst[m][k] = *(const PG8_LAS bf16x8*)(lds + PG8_SA(b, h) + aoff + m * 2048 + k * 1024); } while (0)
; #define PG8_LDB(dst, b, h) do { _Pragma("unroll") for (int n = 0; n < 2; ++n) _Pragma("unroll") for (int k = 0; k < 2; ++k) dst[n][k] = *(const PG8_LAS bf16x8*)(lds + PG8_SB(b, h) + boff + n * 2048 + k * 1024); } while (0)
; #define PG8_MMA(ai, bj, At, Bt) do { __builtin_amdgcn_s_setprio(1); _Pragma("unroll") for (int m = 0; m < 4; ++m) _Pragma("unroll") for (int n = 0; n < 2; ++n) _Pragma("unroll") for (int k = 0; k < 2; ++k) \
;         acc[ai][bj][m][n] = __builtin_amdgcn_mfma_f32_16x16x32_bf16(Bt[n][k], At[m][k], acc[ai][bj][m][n], 0, 0, 0); __builtin_amdgcn_s_setprio(0); } while (0)
; #define PG8_WAIT_V(n) asm volatile("s_waitcnt vmcnt(" #n ")" ::: "memory")
; #define PG8_BAR __builtin_amdgcn_s_barrier()
; template <class Epi, class Sched, bool ALIGN_EPI = false, bool SP2 = false>
; __device__ __forceinline__ void gemm_phase(PG8_LAS unsigned char* lds, const Gemm g, const Sched& S, const Epi& E) {
;     ...
;         for (int t = 0; t < nt; t += 2) {
;             const bool last = (t == nt - 2);
;             const char* a1 = cA + (size_t)(t + 1) * kstep;
;             const char* a2 = last ? nA : cA + (size_t)(t + 2) * kstep; const char* b2 = last ? nB : cB + (size_t)(t + 2) * kstep;
;             const char* a3 = a2 + kstep; const char* b3 = b2 + kstep;
;             if (last && has_next) S.a_ready(nxt);
;             if constexpr (SP2) {
;             PG8_LDB(B0, 0, 0); PG8_LDB(B1, 0, 1); PG8_SCHED; PG8_LDA(At, 0, 0); PG8_STAGE(PG8_SA(1, 1), a1 + hstep, voffA);
;             PG8_WAIT_V(8); PG8_WAIT_L(0); PG8_BAR; PG8_MMA(0, 0, At, B0); PG8_MMA(0, 1, At, B1); PG8_BAR; PG8_SCHED;
;             PG8_LDA(At, 0, 1); PG8_STAGE(PG8_SB(0, 0), b2, voffB); PG8_STAGE(PG8_SB(0, 1), b2 + hstep, voffB); PG8_STAGE(PG8_SA(0, 0), a2, voffA);
;             PG8_WAIT_V(8); PG8_WAIT_L(0); PG8_BAR; PG8_MMA(1, 0, At, B0); PG8_MMA(1, 1, At, B1); PG8_BAR; PG8_SCHED;
.LBB0_894:
	s_add_u32 s20, s20, 0xb0080
	s_addc_u32 s21, s21, 0
	s_add_u32 s70, s34, 0x100
	s_addc_u32 s71, s35, 0
	s_mov_b32 s72, -2
	s_waitcnt lgkmcnt(0)
	ds_read_b128 v[96:99], v223
	ds_read_b128 v[108:111], v223 offset:1024
	ds_read_b128 v[120:123], v223 offset:2048
	ds_read_b128 v[128:131], v223 offset:3072
	ds_read_b128 v[144:147], v224
	ds_read_b128 v[148:151], v224 offset:1024
	ds_read_b128 v[152:155], v224 offset:2048
	ds_read_b128 v[156:159], v224 offset:3072
	ds_read_b128 v[160:163], v225
	ds_read_b128 v[164:167], v225 offset:1024
	ds_read_b128 v[168:171], v225 offset:2048
	ds_read_b128 v[172:175], v225 offset:3072
	ds_read_b128 v[176:179], v225 offset:4096
	ds_read_b128 v[180:183], v225 offset:5120
	ds_read_b128 v[202:205], v225 offset:6144
	ds_read_b128 v[206:209], v225 offset:7168
	s_add_u32 s34, s20, 0xfff50080
	s_addc_u32 s35, s21, -1
	s_cmp_eq_u32 s72, 40
	s_cselect_b32 s49, s1, s35
	s_cselect_b32 s48, s0, s34
	s_cselect_b32 s35, s47, s71
	s_cselect_b32 s34, s46, s70
	s_add_i32 m0, s51, 0xc000
	global_load_lds_dwordx4 v192, s[20:21]
	s_add_i32 m0, s51, 0xe000
	s_nop 0
	global_load_lds_dwordx4 v194, s[20:21]
	s_waitcnt vmcnt(8)
	s_waitcnt lgkmcnt(0)
	s_barrier
	v_mfma_f32_16x16x32_bf16 v[140:143], v[96:99], v[160:163], 0
	v_mfma_f32_16x16x32_bf16 v[136:139], v[120:123], v[160:163], 0
	v_mfma_f32_16x16x32_bf16 v[116:119], v[96:99], v[168:171], 0
	v_mfma_f32_16x16x32_bf16 v[112:115], v[120:123], v[168:171], 0
	v_mfma_f32_16x16x32_bf16 v[92:95], v[96:99], v[176:179], 0
	v_mfma_f32_16x16x32_bf16 v[88:91], v[120:123], v[176:179], 0
	v_mfma_f32_16x16x32_bf16 v[76:79], v[96:99], v[202:205], 0
	v_mfma_f32_16x16x32_bf16 v[72:75], v[120:123], v[202:205], 0
	v_mfma_f32_16x16x32_bf16 v[140:143], v[108:111], v[164:167], v[140:143]
	v_mfma_f32_16x16x32_bf16 v[136:139], v[128:131], v[164:167], v[136:139]
	v_mfma_f32_16x16x32_bf16 v[116:119], v[108:111], v[172:175], v[116:119]
	v_mfma_f32_16x16x32_bf16 v[112:115], v[128:131], v[172:175], v[112:115]
	v_mfma_f32_16x16x32_bf16 v[92:95], v[108:111], v[180:183], v[92:95]
	v_mfma_f32_16x16x32_bf16 v[88:91], v[128:131], v[180:183], v[88:91]
	v_mfma_f32_16x16x32_bf16 v[76:79], v[108:111], v[206:209], v[76:79]
	v_mfma_f32_16x16x32_bf16 v[72:75], v[128:131], v[206:209], v[72:75]
	v_mfma_f32_16x16x32_bf16 v[132:135], v[144:147], v[160:163], 0
	v_mfma_f32_16x16x32_bf16 v[124:127], v[152:155], v[160:163], 0
	v_mfma_f32_16x16x32_bf16 v[104:107], v[144:147], v[168:171], 0
	v_mfma_f32_16x16x32_bf16 v[100:103], v[152:155], v[168:171], 0
	v_mfma_f32_16x16x32_bf16 v[84:87], v[144:147], v[176:179], 0
	v_mfma_f32_16x16x32_bf16 v[80:83], v[152:155], v[176:179], 0
	v_mfma_f32_16x16x32_bf16 v[68:71], v[144:147], v[202:205], 0
	v_mfma_f32_16x16x32_bf16 v[64:67], v[152:155], v[202:205], 0
	v_mfma_f32_16x16x32_bf16 v[132:135], v[148:151], v[164:167], v[132:135]
	v_mfma_f32_16x16x32_bf16 v[124:127], v[156:159], v[164:167], v[124:127]
	v_mfma_f32_16x16x32_bf16 v[104:107], v[148:151], v[172:175], v[104:107]
	v_mfma_f32_16x16x32_bf16 v[100:103], v[156:159], v[172:175], v[100:103]
	v_mfma_f32_16x16x32_bf16 v[84:87], v[148:151], v[180:183], v[84:87]
	v_mfma_f32_16x16x32_bf16 v[80:83], v[156:159], v[180:183], v[80:83]
	v_mfma_f32_16x16x32_bf16 v[68:71], v[148:151], v[206:209], v[68:71]
	v_mfma_f32_16x16x32_bf16 v[64:67], v[156:159], v[206:209], v[64:67]
	s_barrier
	s_add_i32 s73, s64, s50
	s_add_u32 s98, s34, s12
	s_addc_u32 s99, s35, s13
	s_add_u32 s100, s48, s12
	s_addc_u32 s101, s49, s13
	s_mov_b32 m0, s73
	ds_read_b128 v[160:163], v225 offset:16384
	ds_read_b128 v[164:167], v225 offset:17408
	ds_read_b128 v[168:171], v225 offset:18432
	ds_read_b128 v[172:175], v225 offset:19456
	ds_read_b128 v[176:179], v225 offset:20480
	ds_read_b128 v[180:183], v225 offset:21504
	ds_read_b128 v[202:205], v225 offset:22528
	ds_read_b128 v[206:209], v225 offset:23552
	global_load_lds_dwordx4 v186, s[34:35]
	s_add_i32 m0, s73, 0x2000
	s_add_u32 s74, s34, 0xb0000
	s_addc_u32 s75, s35, 0
	s_add_i32 s73, s65, s50
	global_load_lds_dwordx4 v190, s[34:35]
	s_mov_b32 m0, s73
	s_nop 0
	global_load_lds_dwordx4 v186, s[74:75]
	s_add_i32 m0, s73, 0x2000
	s_nop 0
	global_load_lds_dwordx4 v190, s[74:75]
	s_mov_b32 m0, s51
	s_nop 0
	global_load_lds_dwordx4 v184, s[48:49]
	s_mov_b32 m0, s52
	s_nop 0
	global_load_lds_dwordx4 v188, s[48:49]
	s_waitcnt vmcnt(8)
	s_waitcnt lgkmcnt(0)
	s_barrier
	v_mfma_f32_16x16x32_bf16 v[60:63], v[96:99], v[160:163], 0
	v_mfma_f32_16x16x32_bf16 v[56:59], v[120:123], v[160:163], 0
	v_mfma_f32_16x16x32_bf16 v[44:47], v[96:99], v[168:171], 0
	v_mfma_f32_16x16x32_bf16 v[40:43], v[120:123], v[168:171], 0
	v_mfma_f32_16x16x32_bf16 v[28:31], v[96:99], v[176:179], 0
	v_mfma_f32_16x16x32_bf16 v[24:27], v[120:123], v[176:179], 0
	v_mfma_f32_16x16x32_bf16 v[12:15], v[96:99], v[202:205], 0
	v_mfma_f32_16x16x32_bf16 v[8:11], v[120:123], v[202:205], 0
	v_mfma_f32_16x16x32_bf16 v[60:63], v[108:111], v[164:167], v[60:63]
	v_mfma_f32_16x16x32_bf16 v[56:59], v[128:131], v[164:167], v[56:59]
	v_mfma_f32_16x16x32_bf16 v[44:47], v[108:111], v[172:175], v[44:47]
	v_mfma_f32_16x16x32_bf16 v[40:43], v[128:131], v[172:175], v[40:43]
	v_mfma_f32_16x16x32_bf16 v[28:31], v[108:111], v[180:183], v[28:31]
	v_mfma_f32_16x16x32_bf16 v[24:27], v[128:131], v[180:183], v[24:27]
	v_mfma_f32_16x16x32_bf16 v[12:15], v[108:111], v[206:209], v[12:15]
	v_mfma_f32_16x16x32_bf16 v[8:11], v[128:131], v[206:209], v[8:11]
	v_mfma_f32_16x16x32_bf16 v[52:55], v[144:147], v[160:163], 0
	v_mfma_f32_16x16x32_bf16 v[48:51], v[152:155], v[160:163], 0
	v_mfma_f32_16x16x32_bf16 v[36:39], v[144:147], v[168:171], 0
	v_mfma_f32_16x16x32_bf16 v[32:35], v[152:155], v[168:171], 0
	v_mfma_f32_16x16x32_bf16 v[20:23], v[144:147], v[176:179], 0
	v_mfma_f32_16x16x32_bf16 v[16:19], v[152:155], v[176:179], 0
	v_mfma_f32_16x16x32_bf16 v[4:7], v[144:147], v[202:205], 0
	v_mfma_f32_16x16x32_bf16 v[0:3], v[152:155], v[202:205], 0
	v_mfma_f32_16x16x32_bf16 v[52:55], v[148:151], v[164:167], v[52:55]
	v_mfma_f32_16x16x32_bf16 v[48:51], v[156:159], v[164:167], v[48:51]
	v_mfma_f32_16x16x32_bf16 v[36:39], v[148:151], v[172:175], v[36:39]
	v_mfma_f32_16x16x32_bf16 v[32:35], v[156:159], v[172:175], v[32:35]
	v_mfma_f32_16x16x32_bf16 v[20:23], v[148:151], v[180:183], v[20:23]
	v_mfma_f32_16x16x32_bf16 v[16:19], v[156:159], v[180:183], v[16:19]
	v_mfma_f32_16x16x32_bf16 v[4:7], v[148:151], v[206:209], v[4:7]
	v_mfma_f32_16x16x32_bf16 v[0:3], v[156:159], v[206:209], v[0:3]
	s_barrier
; #define PG8_STAGE(bufoff, gbase, voff) do { _Pragma("unroll") for (int _i = 0; _i < 2; ++_i) \
;         __builtin_amdgcn_global_load_lds((const unsigned*)((const char*)(gbase) + (voff)[_i]), (PG8_LAS unsigned*)(lds + (bufoff) + ldsw + _i * 8192), 16, 0, 0); } while (0)
; #define PG8_LDA(dst, b, h) do { _Pragma("unroll") for (int m = 0; m < 4; ++m) _Pragma("unroll") for (int k = 0; k < 2; ++k) dst[m][k] = *(const PG8_LAS bf16x8*)(lds + PG8_SA(b, h) + aoff + m * 2048 + k * 1024); } while (0)
; #define PG8_LDB(dst, b, h) do { _Pragma("unroll") for (int n = 0; n < 2; ++n) _Pragma("unroll") for (int k = 0; k < 2; ++k) dst[n][k] = *(const PG8_LAS bf16x8*)(lds + PG8_SB(b, h) + boff + n * 2048 + k * 1024); } while (0)
; #define PG8_MMA(ai, bj, At, Bt) do { __builtin_amdgcn_s_setprio(1); _Pragma("unroll") for (int m = 0; m < 4; ++m) _Pragma("unroll") for (int n = 0; n < 2; ++n) _Pragma("unroll") for (int k = 0; k < 2; ++k) \
;         acc[ai][bj][m][n] = __builtin_amdgcn_mfma_f32_16x16x32_bf16(Bt[n][k], At[m][k], acc[ai][bj][m][n], 0, 0, 0); __builtin_amdgcn_s_setprio(0); } while (0)
; #define PG8_WAIT_V(n) asm volatile("s_waitcnt vmcnt(" #n ")" ::: "memory")
; #define PG8_WAIT_L(n) asm volatile("s_waitcnt lgkmcnt(" #n ")" ::: "memory")
; #define PG8_BAR __builtin_amdgcn_s_barrier()
; #define PG8_SCHED __builtin_amdgcn_sched_barrier(0)
; template <class Epi, class Sched, bool ALIGN_EPI = false, bool SP2 = false>
; __device__ __forceinline__ void gemm_phase(PG8_LAS unsigned char* lds, const Gemm g, const Sched& S, const Epi& E) {
;     ...
;             PG8_LDB(B0, 1, 0); PG8_LDB(B1, 1, 1); PG8_SCHED; PG8_LDA(At, 1, 0); PG8_STAGE(PG8_SA(0, 1), a2 + hstep, voffA);
;             PG8_WAIT_V(8); PG8_WAIT_L(0); PG8_BAR; PG8_MMA(0, 0, At, B0); PG8_MMA(0, 1, At, B1); PG8_BAR; PG8_SCHED;
;             PG8_LDA(At, 1, 1); PG8_STAGE(PG8_SB(1, 0), b3, voffB); PG8_STAGE(PG8_SB(1, 1), b3 + hstep, voffB); PG8_STAGE(PG8_SA(1, 0), a3, voffA);
;             PG8_WAIT_V(8); PG8_WAIT_L(0); PG8_BAR; PG8_MMA(1, 0, At, B0); PG8_MMA(1, 1, At, B1); PG8_BAR; PG8_SCHED;
	s_add_i32 s73, 0, 0x18000
	s_add_i32 s74, 0, 0x1c000
	v_add_u32_e32 v128, s73, v221
	v_add_u32_e32 v156, s74, v221
	ds_read_b128 v[96:99], v128
	ds_read_b128 v[108:111], v128 offset:1024
	ds_read_b128 v[120:123], v128 offset:2048
	ds_read_b128 v[128:131], v128 offset:3072
	ds_read_b128 v[144:147], v156
	ds_read_b128 v[148:151], v156 offset:1024
	ds_read_b128 v[152:155], v156 offset:2048
	ds_read_b128 v[156:159], v156 offset:3072
	s_add_u32 s48, s48, 0xb0000
	s_addc_u32 s49, s49, 0
	s_mov_b32 m0, s53
	ds_read_b128 v[160:163], v225 offset:32768
	ds_read_b128 v[164:167], v225 offset:33792
	ds_read_b128 v[168:171], v225 offset:34816
	ds_read_b128 v[172:175], v225 offset:35840
	ds_read_b128 v[176:179], v225 offset:36864
	ds_read_b128 v[180:183], v225 offset:37888
	ds_read_b128 v[202:205], v225 offset:38912
	ds_read_b128 v[206:209], v225 offset:39936
	global_load_lds_dwordx4 v184, s[48:49]
	s_mov_b32 m0, s54
	s_nop 0
	global_load_lds_dwordx4 v188, s[48:49]
	s_waitcnt vmcnt(8)
	s_waitcnt lgkmcnt(0)
	s_barrier
	v_mfma_f32_16x16x32_bf16 v[140:143], v[96:99], v[160:163], v[140:143]
	v_mfma_f32_16x16x32_bf16 v[136:139], v[120:123], v[160:163], v[136:139]
	v_mfma_f32_16x16x32_bf16 v[116:119], v[96:99], v[168:171], v[116:119]
	v_mfma_f32_16x16x32_bf16 v[112:115], v[120:123], v[168:171], v[112:115]
	v_mfma_f32_16x16x32_bf16 v[92:95], v[96:99], v[176:179], v[92:95]
	v_mfma_f32_16x16x32_bf16 v[88:91], v[120:123], v[176:179], v[88:91]
	v_mfma_f32_16x16x32_bf16 v[76:79], v[96:99], v[202:205], v[76:79]
	v_mfma_f32_16x16x32_bf16 v[72:75], v[120:123], v[202:205], v[72:75]
	v_mfma_f32_16x16x32_bf16 v[140:143], v[108:111], v[164:167], v[140:143]
	v_mfma_f32_16x16x32_bf16 v[136:139], v[128:131], v[164:167], v[136:139]
	v_mfma_f32_16x16x32_bf16 v[116:119], v[108:111], v[172:175], v[116:119]
	v_mfma_f32_16x16x32_bf16 v[112:115], v[128:131], v[172:175], v[112:115]
	v_mfma_f32_16x16x32_bf16 v[92:95], v[108:111], v[180:183], v[92:95]
	v_mfma_f32_16x16x32_bf16 v[88:91], v[128:131], v[180:183], v[88:91]
	v_mfma_f32_16x16x32_bf16 v[76:79], v[108:111], v[206:209], v[76:79]
	v_mfma_f32_16x16x32_bf16 v[72:75], v[128:131], v[206:209], v[72:75]
	v_mfma_f32_16x16x32_bf16 v[132:135], v[144:147], v[160:163], v[132:135]
	v_mfma_f32_16x16x32_bf16 v[124:127], v[152:155], v[160:163], v[124:127]
	v_mfma_f32_16x16x32_bf16 v[104:107], v[144:147], v[168:171], v[104:107]
	v_mfma_f32_16x16x32_bf16 v[100:103], v[152:155], v[168:171], v[100:103]
	v_mfma_f32_16x16x32_bf16 v[84:87], v[144:147], v[176:179], v[84:87]
	v_mfma_f32_16x16x32_bf16 v[80:83], v[152:155], v[176:179], v[80:83]
	v_mfma_f32_16x16x32_bf16 v[68:71], v[144:147], v[202:205], v[68:71]
	v_mfma_f32_16x16x32_bf16 v[64:67], v[152:155], v[202:205], v[64:67]
	v_mfma_f32_16x16x32_bf16 v[132:135], v[148:151], v[164:167], v[132:135]
	v_mfma_f32_16x16x32_bf16 v[124:127], v[156:159], v[164:167], v[124:127]
	v_mfma_f32_16x16x32_bf16 v[104:107], v[148:151], v[172:175], v[104:107]
	v_mfma_f32_16x16x32_bf16 v[100:103], v[156:159], v[172:175], v[100:103]
	v_mfma_f32_16x16x32_bf16 v[84:87], v[148:151], v[180:183], v[84:87]
	v_mfma_f32_16x16x32_bf16 v[80:83], v[156:159], v[180:183], v[80:83]
	v_mfma_f32_16x16x32_bf16 v[68:71], v[148:151], v[206:209], v[68:71]
	v_mfma_f32_16x16x32_bf16 v[64:67], v[156:159], v[206:209], v[64:67]
	s_barrier
	s_add_i32 s48, s73, s50
	s_mov_b32 m0, s48
	ds_read_b128 v[160:163], v225 offset:49152
	ds_read_b128 v[164:167], v225 offset:50176
	ds_read_b128 v[168:171], v225 offset:51200
	ds_read_b128 v[172:175], v225 offset:52224
	ds_read_b128 v[176:179], v225 offset:53248
	ds_read_b128 v[180:183], v225 offset:54272
	ds_read_b128 v[202:205], v225 offset:55296
	ds_read_b128 v[206:209], v225 offset:56320
	global_load_lds_dwordx4 v186, s[98:99]
	s_add_i32 m0, s48, 0x2000
	s_add_u32 s34, s34, 0xb0080
	s_addc_u32 s35, s35, 0
	s_add_i32 s48, s74, s50
	global_load_lds_dwordx4 v190, s[98:99]
	s_mov_b32 m0, s48
	s_nop 0
	global_load_lds_dwordx4 v186, s[34:35]
	s_add_i32 m0, s48, 0x2000
	s_nop 0
	global_load_lds_dwordx4 v190, s[34:35]
	s_mov_b32 m0, s59
	s_nop 0
	global_load_lds_dwordx4 v184, s[100:101]
	s_mov_b32 m0, s60
	s_nop 0
	global_load_lds_dwordx4 v188, s[100:101]
	s_waitcnt vmcnt(8)
	s_waitcnt lgkmcnt(0)
	s_barrier
	v_mfma_f32_16x16x32_bf16 v[60:63], v[96:99], v[160:163], v[60:63]
	v_mfma_f32_16x16x32_bf16 v[56:59], v[120:123], v[160:163], v[56:59]
	v_mfma_f32_16x16x32_bf16 v[44:47], v[96:99], v[168:171], v[44:47]
	v_mfma_f32_16x16x32_bf16 v[40:43], v[120:123], v[168:171], v[40:43]
	v_mfma_f32_16x16x32_bf16 v[28:31], v[96:99], v[176:179], v[28:31]
	v_mfma_f32_16x16x32_bf16 v[24:27], v[120:123], v[176:179], v[24:27]
	v_mfma_f32_16x16x32_bf16 v[12:15], v[96:99], v[202:205], v[12:15]
	v_mfma_f32_16x16x32_bf16 v[8:11], v[120:123], v[202:205], v[8:11]
	v_mfma_f32_16x16x32_bf16 v[60:63], v[108:111], v[164:167], v[60:63]
	v_mfma_f32_16x16x32_bf16 v[56:59], v[128:131], v[164:167], v[56:59]
	v_mfma_f32_16x16x32_bf16 v[44:47], v[108:111], v[172:175], v[44:47]
	v_mfma_f32_16x16x32_bf16 v[40:43], v[128:131], v[172:175], v[40:43]
	v_mfma_f32_16x16x32_bf16 v[28:31], v[108:111], v[180:183], v[28:31]
	v_mfma_f32_16x16x32_bf16 v[24:27], v[128:131], v[180:183], v[24:27]
	v_mfma_f32_16x16x32_bf16 v[12:15], v[108:111], v[206:209], v[12:15]
	v_mfma_f32_16x16x32_bf16 v[8:11], v[128:131], v[206:209], v[8:11]
	v_mfma_f32_16x16x32_bf16 v[52:55], v[144:147], v[160:163], v[52:55]
	v_mfma_f32_16x16x32_bf16 v[48:51], v[152:155], v[160:163], v[48:51]
	v_mfma_f32_16x16x32_bf16 v[36:39], v[144:147], v[168:171], v[36:39]
	v_mfma_f32_16x16x32_bf16 v[32:35], v[152:155], v[168:171], v[32:35]
	v_mfma_f32_16x16x32_bf16 v[20:23], v[144:147], v[176:179], v[20:23]
	v_mfma_f32_16x16x32_bf16 v[16:19], v[152:155], v[176:179], v[16:19]
	v_mfma_f32_16x16x32_bf16 v[4:7], v[144:147], v[202:205], v[4:7]
	v_mfma_f32_16x16x32_bf16 v[0:3], v[152:155], v[202:205], v[0:3]
	v_mfma_f32_16x16x32_bf16 v[52:55], v[148:151], v[164:167], v[52:55]
	v_mfma_f32_16x16x32_bf16 v[48:51], v[156:159], v[164:167], v[48:51]
	v_mfma_f32_16x16x32_bf16 v[36:39], v[148:151], v[172:175], v[36:39]
	v_mfma_f32_16x16x32_bf16 v[32:35], v[156:159], v[172:175], v[32:35]
	v_mfma_f32_16x16x32_bf16 v[20:23], v[148:151], v[180:183], v[20:23]
	v_mfma_f32_16x16x32_bf16 v[16:19], v[156:159], v[180:183], v[16:19]
	v_mfma_f32_16x16x32_bf16 v[4:7], v[148:151], v[206:209], v[4:7]
	v_mfma_f32_16x16x32_bf16 v[0:3], v[156:159], v[206:209], v[0:3]
	s_barrier
	s_add_i32 s72, s72, 2
	s_add_u32 s20, s20, 0x100
	s_addc_u32 s21, s21, 0
	s_add_u32 s70, s70, 0x100
	s_addc_u32 s71, s71, 0
	s_cmp_gt_u32 s72, 41

; #define PG8_STAGE(bufoff, gbase, voff) do { _Pragma("unroll") for (int _i = 0; _i < 2; ++_i) \
;         __builtin_amdgcn_global_load_lds((const unsigned*)((const char*)(gbase) + (voff)[_i]), (PG8_LAS unsigned*)(lds + (bufoff) + ldsw + _i * 8192), 16, 0, 0); } while (0)
; #define PG8_LDA(dst, b, h) do { _Pragma("unroll") for (int m = 0; m < 4; ++m) _Pragma("unroll") for (int k = 0; k < 2; ++k) dst[m][k] = *(const PG8_LAS bf16x8*)(lds + PG8_SA(b, h) + aoff + m * 2048 + k * 1024); } while (0)
; #define PG8_LDB(dst, b, h) do { _Pragma("unroll") for (int n = 0; n < 2; ++n) _Pragma("unroll") for (int k = 0; k < 2; ++k) dst[n][k] = *(const PG8_LAS bf16x8*)(lds + PG8_SB(b, h) + boff + n * 2048 + k * 1024); } while (0)
; #define PG8_MMA(ai, bj, At, Bt) do { __builtin_amdgcn_s_setprio(1); _Pragma("unroll") for (int m = 0; m < 4; ++m) _Pragma("unroll") for (int n = 0; n < 2; ++n) _Pragma("unroll") for (int k = 0; k < 2; ++k) \
;         acc[ai][bj][m][n] = __builtin_amdgcn_mfma_f32_16x16x32_bf16(Bt[n][k], At[m][k], acc[ai][bj][m][n], 0, 0, 0); __builtin_amdgcn_s_setprio(0); } while (0)
; #define PG8_WAIT_V(n) asm volatile("s_waitcnt vmcnt(" #n ")" ::: "memory")
; template <class Epi, class Sched, bool ALIGN_EPI = false, bool SP2 = false>
; __device__ __forceinline__ void gemm_phase(PG8_LAS unsigned char* lds, const Gemm g, const Sched& S, const Epi& E) {
;     ...
;         const char* nA = has_next ? (const char*)g.A + (size_t)nxt.pm * tstep : cA; const char* nB = has_next ? (const char*)g.Bt + (size_t)nxt.pn * tstep : cB;
;         for (int t = 0; t < nt; t += 2) {
;             const bool last = (t == nt - 2);
;             const char* a1 = cA + (size_t)(t + 1) * kstep;
;             const char* a2 = last ? nA : cA + (size_t)(t + 2) * kstep; const char* b2 = last ? nB : cB + (size_t)(t + 2) * kstep;
;             const char* a3 = a2 + kstep; const char* b3 = b2 + kstep;
;             if (last && has_next) S.a_ready(nxt);
;             if constexpr (SP2) {
;             PG8_LDB(B0, 0, 0); PG8_LDB(B1, 0, 1); PG8_SCHED; PG8_LDA(At, 0, 0); PG8_STAGE(PG8_SA(1, 1), a1 + hstep, voffA);
;             PG8_WAIT_V(8); PG8_WAIT_L(0); PG8_BAR; PG8_MMA(0, 0, At, B0); PG8_MMA(0, 1, At, B1); PG8_BAR; PG8_SCHED;
;             PG8_LDA(At, 0, 1); PG8_STAGE(PG8_SB(0, 0), b2, voffB); PG8_STAGE(PG8_SB(0, 1), b2 + hstep, voffB); PG8_STAGE(PG8_SA(0, 0), a2, voffA);
.LBB0_1199:
	s_ashr_i32 s57, s56, 31
	s_lshl_b64 s[58:59], s[56:57], 19
	s_add_u32 s58, s36, s58
	s_addc_u32 s59, s37, s59
	s_and_b64 s[60:61], s[8:9], exec
	s_cselect_b32 s1, s59, s21
	s_cselect_b32 s57, s58, s20
	s_ashr_i32 s55, s54, 31
	s_lshl_b64 s[60:61], s[54:55], 19
	s_add_u32 s60, s68, s60
	s_addc_u32 s61, s69, s61
	s_and_b64 s[62:63], s[8:9], exec
	s_cselect_b32 s55, s61, s35
	s_cselect_b32 s85, s60, s34
	s_add_u32 s20, s20, 0x40080
	s_addc_u32 s21, s21, 0
	s_add_u32 s86, s34, 0x100
	s_addc_u32 s87, s35, 0
	s_mov_b32 s88, -2
	s_waitcnt lgkmcnt(0)
	ds_read_b128 v[140:143], v163
	ds_read_b128 v[168:171], v163 offset:1024
	ds_read_b128 v[172:175], v163 offset:2048
	ds_read_b128 v[176:179], v163 offset:3072
	ds_read_b128 v[180:183], v164
	ds_read_b128 v[184:187], v164 offset:1024
	ds_read_b128 v[188:191], v164 offset:2048
	ds_read_b128 v[192:195], v164 offset:3072
	ds_read_b128 v[198:201], v165
	ds_read_b128 v[202:205], v165 offset:1024
	ds_read_b128 v[206:209], v165 offset:2048
	ds_read_b128 v[210:213], v165 offset:3072
	ds_read_b128 v[214:217], v165 offset:4096
	ds_read_b128 v[218:221], v165 offset:5120
	ds_read_b128 v[222:225], v165 offset:6144
	ds_read_b128 v[226:229], v165 offset:7168
	s_add_u32 s34, s20, 0xfffc0080
	s_addc_u32 s35, s21, -1
	s_cmp_eq_u32 s88, 12
	s_cselect_b32 s63, s1, s35
	s_cselect_b32 s62, s57, s34
	s_cselect_b32 s35, s55, s87
	s_cselect_b32 s34, s85, s86
	s_add_i32 m0, s71, 0xc000
	global_load_lds_dwordx4 v132, s[20:21]
	s_add_i32 m0, s71, 0xe000
	s_nop 0
	global_load_lds_dwordx4 v134, s[20:21]
	s_waitcnt vmcnt(8)
	s_waitcnt lgkmcnt(0)
	s_barrier
	v_mfma_f32_16x16x32_bf16 v[124:127], v[140:143], v[198:201], 0
	v_mfma_f32_16x16x32_bf16 v[120:123], v[172:175], v[198:201], 0
	v_mfma_f32_16x16x32_bf16 v[108:111], v[140:143], v[206:209], 0
	v_mfma_f32_16x16x32_bf16 v[104:107], v[172:175], v[206:209], 0
	v_mfma_f32_16x16x32_bf16 v[92:95], v[140:143], v[214:217], 0
	v_mfma_f32_16x16x32_bf16 v[88:91], v[172:175], v[214:217], 0
	v_mfma_f32_16x16x32_bf16 v[76:79], v[140:143], v[222:225], 0
	v_mfma_f32_16x16x32_bf16 v[72:75], v[172:175], v[222:225], 0
	v_mfma_f32_16x16x32_bf16 v[124:127], v[168:171], v[202:205], v[124:127]
	v_mfma_f32_16x16x32_bf16 v[120:123], v[176:179], v[202:205], v[120:123]
	v_mfma_f32_16x16x32_bf16 v[108:111], v[168:171], v[210:213], v[108:111]
	v_mfma_f32_16x16x32_bf16 v[104:107], v[176:179], v[210:213], v[104:107]
	v_mfma_f32_16x16x32_bf16 v[92:95], v[168:171], v[218:221], v[92:95]
	v_mfma_f32_16x16x32_bf16 v[88:91], v[176:179], v[218:221], v[88:91]
	v_mfma_f32_16x16x32_bf16 v[76:79], v[168:171], v[226:229], v[76:79]
	v_mfma_f32_16x16x32_bf16 v[72:75], v[176:179], v[226:229], v[72:75]
	v_mfma_f32_16x16x32_bf16 v[116:119], v[180:183], v[198:201], 0
	v_mfma_f32_16x16x32_bf16 v[112:115], v[188:191], v[198:201], 0
	v_mfma_f32_16x16x32_bf16 v[100:103], v[180:183], v[206:209], 0
	v_mfma_f32_16x16x32_bf16 v[96:99], v[188:191], v[206:209], 0
	v_mfma_f32_16x16x32_bf16 v[84:87], v[180:183], v[214:217], 0
	v_mfma_f32_16x16x32_bf16 v[80:83], v[188:191], v[214:217], 0
	v_mfma_f32_16x16x32_bf16 v[68:71], v[180:183], v[222:225], 0
	v_mfma_f32_16x16x32_bf16 v[64:67], v[188:191], v[222:225], 0
	v_mfma_f32_16x16x32_bf16 v[116:119], v[184:187], v[202:205], v[116:119]
	v_mfma_f32_16x16x32_bf16 v[112:115], v[192:195], v[202:205], v[112:115]
	v_mfma_f32_16x16x32_bf16 v[100:103], v[184:187], v[210:213], v[100:103]
	v_mfma_f32_16x16x32_bf16 v[96:99], v[192:195], v[210:213], v[96:99]
	v_mfma_f32_16x16x32_bf16 v[84:87], v[184:187], v[218:221], v[84:87]
	v_mfma_f32_16x16x32_bf16 v[80:83], v[192:195], v[218:221], v[80:83]
	v_mfma_f32_16x16x32_bf16 v[68:71], v[184:187], v[226:229], v[68:71]
	v_mfma_f32_16x16x32_bf16 v[64:67], v[192:195], v[226:229], v[64:67]
	s_barrier
	s_add_i32 s89, s77, s70
	s_add_u32 s98, s34, s18
	s_addc_u32 s99, s35, s19
	s_add_u32 s100, s62, s18
	s_addc_u32 s101, s63, s19
	s_mov_b32 m0, s89
	ds_read_b128 v[198:201], v165 offset:16384
	ds_read_b128 v[202:205], v165 offset:17408
	ds_read_b128 v[206:209], v165 offset:18432
	ds_read_b128 v[210:213], v165 offset:19456
	ds_read_b128 v[214:217], v165 offset:20480
	ds_read_b128 v[218:221], v165 offset:21504
	ds_read_b128 v[222:225], v165 offset:22528
	ds_read_b128 v[226:229], v165 offset:23552
	global_load_lds_dwordx4 v146, s[34:35]
	s_add_i32 m0, s89, 0x2000
	s_add_u32 s90, s34, 0x40000
	s_addc_u32 s91, s35, 0
	s_add_i32 s89, s78, s70
	global_load_lds_dwordx4 v150, s[34:35]
	s_mov_b32 m0, s89
	s_nop 0
	global_load_lds_dwordx4 v146, s[90:91]
	s_add_i32 m0, s89, 0x2000
	s_nop 0
	global_load_lds_dwordx4 v150, s[90:91]
	s_mov_b32 m0, s71
	s_nop 0
	global_load_lds_dwordx4 v144, s[62:63]
	s_mov_b32 m0, s72
	s_nop 0
	global_load_lds_dwordx4 v148, s[62:63]
	s_waitcnt vmcnt(8)
	s_waitcnt lgkmcnt(0)
	s_barrier
; #define PG8_STAGE(bufoff, gbase, voff) do { _Pragma("unroll") for (int _i = 0; _i < 2; ++_i) \
;         __builtin_amdgcn_global_load_lds((const unsigned*)((const char*)(gbase) + (voff)[_i]), (PG8_LAS unsigned*)(lds + (bufoff) + ldsw + _i * 8192), 16, 0, 0); } while (0)
; #define PG8_LDA(dst, b, h) do { _Pragma("unroll") for (int m = 0; m < 4; ++m) _Pragma("unroll") for (int k = 0; k < 2; ++k) dst[m][k] = *(const PG8_LAS bf16x8*)(lds + PG8_SA(b, h) + aoff + m * 2048 + k * 1024); } while (0)
; #define PG8_LDB(dst, b, h) do { _Pragma("unroll") for (int n = 0; n < 2; ++n) _Pragma("unroll") for (int k = 0; k < 2; ++k) dst[n][k] = *(const PG8_LAS bf16x8*)(lds + PG8_SB(b, h) + boff + n * 2048 + k * 1024); } while (0)
; #define PG8_MMA(ai, bj, At, Bt) do { __builtin_amdgcn_s_setprio(1); _Pragma("unroll") for (int m = 0; m < 4; ++m) _Pragma("unroll") for (int n = 0; n < 2; ++n) _Pragma("unroll") for (int k = 0; k < 2; ++k) \
;         acc[ai][bj][m][n] = __builtin_amdgcn_mfma_f32_16x16x32_bf16(Bt[n][k], At[m][k], acc[ai][bj][m][n], 0, 0, 0); __builtin_amdgcn_s_setprio(0); } while (0)
; #define PG8_WAIT_V(n) asm volatile("s_waitcnt vmcnt(" #n ")" ::: "memory")
; #define PG8_WAIT_L(n) asm volatile("s_waitcnt lgkmcnt(" #n ")" ::: "memory")
; #define PG8_BAR __builtin_amdgcn_s_barrier()
; #define PG8_SCHED __builtin_amdgcn_sched_barrier(0)
; template <class Epi, class Sched, bool ALIGN_EPI = false, bool SP2 = false>
; __device__ __forceinline__ void gemm_phase(PG8_LAS unsigned char* lds, const Gemm g, const Sched& S, const Epi& E) {
;     ...
;             PG8_WAIT_V(8); PG8_WAIT_L(0); PG8_BAR; PG8_MMA(1, 0, At, B0); PG8_MMA(1, 1, At, B1); PG8_BAR; PG8_SCHED;
;             PG8_LDB(B0, 1, 0); PG8_LDB(B1, 1, 1); PG8_SCHED; PG8_LDA(At, 1, 0); PG8_STAGE(PG8_SA(0, 1), a2 + hstep, voffA);
;             PG8_WAIT_V(8); PG8_WAIT_L(0); PG8_BAR; PG8_MMA(0, 0, At, B0); PG8_MMA(0, 1, At, B1); PG8_BAR; PG8_SCHED;
	v_mfma_f32_16x16x32_bf16 v[60:63], v[140:143], v[198:201], 0
	v_mfma_f32_16x16x32_bf16 v[56:59], v[172:175], v[198:201], 0
	v_mfma_f32_16x16x32_bf16 v[48:51], v[140:143], v[206:209], 0
	v_mfma_f32_16x16x32_bf16 v[40:43], v[172:175], v[206:209], 0
	v_mfma_f32_16x16x32_bf16 v[32:35], v[140:143], v[214:217], 0
	v_mfma_f32_16x16x32_bf16 v[24:27], v[172:175], v[214:217], 0
	v_mfma_f32_16x16x32_bf16 v[16:19], v[140:143], v[222:225], 0
	v_mfma_f32_16x16x32_bf16 v[8:11], v[172:175], v[222:225], 0
	v_mfma_f32_16x16x32_bf16 v[60:63], v[168:171], v[202:205], v[60:63]
	v_mfma_f32_16x16x32_bf16 v[56:59], v[176:179], v[202:205], v[56:59]
	v_mfma_f32_16x16x32_bf16 v[48:51], v[168:171], v[210:213], v[48:51]
	v_mfma_f32_16x16x32_bf16 v[40:43], v[176:179], v[210:213], v[40:43]
	v_mfma_f32_16x16x32_bf16 v[32:35], v[168:171], v[218:221], v[32:35]
	v_mfma_f32_16x16x32_bf16 v[24:27], v[176:179], v[218:221], v[24:27]
	v_mfma_f32_16x16x32_bf16 v[16:19], v[168:171], v[226:229], v[16:19]
	v_mfma_f32_16x16x32_bf16 v[8:11], v[176:179], v[226:229], v[8:11]
	v_mfma_f32_16x16x32_bf16 v[52:55], v[180:183], v[198:201], 0
	v_mfma_f32_16x16x32_bf16 v[44:47], v[188:191], v[198:201], 0
	v_mfma_f32_16x16x32_bf16 v[36:39], v[180:183], v[206:209], 0
	v_mfma_f32_16x16x32_bf16 v[28:31], v[188:191], v[206:209], 0
	v_mfma_f32_16x16x32_bf16 v[20:23], v[180:183], v[214:217], 0
	v_mfma_f32_16x16x32_bf16 v[12:15], v[188:191], v[214:217], 0
	v_mfma_f32_16x16x32_bf16 v[4:7], v[180:183], v[222:225], 0
	v_mfma_f32_16x16x32_bf16 v[0:3], v[188:191], v[222:225], 0
	v_mfma_f32_16x16x32_bf16 v[52:55], v[184:187], v[202:205], v[52:55]
	v_mfma_f32_16x16x32_bf16 v[44:47], v[192:195], v[202:205], v[44:47]
	v_mfma_f32_16x16x32_bf16 v[36:39], v[184:187], v[210:213], v[36:39]
	v_mfma_f32_16x16x32_bf16 v[28:31], v[192:195], v[210:213], v[28:31]
	v_mfma_f32_16x16x32_bf16 v[20:23], v[184:187], v[218:221], v[20:23]
	v_mfma_f32_16x16x32_bf16 v[12:15], v[192:195], v[218:221], v[12:15]
	v_mfma_f32_16x16x32_bf16 v[4:7], v[184:187], v[226:229], v[4:7]
	v_mfma_f32_16x16x32_bf16 v[0:3], v[192:195], v[226:229], v[0:3]
	s_barrier
	s_add_i32 s89, 0, 0x18000
	v_add_u32_e32 v128, s89, v161
	s_add_i32 s90, 0, 0x1c000
	ds_read_b128 v[140:143], v128
	ds_read_b128 v[168:171], v128 offset:1024
	ds_read_b128 v[172:175], v128 offset:2048
	ds_read_b128 v[176:179], v128 offset:3072
	v_add_u32_e32 v128, s90, v161
	ds_read_b128 v[180:183], v128
	ds_read_b128 v[184:187], v128 offset:1024
	ds_read_b128 v[188:191], v128 offset:2048
	ds_read_b128 v[192:195], v128 offset:3072
	s_add_u32 s62, s62, 0x40000
	s_addc_u32 s63, s63, 0
	s_mov_b32 m0, s73
	ds_read_b128 v[198:201], v165 offset:32768
	ds_read_b128 v[202:205], v165 offset:33792
	ds_read_b128 v[206:209], v165 offset:34816
	ds_read_b128 v[210:213], v165 offset:35840
	ds_read_b128 v[214:217], v165 offset:36864
	ds_read_b128 v[218:221], v165 offset:37888
	ds_read_b128 v[222:225], v165 offset:38912
	ds_read_b128 v[226:229], v165 offset:39936
	global_load_lds_dwordx4 v144, s[62:63]
	s_mov_b32 m0, s74
	s_nop 0
	global_load_lds_dwordx4 v148, s[62:63]
	s_waitcnt vmcnt(8)
	s_waitcnt lgkmcnt(0)
	s_barrier
	v_mfma_f32_16x16x32_bf16 v[124:127], v[140:143], v[198:201], v[124:127]
	v_mfma_f32_16x16x32_bf16 v[120:123], v[172:175], v[198:201], v[120:123]
	v_mfma_f32_16x16x32_bf16 v[108:111], v[140:143], v[206:209], v[108:111]
	v_mfma_f32_16x16x32_bf16 v[104:107], v[172:175], v[206:209], v[104:107]
	v_mfma_f32_16x16x32_bf16 v[92:95], v[140:143], v[214:217], v[92:95]
	v_mfma_f32_16x16x32_bf16 v[88:91], v[172:175], v[214:217], v[88:91]
	v_mfma_f32_16x16x32_bf16 v[76:79], v[140:143], v[222:225], v[76:79]
	v_mfma_f32_16x16x32_bf16 v[72:75], v[172:175], v[222:225], v[72:75]
	v_mfma_f32_16x16x32_bf16 v[124:127], v[168:171], v[202:205], v[124:127]
	v_mfma_f32_16x16x32_bf16 v[120:123], v[176:179], v[202:205], v[120:123]
	v_mfma_f32_16x16x32_bf16 v[108:111], v[168:171], v[210:213], v[108:111]
	v_mfma_f32_16x16x32_bf16 v[104:107], v[176:179], v[210:213], v[104:107]
	v_mfma_f32_16x16x32_bf16 v[92:95], v[168:171], v[218:221], v[92:95]
	v_mfma_f32_16x16x32_bf16 v[88:91], v[176:179], v[218:221], v[88:91]
	v_mfma_f32_16x16x32_bf16 v[76:79], v[168:171], v[226:229], v[76:79]
	v_mfma_f32_16x16x32_bf16 v[72:75], v[176:179], v[226:229], v[72:75]
	v_mfma_f32_16x16x32_bf16 v[116:119], v[180:183], v[198:201], v[116:119]
	v_mfma_f32_16x16x32_bf16 v[112:115], v[188:191], v[198:201], v[112:115]
	v_mfma_f32_16x16x32_bf16 v[100:103], v[180:183], v[206:209], v[100:103]
	v_mfma_f32_16x16x32_bf16 v[96:99], v[188:191], v[206:209], v[96:99]
	v_mfma_f32_16x16x32_bf16 v[84:87], v[180:183], v[214:217], v[84:87]
	v_mfma_f32_16x16x32_bf16 v[80:83], v[188:191], v[214:217], v[80:83]
	v_mfma_f32_16x16x32_bf16 v[68:71], v[180:183], v[222:225], v[68:71]
	v_mfma_f32_16x16x32_bf16 v[64:67], v[188:191], v[222:225], v[64:67]
	v_mfma_f32_16x16x32_bf16 v[116:119], v[184:187], v[202:205], v[116:119]
	v_mfma_f32_16x16x32_bf16 v[112:115], v[192:195], v[202:205], v[112:115]
	v_mfma_f32_16x16x32_bf16 v[100:103], v[184:187], v[210:213], v[100:103]
	v_mfma_f32_16x16x32_bf16 v[96:99], v[192:195], v[210:213], v[96:99]
	v_mfma_f32_16x16x32_bf16 v[84:87], v[184:187], v[218:221], v[84:87]
	v_mfma_f32_16x16x32_bf16 v[80:83], v[192:195], v[218:221], v[80:83]
	v_mfma_f32_16x16x32_bf16 v[68:71], v[184:187], v[226:229], v[68:71]
	v_mfma_f32_16x16x32_bf16 v[64:67], v[192:195], v[226:229], v[64:67]
	s_barrier
; #define PG8_STAGE(bufoff, gbase, voff) do { _Pragma("unroll") for (int _i = 0; _i < 2; ++_i) \
;         __builtin_amdgcn_global_load_lds((const unsigned*)((const char*)(gbase) + (voff)[_i]), (PG8_LAS unsigned*)(lds + (bufoff) + ldsw + _i * 8192), 16, 0, 0); } while (0)
; #define PG8_LDA(dst, b, h) do { _Pragma("unroll") for (int m = 0; m < 4; ++m) _Pragma("unroll") for (int k = 0; k < 2; ++k) dst[m][k] = *(const PG8_LAS bf16x8*)(lds + PG8_SA(b, h) + aoff + m * 2048 + k * 1024); } while (0)
; #define PG8_MMA(ai, bj, At, Bt) do { __builtin_amdgcn_s_setprio(1); _Pragma("unroll") for (int m = 0; m < 4; ++m) _Pragma("unroll") for (int n = 0; n < 2; ++n) _Pragma("unroll") for (int k = 0; k < 2; ++k) \
;         acc[ai][bj][m][n] = __builtin_amdgcn_mfma_f32_16x16x32_bf16(Bt[n][k], At[m][k], acc[ai][bj][m][n], 0, 0, 0); __builtin_amdgcn_s_setprio(0); } while (0)
; #define PG8_WAIT_V(n) asm volatile("s_waitcnt vmcnt(" #n ")" ::: "memory")
; #define PG8_WAIT_L(n) asm volatile("s_waitcnt lgkmcnt(" #n ")" ::: "memory")
; #define PG8_BAR __builtin_amdgcn_s_barrier()
; #define PG8_SCHED __builtin_amdgcn_sched_barrier(0)
; template <class Epi, class Sched, bool ALIGN_EPI = false, bool SP2 = false>
; __device__ __forceinline__ void gemm_phase(PG8_LAS unsigned char* lds, const Gemm g, const Sched& S, const Epi& E) {
;     ...
;             PG8_LDA(At, 1, 1); PG8_STAGE(PG8_SB(1, 0), b3, voffB); PG8_STAGE(PG8_SB(1, 1), b3 + hstep, voffB); PG8_STAGE(PG8_SA(1, 0), a3, voffA);
;             PG8_WAIT_V(8); PG8_WAIT_L(0); PG8_BAR; PG8_MMA(1, 0, At, B0); PG8_MMA(1, 1, At, B1); PG8_BAR; PG8_SCHED;
	s_add_i32 s62, s89, s70
	s_mov_b32 m0, s62
	ds_read_b128 v[198:201], v165 offset:49152
	ds_read_b128 v[202:205], v165 offset:50176
	ds_read_b128 v[206:209], v165 offset:51200
	ds_read_b128 v[210:213], v165 offset:52224
	ds_read_b128 v[214:217], v165 offset:53248
	ds_read_b128 v[218:221], v165 offset:54272
	ds_read_b128 v[222:225], v165 offset:55296
	ds_read_b128 v[226:229], v165 offset:56320
	global_load_lds_dwordx4 v146, s[98:99]
	s_add_i32 m0, s62, 0x2000
	s_add_u32 s34, s34, 0x40080
	s_addc_u32 s35, s35, 0
	s_add_i32 s62, s90, s70
	global_load_lds_dwordx4 v150, s[98:99]
	s_mov_b32 m0, s62
	s_nop 0
	global_load_lds_dwordx4 v146, s[34:35]
	s_add_i32 m0, s62, 0x2000
	s_nop 0
	global_load_lds_dwordx4 v150, s[34:35]
	s_mov_b32 m0, s75
	s_nop 0
	global_load_lds_dwordx4 v144, s[100:101]
	s_mov_b32 m0, s76
	s_nop 0
	global_load_lds_dwordx4 v148, s[100:101]
	s_waitcnt vmcnt(8)
	s_waitcnt lgkmcnt(0)
	s_barrier
	v_mfma_f32_16x16x32_bf16 v[60:63], v[140:143], v[198:201], v[60:63]
	v_mfma_f32_16x16x32_bf16 v[56:59], v[172:175], v[198:201], v[56:59]
	v_mfma_f32_16x16x32_bf16 v[48:51], v[140:143], v[206:209], v[48:51]
	v_mfma_f32_16x16x32_bf16 v[40:43], v[172:175], v[206:209], v[40:43]
	v_mfma_f32_16x16x32_bf16 v[32:35], v[140:143], v[214:217], v[32:35]
	v_mfma_f32_16x16x32_bf16 v[24:27], v[172:175], v[214:217], v[24:27]
	v_mfma_f32_16x16x32_bf16 v[16:19], v[140:143], v[222:225], v[16:19]
	v_mfma_f32_16x16x32_bf16 v[8:11], v[172:175], v[222:225], v[8:11]
	v_mfma_f32_16x16x32_bf16 v[60:63], v[168:171], v[202:205], v[60:63]
	v_mfma_f32_16x16x32_bf16 v[56:59], v[176:179], v[202:205], v[56:59]
	v_mfma_f32_16x16x32_bf16 v[48:51], v[168:171], v[210:213], v[48:51]
	v_mfma_f32_16x16x32_bf16 v[40:43], v[176:179], v[210:213], v[40:43]
	v_mfma_f32_16x16x32_bf16 v[32:35], v[168:171], v[218:221], v[32:35]
	v_mfma_f32_16x16x32_bf16 v[24:27], v[176:179], v[218:221], v[24:27]
	v_mfma_f32_16x16x32_bf16 v[16:19], v[168:171], v[226:229], v[16:19]
	v_mfma_f32_16x16x32_bf16 v[8:11], v[176:179], v[226:229], v[8:11]
	v_mfma_f32_16x16x32_bf16 v[52:55], v[180:183], v[198:201], v[52:55]
	v_mfma_f32_16x16x32_bf16 v[44:47], v[188:191], v[198:201], v[44:47]
	v_mfma_f32_16x16x32_bf16 v[36:39], v[180:183], v[206:209], v[36:39]
	v_mfma_f32_16x16x32_bf16 v[28:31], v[188:191], v[206:209], v[28:31]
	v_mfma_f32_16x16x32_bf16 v[20:23], v[180:183], v[214:217], v[20:23]
	v_mfma_f32_16x16x32_bf16 v[12:15], v[188:191], v[214:217], v[12:15]
	v_mfma_f32_16x16x32_bf16 v[4:7], v[180:183], v[222:225], v[4:7]
	v_mfma_f32_16x16x32_bf16 v[0:3], v[188:191], v[222:225], v[0:3]
	v_mfma_f32_16x16x32_bf16 v[52:55], v[184:187], v[202:205], v[52:55]
	v_mfma_f32_16x16x32_bf16 v[44:47], v[192:195], v[202:205], v[44:47]
	v_mfma_f32_16x16x32_bf16 v[36:39], v[184:187], v[210:213], v[36:39]
	v_mfma_f32_16x16x32_bf16 v[28:31], v[192:195], v[210:213], v[28:31]
	v_mfma_f32_16x16x32_bf16 v[20:23], v[184:187], v[218:221], v[20:23]
	v_mfma_f32_16x16x32_bf16 v[12:15], v[192:195], v[218:221], v[12:15]
	v_mfma_f32_16x16x32_bf16 v[4:7], v[184:187], v[226:229], v[4:7]
	v_mfma_f32_16x16x32_bf16 v[0:3], v[192:195], v[226:229], v[0:3]
	s_barrier
	s_add_i32 s88, s88, 2
	s_add_u32 s20, s20, 0x100
	s_addc_u32 s21, s21, 0
	s_add_u32 s86, s86, 0x100
	s_addc_u32 s87, s87, 0
	s_cmp_gt_u32 s88, 13

; #define PG8_STAGE(bufoff, gbase, voff) do { _Pragma("unroll") for (int _i = 0; _i < 2; ++_i) \
;         __builtin_amdgcn_global_load_lds((const unsigned*)((const char*)(gbase) + (voff)[_i]), (PG8_LAS unsigned*)(lds + (bufoff) + ldsw + _i * 8192), 16, 0, 0); } while (0)
; #define PG8_LDA(dst, b, h) do { _Pragma("unroll") for (int m = 0; m < 4; ++m) _Pragma("unroll") for (int k = 0; k < 2; ++k) dst[m][k] = *(const PG8_LAS bf16x8*)(lds + PG8_SA(b, h) + aoff + m * 2048 + k * 1024); } while (0)
; #define PG8_LDB(dst, b, h) do { _Pragma("unroll") for (int n = 0; n < 2; ++n) _Pragma("unroll") for (int k = 0; k < 2; ++k) dst[n][k] = *(const PG8_LAS bf16x8*)(lds + PG8_SB(b, h) + boff + n * 2048 + k * 1024); } while (0)
; #define PG8_SCHED __builtin_amdgcn_sched_barrier(0)
;     __host__ __device__ bool next(int i, Unit& u) const {
;         const long L = (long)i * G + c; if (L >= nwg) return false;
;         int wgid = (int)L; { const int q = nwg / NXCD, r = nwg % NXCD, xcd = wgid % NXCD, off = wgid / NXCD; wgid = (xcd < r ? xcd * (q + 1) : r * (q + 1) + (xcd - r) * q) + off; }
;         const int nig = WGM * nN, gid = wgid / nig, fm = gid * WGM, gsz = (nM - fm) < WGM ? (nM - fm) : WGM;
; template <class Epi, class Sched, bool ALIGN_EPI = false, bool SP2 = false>
; __device__ __forceinline__ void gemm_phase(PG8_LAS unsigned char* lds, const Gemm g, const Sched& S, const Epi& E) {
;     ...
;         const bool has_next = S.next(ui + 1, nxt);
;         const char* nA = has_next ? (const char*)g.A + (size_t)nxt.pm * tstep : cA; const char* nB = has_next ? (const char*)g.Bt + (size_t)nxt.pn * tstep : cB;
;         for (int t = 0; t < nt; t += 2) {
;             const bool last = (t == nt - 2);
;             const char* a1 = cA + (size_t)(t + 1) * kstep;
;             const char* a2 = last ? nA : cA + (size_t)(t + 2) * kstep; const char* b2 = last ? nB : cB + (size_t)(t + 2) * kstep;
;             const char* a3 = a2 + kstep; const char* b3 = b2 + kstep;
;             if (last && has_next) S.a_ready(nxt);
;             if constexpr (SP2) {
;             PG8_LDB(B0, 0, 0); PG8_LDB(B1, 0, 1); PG8_SCHED; PG8_LDA(At, 0, 0); PG8_STAGE(PG8_SA(1, 1), a1 + hstep, voffA);
.LBB0_1439:
	ds_read_b128 v[128:131], v153
	ds_read_b128 v[132:135], v153 offset:1024
	ds_read_b128 v[136:139], v153 offset:2048
	ds_read_b128 v[140:143], v153 offset:3072
	ds_read_b128 v[172:175], v155
	ds_read_b128 v[176:179], v155 offset:1024
	ds_read_b128 v[180:183], v155 offset:2048
	ds_read_b128 v[184:187], v155 offset:3072
	ds_read_b128 v[188:191], v157
	ds_read_b128 v[192:195], v157 offset:1024
	ds_read_b128 v[198:201], v157 offset:2048
	ds_read_b128 v[202:205], v157 offset:3072
	ds_read_b128 v[206:209], v157 offset:4096
	ds_read_b128 v[210:213], v157 offset:5120
	ds_read_b128 v[214:217], v157 offset:6144
	ds_read_b128 v[218:221], v157 offset:7168
	s_add_i32 s55, s55, 1
	s_mul_i32 s4, s55, s33
	s_mul_hi_u32 s5, s55, s64
	s_add_i32 s5, s5, s4
	s_mul_i32 s4, s55, s64
	s_add_u32 s16, s4, s2
	s_addc_u32 s17, s5, s3
	v_cmp_gt_i64_e32 vcc, s[16:17], v[168:169]
	v_cmp_lt_i64_e64 s[4:5], s[16:17], v[166:167]
	s_cbranch_vccnz .LBB0_1445
	s_ashr_i32 s12, s16, 31
	s_lshr_b32 s12, s12, 29
	s_add_i32 s14, s16, s12
	s_and_b32 s12, s14, -8
	s_sub_i32 s15, s16, s12
	s_cmp_gt_i32 s15, -1
	s_mov_b64 s[12:13], -1
	s_cbranch_scc0 .LBB0_1442
	s_lshl_b32 s16, s15, 6
	s_mov_b64 s[12:13], 0

; #define PG8_STAGE(bufoff, gbase, voff) do { _Pragma("unroll") for (int _i = 0; _i < 2; ++_i) \
;         __builtin_amdgcn_global_load_lds((const unsigned*)((const char*)(gbase) + (voff)[_i]), (PG8_LAS unsigned*)(lds + (bufoff) + ldsw + _i * 8192), 16, 0, 0); } while (0)
; #define PG8_LDA(dst, b, h) do { _Pragma("unroll") for (int m = 0; m < 4; ++m) _Pragma("unroll") for (int k = 0; k < 2; ++k) dst[m][k] = *(const PG8_LAS bf16x8*)(lds + PG8_SA(b, h) + aoff + m * 2048 + k * 1024); } while (0)
; #define PG8_LDB(dst, b, h) do { _Pragma("unroll") for (int n = 0; n < 2; ++n) _Pragma("unroll") for (int k = 0; k < 2; ++k) dst[n][k] = *(const PG8_LAS bf16x8*)(lds + PG8_SB(b, h) + boff + n * 2048 + k * 1024); } while (0)
; #define PG8_WAIT_V(n) asm volatile("s_waitcnt vmcnt(" #n ")" ::: "memory")
; #define PG8_WAIT_L(n) asm volatile("s_waitcnt lgkmcnt(" #n ")" ::: "memory")
; #define PG8_BAR __builtin_amdgcn_s_barrier()
; #define PG8_SCHED __builtin_amdgcn_sched_barrier(0)
; template <class Epi, class Sched, bool ALIGN_EPI = false, bool SP2 = false>
; __device__ __forceinline__ void gemm_phase(PG8_LAS unsigned char* lds, const Gemm g, const Sched& S, const Epi& E) {
;     ...
;         const char* nA = has_next ? (const char*)g.A + (size_t)nxt.pm * tstep : cA; const char* nB = has_next ? (const char*)g.Bt + (size_t)nxt.pn * tstep : cB;
;         for (int t = 0; t < nt; t += 2) {
;             const bool last = (t == nt - 2);
;             const char* a1 = cA + (size_t)(t + 1) * kstep;
;             const char* a2 = last ? nA : cA + (size_t)(t + 2) * kstep; const char* b2 = last ? nB : cB + (size_t)(t + 2) * kstep;
;             const char* a3 = a2 + kstep; const char* b3 = b2 + kstep;
;             if (last && has_next) S.a_ready(nxt);
;             if constexpr (SP2) {
;             PG8_LDB(B0, 0, 0); PG8_LDB(B1, 0, 1); PG8_SCHED; PG8_LDA(At, 0, 0); PG8_STAGE(PG8_SA(1, 1), a1 + hstep, voffA);
;             PG8_WAIT_V(8); PG8_WAIT_L(0); PG8_BAR; PG8_MMA(0, 0, At, B0); PG8_MMA(0, 1, At, B1); PG8_BAR; PG8_SCHED;
;             PG8_LDA(At, 0, 1); PG8_STAGE(PG8_SB(0, 0), b2, voffB); PG8_STAGE(PG8_SB(0, 1), b2 + hstep, voffB); PG8_STAGE(PG8_SA(0, 0), a2, voffA);
;             PG8_WAIT_V(8); PG8_WAIT_L(0); PG8_BAR; PG8_MMA(1, 0, At, B0); PG8_MMA(1, 1, At, B1); PG8_BAR; PG8_SCHED;
.LBB0_1445:
	s_ashr_i32 s15, s14, 31
	s_lshl_b64 s[16:17], s[14:15], 19
	s_add_u32 s16, s49, s16
	s_addc_u32 s17, s50, s17
	s_and_b64 s[18:19], s[4:5], exec
	s_cselect_b32 s15, s17, s21
	s_cselect_b32 s65, s16, s20
	s_ashr_i32 s13, s12, 31
	s_lshl_b64 s[18:19], s[12:13], 19
	s_add_u32 s18, s36, s18
	s_addc_u32 s19, s37, s19
	s_and_b64 s[44:45], s[4:5], exec
	s_cselect_b32 s13, s19, s39
	s_cselect_b32 s66, s18, s38
	s_add_u32 s20, s20, 0x40080
	s_addc_u32 s21, s21, 0
	s_add_u32 s67, s38, 0x100
	s_addc_u32 s68, s39, 0
	s_mov_b32 s69, -2
	s_add_u32 s38, s20, 0xfffc0080
	s_addc_u32 s39, s21, -1
	s_cmp_eq_u32 s69, 12
	s_cselect_b32 s45, s15, s39
	s_cselect_b32 s44, s65, s38
	s_cselect_b32 s39, s13, s68
	s_cselect_b32 s38, s66, s67
	s_add_i32 m0, s35, 0xc000
	global_load_lds_dwordx4 v162, s[20:21]
	s_add_i32 m0, s35, 0xe000
	s_nop 0
	global_load_lds_dwordx4 v164, s[20:21]
	s_waitcnt vmcnt(8)
	s_waitcnt lgkmcnt(0)
	s_barrier
	v_mfma_f32_16x16x32_bf16 v[124:127], v[128:131], v[188:191], 0
	v_mfma_f32_16x16x32_bf16 v[120:123], v[136:139], v[188:191], 0
	v_mfma_f32_16x16x32_bf16 v[108:111], v[128:131], v[198:201], 0
	v_mfma_f32_16x16x32_bf16 v[104:107], v[136:139], v[198:201], 0
	v_mfma_f32_16x16x32_bf16 v[96:99], v[128:131], v[206:209], 0
	v_mfma_f32_16x16x32_bf16 v[88:91], v[136:139], v[206:209], 0
	v_mfma_f32_16x16x32_bf16 v[80:83], v[128:131], v[214:217], 0
	v_mfma_f32_16x16x32_bf16 v[72:75], v[136:139], v[214:217], 0
	v_mfma_f32_16x16x32_bf16 v[124:127], v[132:135], v[192:195], v[124:127]
	v_mfma_f32_16x16x32_bf16 v[120:123], v[140:143], v[192:195], v[120:123]
	v_mfma_f32_16x16x32_bf16 v[108:111], v[132:135], v[202:205], v[108:111]
	v_mfma_f32_16x16x32_bf16 v[104:107], v[140:143], v[202:205], v[104:107]
	v_mfma_f32_16x16x32_bf16 v[96:99], v[132:135], v[210:213], v[96:99]
	v_mfma_f32_16x16x32_bf16 v[88:91], v[140:143], v[210:213], v[88:91]
	v_mfma_f32_16x16x32_bf16 v[80:83], v[132:135], v[218:221], v[80:83]
	v_mfma_f32_16x16x32_bf16 v[72:75], v[140:143], v[218:221], v[72:75]
	v_mfma_f32_16x16x32_bf16 v[116:119], v[172:175], v[188:191], 0
	v_mfma_f32_16x16x32_bf16 v[112:115], v[180:183], v[188:191], 0
	v_mfma_f32_16x16x32_bf16 v[100:103], v[172:175], v[198:201], 0
	v_mfma_f32_16x16x32_bf16 v[92:95], v[180:183], v[198:201], 0
	v_mfma_f32_16x16x32_bf16 v[84:87], v[172:175], v[206:209], 0
	v_mfma_f32_16x16x32_bf16 v[76:79], v[180:183], v[206:209], 0
	v_mfma_f32_16x16x32_bf16 v[68:71], v[172:175], v[214:217], 0
	v_mfma_f32_16x16x32_bf16 v[64:67], v[180:183], v[214:217], 0
	v_mfma_f32_16x16x32_bf16 v[116:119], v[176:179], v[192:195], v[116:119]
	v_mfma_f32_16x16x32_bf16 v[112:115], v[184:187], v[192:195], v[112:115]
	v_mfma_f32_16x16x32_bf16 v[100:103], v[176:179], v[202:205], v[100:103]
	v_mfma_f32_16x16x32_bf16 v[92:95], v[184:187], v[202:205], v[92:95]
	v_mfma_f32_16x16x32_bf16 v[84:87], v[176:179], v[210:213], v[84:87]
	v_mfma_f32_16x16x32_bf16 v[76:79], v[184:187], v[210:213], v[76:79]
	v_mfma_f32_16x16x32_bf16 v[68:71], v[176:179], v[218:221], v[68:71]
	v_mfma_f32_16x16x32_bf16 v[64:67], v[184:187], v[218:221], v[64:67]
	s_barrier
	s_add_i32 s70, s60, s51
	s_add_u32 s98, s38, s6
	s_addc_u32 s99, s39, s7
	s_add_u32 s100, s44, s6
	s_addc_u32 s101, s45, s7
	s_mov_b32 m0, s70
	ds_read_b128 v[188:191], v157 offset:16384
	ds_read_b128 v[192:195], v157 offset:17408
	ds_read_b128 v[198:201], v157 offset:18432
	ds_read_b128 v[202:205], v157 offset:19456
	ds_read_b128 v[206:209], v157 offset:20480
	ds_read_b128 v[210:213], v157 offset:21504
	ds_read_b128 v[214:217], v157 offset:22528
	ds_read_b128 v[218:221], v157 offset:23552
	global_load_lds_dwordx4 v146, s[38:39]
	s_add_i32 m0, s70, 0x2000
	s_add_u32 s70, s38, 0x40000
	s_addc_u32 s71, s39, 0
	s_add_i32 s72, s61, s51
	global_load_lds_dwordx4 v150, s[38:39]
	s_mov_b32 m0, s72
	s_nop 0
	global_load_lds_dwordx4 v146, s[70:71]
	s_add_i32 m0, s72, 0x2000
	s_nop 0
	global_load_lds_dwordx4 v150, s[70:71]
	s_mov_b32 m0, s35
	s_nop 0
	global_load_lds_dwordx4 v144, s[44:45]
	s_mov_b32 m0, s52
	s_nop 0
	global_load_lds_dwordx4 v148, s[44:45]
	s_waitcnt vmcnt(8)
	s_waitcnt lgkmcnt(0)
	s_barrier
	v_mfma_f32_16x16x32_bf16 v[60:63], v[128:131], v[188:191], 0
	v_mfma_f32_16x16x32_bf16 v[56:59], v[136:139], v[188:191], 0
	v_mfma_f32_16x16x32_bf16 v[48:51], v[128:131], v[198:201], 0
	v_mfma_f32_16x16x32_bf16 v[40:43], v[136:139], v[198:201], 0
	v_mfma_f32_16x16x32_bf16 v[32:35], v[128:131], v[206:209], 0
	v_mfma_f32_16x16x32_bf16 v[24:27], v[136:139], v[206:209], 0
	v_mfma_f32_16x16x32_bf16 v[16:19], v[128:131], v[214:217], 0
	v_mfma_f32_16x16x32_bf16 v[8:11], v[136:139], v[214:217], 0
	v_mfma_f32_16x16x32_bf16 v[60:63], v[132:135], v[192:195], v[60:63]
	v_mfma_f32_16x16x32_bf16 v[56:59], v[140:143], v[192:195], v[56:59]
	v_mfma_f32_16x16x32_bf16 v[48:51], v[132:135], v[202:205], v[48:51]
	v_mfma_f32_16x16x32_bf16 v[40:43], v[140:143], v[202:205], v[40:43]
	v_mfma_f32_16x16x32_bf16 v[32:35], v[132:135], v[210:213], v[32:35]
	v_mfma_f32_16x16x32_bf16 v[24:27], v[140:143], v[210:213], v[24:27]
	v_mfma_f32_16x16x32_bf16 v[16:19], v[132:135], v[218:221], v[16:19]
	v_mfma_f32_16x16x32_bf16 v[8:11], v[140:143], v[218:221], v[8:11]
	v_mfma_f32_16x16x32_bf16 v[52:55], v[172:175], v[188:191], 0
	v_mfma_f32_16x16x32_bf16 v[44:47], v[180:183], v[188:191], 0
	v_mfma_f32_16x16x32_bf16 v[36:39], v[172:175], v[198:201], 0
	v_mfma_f32_16x16x32_bf16 v[28:31], v[180:183], v[198:201], 0
	v_mfma_f32_16x16x32_bf16 v[20:23], v[172:175], v[206:209], 0
	v_mfma_f32_16x16x32_bf16 v[12:15], v[180:183], v[206:209], 0
	v_mfma_f32_16x16x32_bf16 v[4:7], v[172:175], v[214:217], 0
	v_mfma_f32_16x16x32_bf16 v[0:3], v[180:183], v[214:217], 0
	v_mfma_f32_16x16x32_bf16 v[52:55], v[176:179], v[192:195], v[52:55]
	v_mfma_f32_16x16x32_bf16 v[44:47], v[184:187], v[192:195], v[44:47]
	v_mfma_f32_16x16x32_bf16 v[36:39], v[176:179], v[202:205], v[36:39]
	v_mfma_f32_16x16x32_bf16 v[28:31], v[184:187], v[202:205], v[28:31]
	v_mfma_f32_16x16x32_bf16 v[20:23], v[176:179], v[210:213], v[20:23]
	v_mfma_f32_16x16x32_bf16 v[12:15], v[184:187], v[210:213], v[12:15]
	v_mfma_f32_16x16x32_bf16 v[4:7], v[176:179], v[218:221], v[4:7]
	v_mfma_f32_16x16x32_bf16 v[0:3], v[184:187], v[218:221], v[0:3]
	s_barrier
; #define PG8_STAGE(bufoff, gbase, voff) do { _Pragma("unroll") for (int _i = 0; _i < 2; ++_i) \
;         __builtin_amdgcn_global_load_lds((const unsigned*)((const char*)(gbase) + (voff)[_i]), (PG8_LAS unsigned*)(lds + (bufoff) + ldsw + _i * 8192), 16, 0, 0); } while (0)
; #define PG8_LDA(dst, b, h) do { _Pragma("unroll") for (int m = 0; m < 4; ++m) _Pragma("unroll") for (int k = 0; k < 2; ++k) dst[m][k] = *(const PG8_LAS bf16x8*)(lds + PG8_SA(b, h) + aoff + m * 2048 + k * 1024); } while (0)
; #define PG8_LDB(dst, b, h) do { _Pragma("unroll") for (int n = 0; n < 2; ++n) _Pragma("unroll") for (int k = 0; k < 2; ++k) dst[n][k] = *(const PG8_LAS bf16x8*)(lds + PG8_SB(b, h) + boff + n * 2048 + k * 1024); } while (0)
; #define PG8_MMA(ai, bj, At, Bt) do { __builtin_amdgcn_s_setprio(1); _Pragma("unroll") for (int m = 0; m < 4; ++m) _Pragma("unroll") for (int n = 0; n < 2; ++n) _Pragma("unroll") for (int k = 0; k < 2; ++k) \
;         acc[ai][bj][m][n] = __builtin_amdgcn_mfma_f32_16x16x32_bf16(Bt[n][k], At[m][k], acc[ai][bj][m][n], 0, 0, 0); __builtin_amdgcn_s_setprio(0); } while (0)
; #define PG8_WAIT_V(n) asm volatile("s_waitcnt vmcnt(" #n ")" ::: "memory")
; #define PG8_WAIT_L(n) asm volatile("s_waitcnt lgkmcnt(" #n ")" ::: "memory")
; #define PG8_BAR __builtin_amdgcn_s_barrier()
; #define PG8_SCHED __builtin_amdgcn_sched_barrier(0)
; template <class Epi, class Sched, bool ALIGN_EPI = false, bool SP2 = false>
; __device__ __forceinline__ void gemm_phase(PG8_LAS unsigned char* lds, const Gemm g, const Sched& S, const Epi& E) {
;     ...
;             PG8_LDB(B0, 1, 0); PG8_LDB(B1, 1, 1); PG8_SCHED; PG8_LDA(At, 1, 0); PG8_STAGE(PG8_SA(0, 1), a2 + hstep, voffA);
;             PG8_WAIT_V(8); PG8_WAIT_L(0); PG8_BAR; PG8_MMA(0, 0, At, B0); PG8_MMA(0, 1, At, B1); PG8_BAR; PG8_SCHED;
;             PG8_LDA(At, 1, 1); PG8_STAGE(PG8_SB(1, 0), b3, voffB); PG8_STAGE(PG8_SB(1, 1), b3 + hstep, voffB); PG8_STAGE(PG8_SA(1, 0), a3, voffA);
;             PG8_WAIT_V(8); PG8_WAIT_L(0); PG8_BAR; PG8_MMA(1, 0, At, B0); PG8_MMA(1, 1, At, B1); PG8_BAR; PG8_SCHED;
	s_add_i32 s70, 0, 0x18000
	s_add_i32 s71, 0, 0x1c000
	v_add_u32_e32 v140, s70, v170
	v_add_u32_e32 v159, s71, v170
	ds_read_b128 v[128:131], v140
	ds_read_b128 v[132:135], v140 offset:1024
	ds_read_b128 v[136:139], v140 offset:2048
	ds_read_b128 v[140:143], v140 offset:3072
	ds_read_b128 v[172:175], v159
	ds_read_b128 v[176:179], v159 offset:1024
	ds_read_b128 v[180:183], v159 offset:2048
	ds_read_b128 v[184:187], v159 offset:3072
	s_add_u32 s44, s44, 0x40000
	s_addc_u32 s45, s45, 0
	s_mov_b32 m0, s53
	ds_read_b128 v[188:191], v157 offset:32768
	ds_read_b128 v[192:195], v157 offset:33792
	ds_read_b128 v[198:201], v157 offset:34816
	ds_read_b128 v[202:205], v157 offset:35840
	ds_read_b128 v[206:209], v157 offset:36864
	ds_read_b128 v[210:213], v157 offset:37888
	ds_read_b128 v[214:217], v157 offset:38912
	ds_read_b128 v[218:221], v157 offset:39936
	global_load_lds_dwordx4 v144, s[44:45]
	s_mov_b32 m0, s54
	s_nop 0
	global_load_lds_dwordx4 v148, s[44:45]
	s_waitcnt vmcnt(8)
	s_waitcnt lgkmcnt(0)
	s_barrier
	v_mfma_f32_16x16x32_bf16 v[124:127], v[128:131], v[188:191], v[124:127]
	v_mfma_f32_16x16x32_bf16 v[120:123], v[136:139], v[188:191], v[120:123]
	v_mfma_f32_16x16x32_bf16 v[108:111], v[128:131], v[198:201], v[108:111]
	v_mfma_f32_16x16x32_bf16 v[104:107], v[136:139], v[198:201], v[104:107]
	v_mfma_f32_16x16x32_bf16 v[96:99], v[128:131], v[206:209], v[96:99]
	v_mfma_f32_16x16x32_bf16 v[88:91], v[136:139], v[206:209], v[88:91]
	v_mfma_f32_16x16x32_bf16 v[80:83], v[128:131], v[214:217], v[80:83]
	v_mfma_f32_16x16x32_bf16 v[72:75], v[136:139], v[214:217], v[72:75]
	v_mfma_f32_16x16x32_bf16 v[124:127], v[132:135], v[192:195], v[124:127]
	v_mfma_f32_16x16x32_bf16 v[120:123], v[140:143], v[192:195], v[120:123]
	v_mfma_f32_16x16x32_bf16 v[108:111], v[132:135], v[202:205], v[108:111]
	v_mfma_f32_16x16x32_bf16 v[104:107], v[140:143], v[202:205], v[104:107]
	v_mfma_f32_16x16x32_bf16 v[96:99], v[132:135], v[210:213], v[96:99]
	v_mfma_f32_16x16x32_bf16 v[88:91], v[140:143], v[210:213], v[88:91]
	v_mfma_f32_16x16x32_bf16 v[80:83], v[132:135], v[218:221], v[80:83]
	v_mfma_f32_16x16x32_bf16 v[72:75], v[140:143], v[218:221], v[72:75]
	v_mfma_f32_16x16x32_bf16 v[116:119], v[172:175], v[188:191], v[116:119]
	v_mfma_f32_16x16x32_bf16 v[112:115], v[180:183], v[188:191], v[112:115]
	v_mfma_f32_16x16x32_bf16 v[100:103], v[172:175], v[198:201], v[100:103]
	v_mfma_f32_16x16x32_bf16 v[92:95], v[180:183], v[198:201], v[92:95]
	v_mfma_f32_16x16x32_bf16 v[84:87], v[172:175], v[206:209], v[84:87]
	v_mfma_f32_16x16x32_bf16 v[76:79], v[180:183], v[206:209], v[76:79]
	v_mfma_f32_16x16x32_bf16 v[68:71], v[172:175], v[214:217], v[68:71]
	v_mfma_f32_16x16x32_bf16 v[64:67], v[180:183], v[214:217], v[64:67]
	v_mfma_f32_16x16x32_bf16 v[116:119], v[176:179], v[192:195], v[116:119]
	v_mfma_f32_16x16x32_bf16 v[112:115], v[184:187], v[192:195], v[112:115]
	v_mfma_f32_16x16x32_bf16 v[100:103], v[176:179], v[202:205], v[100:103]
	v_mfma_f32_16x16x32_bf16 v[92:95], v[184:187], v[202:205], v[92:95]
	v_mfma_f32_16x16x32_bf16 v[84:87], v[176:179], v[210:213], v[84:87]
	v_mfma_f32_16x16x32_bf16 v[76:79], v[184:187], v[210:213], v[76:79]
	v_mfma_f32_16x16x32_bf16 v[68:71], v[176:179], v[218:221], v[68:71]
	v_mfma_f32_16x16x32_bf16 v[64:67], v[184:187], v[218:221], v[64:67]
	s_barrier
	s_add_i32 s44, s70, s51
	s_mov_b32 m0, s44
	ds_read_b128 v[188:191], v157 offset:49152
	ds_read_b128 v[192:195], v157 offset:50176
	ds_read_b128 v[198:201], v157 offset:51200
	ds_read_b128 v[202:205], v157 offset:52224
	ds_read_b128 v[206:209], v157 offset:53248
	ds_read_b128 v[210:213], v157 offset:54272
	ds_read_b128 v[214:217], v157 offset:55296
	ds_read_b128 v[218:221], v157 offset:56320
	global_load_lds_dwordx4 v146, s[98:99]
	s_add_i32 m0, s44, 0x2000
	s_add_u32 s38, s38, 0x40080
	s_addc_u32 s39, s39, 0
	s_add_i32 s44, s71, s51
	global_load_lds_dwordx4 v150, s[98:99]
	s_mov_b32 m0, s44
	s_nop 0
	global_load_lds_dwordx4 v146, s[38:39]
	s_add_i32 m0, s44, 0x2000
	s_nop 0
	global_load_lds_dwordx4 v150, s[38:39]
	s_mov_b32 m0, s58
	s_nop 0
	global_load_lds_dwordx4 v144, s[100:101]
	s_mov_b32 m0, s59
	s_nop 0
	global_load_lds_dwordx4 v148, s[100:101]
	s_waitcnt vmcnt(8)
	s_waitcnt lgkmcnt(0)
	s_barrier
	v_mfma_f32_16x16x32_bf16 v[60:63], v[128:131], v[188:191], v[60:63]
	v_mfma_f32_16x16x32_bf16 v[56:59], v[136:139], v[188:191], v[56:59]
	v_mfma_f32_16x16x32_bf16 v[48:51], v[128:131], v[198:201], v[48:51]
	v_mfma_f32_16x16x32_bf16 v[40:43], v[136:139], v[198:201], v[40:43]
	v_mfma_f32_16x16x32_bf16 v[32:35], v[128:131], v[206:209], v[32:35]
	v_mfma_f32_16x16x32_bf16 v[24:27], v[136:139], v[206:209], v[24:27]
	v_mfma_f32_16x16x32_bf16 v[16:19], v[128:131], v[214:217], v[16:19]
	v_mfma_f32_16x16x32_bf16 v[8:11], v[136:139], v[214:217], v[8:11]
	v_mfma_f32_16x16x32_bf16 v[60:63], v[132:135], v[192:195], v[60:63]
	v_mfma_f32_16x16x32_bf16 v[56:59], v[140:143], v[192:195], v[56:59]
	v_mfma_f32_16x16x32_bf16 v[48:51], v[132:135], v[202:205], v[48:51]
	v_mfma_f32_16x16x32_bf16 v[40:43], v[140:143], v[202:205], v[40:43]
	v_mfma_f32_16x16x32_bf16 v[32:35], v[132:135], v[210:213], v[32:35]
	v_mfma_f32_16x16x32_bf16 v[24:27], v[140:143], v[210:213], v[24:27]
	v_mfma_f32_16x16x32_bf16 v[16:19], v[132:135], v[218:221], v[16:19]
	v_mfma_f32_16x16x32_bf16 v[8:11], v[140:143], v[218:221], v[8:11]
	v_mfma_f32_16x16x32_bf16 v[52:55], v[172:175], v[188:191], v[52:55]
	v_mfma_f32_16x16x32_bf16 v[44:47], v[180:183], v[188:191], v[44:47]
	v_mfma_f32_16x16x32_bf16 v[36:39], v[172:175], v[198:201], v[36:39]
	v_mfma_f32_16x16x32_bf16 v[28:31], v[180:183], v[198:201], v[28:31]
	v_mfma_f32_16x16x32_bf16 v[20:23], v[172:175], v[206:209], v[20:23]
	v_mfma_f32_16x16x32_bf16 v[12:15], v[180:183], v[206:209], v[12:15]
	v_mfma_f32_16x16x32_bf16 v[4:7], v[172:175], v[214:217], v[4:7]
	v_mfma_f32_16x16x32_bf16 v[0:3], v[180:183], v[214:217], v[0:3]
	v_mfma_f32_16x16x32_bf16 v[52:55], v[176:179], v[192:195], v[52:55]
	v_mfma_f32_16x16x32_bf16 v[44:47], v[184:187], v[192:195], v[44:47]
	v_mfma_f32_16x16x32_bf16 v[36:39], v[176:179], v[202:205], v[36:39]
	v_mfma_f32_16x16x32_bf16 v[28:31], v[184:187], v[202:205], v[28:31]
	v_mfma_f32_16x16x32_bf16 v[20:23], v[176:179], v[210:213], v[20:23]
	v_mfma_f32_16x16x32_bf16 v[12:15], v[184:187], v[210:213], v[12:15]
	v_mfma_f32_16x16x32_bf16 v[4:7], v[176:179], v[218:221], v[4:7]
	v_mfma_f32_16x16x32_bf16 v[0:3], v[184:187], v[218:221], v[0:3]
	s_barrier
	s_add_i32 s69, s69, 2
	s_add_u32 s20, s20, 0x100
	s_addc_u32 s21, s21, 0
	s_add_u32 s67, s67, 0x100
	s_addc_u32 s68, s68, 0
	s_cmp_gt_u32 s69, 13

; #define PG8_STAGE(bufoff, gbase, voff) do { _Pragma("unroll") for (int _i = 0; _i < 2; ++_i) \
;         __builtin_amdgcn_global_load_lds((const unsigned*)((const char*)(gbase) + (voff)[_i]), (PG8_LAS unsigned*)(lds + (bufoff) + ldsw + _i * 8192), 16, 0, 0); } while (0)
; #define PG8_LDA(dst, b, h) do { _Pragma("unroll") for (int m = 0; m < 4; ++m) _Pragma("unroll") for (int k = 0; k < 2; ++k) dst[m][k] = *(const PG8_LAS bf16x8*)(lds + PG8_SA(b, h) + aoff + m * 2048 + k * 1024); } while (0)
; #define PG8_LDB(dst, b, h) do { _Pragma("unroll") for (int n = 0; n < 2; ++n) _Pragma("unroll") for (int k = 0; k < 2; ++k) dst[n][k] = *(const PG8_LAS bf16x8*)(lds + PG8_SB(b, h) + boff + n * 2048 + k * 1024); } while (0)
; #define PG8_MMA(ai, bj, At, Bt) do { __builtin_amdgcn_s_setprio(1); _Pragma("unroll") for (int m = 0; m < 4; ++m) _Pragma("unroll") for (int n = 0; n < 2; ++n) _Pragma("unroll") for (int k = 0; k < 2; ++k) \
;         acc[ai][bj][m][n] = __builtin_amdgcn_mfma_f32_16x16x32_bf16(Bt[n][k], At[m][k], acc[ai][bj][m][n], 0, 0, 0); __builtin_amdgcn_s_setprio(0); } while (0)
; #define PG8_BAR __builtin_amdgcn_s_barrier()
; template <class Epi, class Sched, bool ALIGN_EPI = false, bool SP2 = false>
; __device__ __forceinline__ void gemm_phase(PG8_LAS unsigned char* lds, const Gemm g, const Sched& S, const Epi& E) {
;     ...
;         const bool has_next = S.next(ui + 1, nxt);
;         const char* nA = has_next ? (const char*)g.A + (size_t)nxt.pm * tstep : cA; const char* nB = has_next ? (const char*)g.Bt + (size_t)nxt.pn * tstep : cB;
;         for (int t = 0; t < nt; t += 2) {
;             const bool last = (t == nt - 2);
;             const char* a1 = cA + (size_t)(t + 1) * kstep;
;             const char* a2 = last ? nA : cA + (size_t)(t + 2) * kstep; const char* b2 = last ? nB : cB + (size_t)(t + 2) * kstep;
;             const char* a3 = a2 + kstep; const char* b3 = b2 + kstep;
;             if (last && has_next) S.a_ready(nxt);
;             if constexpr (SP2) {
;             PG8_LDB(B0, 0, 0); PG8_LDB(B1, 0, 1); PG8_SCHED; PG8_LDA(At, 0, 0); PG8_STAGE(PG8_SA(1, 1), a1 + hstep, voffA);
;             PG8_WAIT_V(8); PG8_WAIT_L(0); PG8_BAR; PG8_MMA(0, 0, At, B0); PG8_MMA(0, 1, At, B1); PG8_BAR; PG8_SCHED;
;             PG8_LDA(At, 0, 1); PG8_STAGE(PG8_SB(0, 0), b2, voffB); PG8_STAGE(PG8_SB(0, 1), b2 + hstep, voffB); PG8_STAGE(PG8_SA(0, 0), a2, voffA);
.LBB0_1634:
	s_ashr_i32 s47, s46, 31
	s_lshl_b64 s[48:49], s[46:47], 19
	s_add_u32 s48, s18, s48
	s_addc_u32 s49, s19, s49
	s_and_b64 s[50:51], s[6:7], exec
	s_cselect_b32 s35, s49, s21
	s_cselect_b32 s47, s48, s20
	s_ashr_i32 s45, s44, 31
	s_lshl_b64 s[50:51], s[44:45], 19
	s_add_u32 s50, s3, s50
	s_addc_u32 s51, s33, s51
	s_and_b64 s[56:57], s[6:7], exec
	s_cselect_b32 s45, s51, s55
	s_cselect_b32 s73, s50, s54
	s_add_u32 s20, s20, 0x40080
	s_addc_u32 s21, s21, 0
	s_add_u32 s74, s54, 0x100
	s_addc_u32 s75, s55, 0
	s_mov_b32 s76, -2
	s_waitcnt lgkmcnt(0)
	ds_read_b128 v[96:99], v223
	ds_read_b128 v[108:111], v223 offset:1024
	ds_read_b128 v[120:123], v223 offset:2048
	ds_read_b128 v[128:131], v223 offset:3072
	ds_read_b128 v[144:147], v224
	ds_read_b128 v[148:151], v224 offset:1024
	ds_read_b128 v[152:155], v224 offset:2048
	ds_read_b128 v[156:159], v224 offset:3072
	ds_read_b128 v[160:163], v225
	ds_read_b128 v[164:167], v225 offset:1024
	ds_read_b128 v[168:171], v225 offset:2048
	ds_read_b128 v[172:175], v225 offset:3072
	ds_read_b128 v[176:179], v225 offset:4096
	ds_read_b128 v[180:183], v225 offset:5120
	ds_read_b128 v[202:205], v225 offset:6144
	ds_read_b128 v[206:209], v225 offset:7168
	s_add_u32 s54, s20, 0xfffc0080
	s_addc_u32 s55, s21, -1
	s_cmp_eq_u32 s76, 12
	s_cselect_b32 s57, s35, s55
	s_cselect_b32 s56, s47, s54
	s_cselect_b32 s55, s45, s75
	s_cselect_b32 s54, s73, s74
	s_add_i32 m0, s53, 0xc000
	global_load_lds_dwordx4 v192, s[20:21]
	s_add_i32 m0, s53, 0xe000
	s_nop 0
	global_load_lds_dwordx4 v194, s[20:21]
	s_waitcnt vmcnt(8)
	s_waitcnt lgkmcnt(0)
	s_barrier
	v_mfma_f32_16x16x32_bf16 v[140:143], v[96:99], v[160:163], 0
	v_mfma_f32_16x16x32_bf16 v[136:139], v[120:123], v[160:163], 0
	v_mfma_f32_16x16x32_bf16 v[116:119], v[96:99], v[168:171], 0
	v_mfma_f32_16x16x32_bf16 v[112:115], v[120:123], v[168:171], 0
	v_mfma_f32_16x16x32_bf16 v[92:95], v[96:99], v[176:179], 0
	v_mfma_f32_16x16x32_bf16 v[88:91], v[120:123], v[176:179], 0
	v_mfma_f32_16x16x32_bf16 v[76:79], v[96:99], v[202:205], 0
	v_mfma_f32_16x16x32_bf16 v[72:75], v[120:123], v[202:205], 0
	v_mfma_f32_16x16x32_bf16 v[140:143], v[108:111], v[164:167], v[140:143]
	v_mfma_f32_16x16x32_bf16 v[136:139], v[128:131], v[164:167], v[136:139]
	v_mfma_f32_16x16x32_bf16 v[116:119], v[108:111], v[172:175], v[116:119]
	v_mfma_f32_16x16x32_bf16 v[112:115], v[128:131], v[172:175], v[112:115]
	v_mfma_f32_16x16x32_bf16 v[92:95], v[108:111], v[180:183], v[92:95]
	v_mfma_f32_16x16x32_bf16 v[88:91], v[128:131], v[180:183], v[88:91]
	v_mfma_f32_16x16x32_bf16 v[76:79], v[108:111], v[206:209], v[76:79]
	v_mfma_f32_16x16x32_bf16 v[72:75], v[128:131], v[206:209], v[72:75]
	v_mfma_f32_16x16x32_bf16 v[132:135], v[144:147], v[160:163], 0
	v_mfma_f32_16x16x32_bf16 v[124:127], v[152:155], v[160:163], 0
	v_mfma_f32_16x16x32_bf16 v[104:107], v[144:147], v[168:171], 0
	v_mfma_f32_16x16x32_bf16 v[100:103], v[152:155], v[168:171], 0
	v_mfma_f32_16x16x32_bf16 v[84:87], v[144:147], v[176:179], 0
	v_mfma_f32_16x16x32_bf16 v[80:83], v[152:155], v[176:179], 0
	v_mfma_f32_16x16x32_bf16 v[68:71], v[144:147], v[202:205], 0
	v_mfma_f32_16x16x32_bf16 v[64:67], v[152:155], v[202:205], 0
	v_mfma_f32_16x16x32_bf16 v[132:135], v[148:151], v[164:167], v[132:135]
	v_mfma_f32_16x16x32_bf16 v[124:127], v[156:159], v[164:167], v[124:127]
	v_mfma_f32_16x16x32_bf16 v[104:107], v[148:151], v[172:175], v[104:107]
	v_mfma_f32_16x16x32_bf16 v[100:103], v[156:159], v[172:175], v[100:103]
	v_mfma_f32_16x16x32_bf16 v[84:87], v[148:151], v[180:183], v[84:87]
	v_mfma_f32_16x16x32_bf16 v[80:83], v[156:159], v[180:183], v[80:83]
	v_mfma_f32_16x16x32_bf16 v[68:71], v[148:151], v[206:209], v[68:71]
	v_mfma_f32_16x16x32_bf16 v[64:67], v[156:159], v[206:209], v[64:67]
	s_barrier
	s_add_i32 s77, s71, s58
	s_add_u32 s98, s54, s12
	s_addc_u32 s99, s55, s13
	s_add_u32 s100, s56, s12
	s_addc_u32 s101, s57, s13
	s_mov_b32 m0, s77
	ds_read_b128 v[160:163], v225 offset:16384
	ds_read_b128 v[164:167], v225 offset:17408
	ds_read_b128 v[168:171], v225 offset:18432
	ds_read_b128 v[172:175], v225 offset:19456
	ds_read_b128 v[176:179], v225 offset:20480
	ds_read_b128 v[180:183], v225 offset:21504
	ds_read_b128 v[202:205], v225 offset:22528
	ds_read_b128 v[206:209], v225 offset:23552
	global_load_lds_dwordx4 v186, s[54:55]
	s_add_i32 m0, s77, 0x2000
	s_add_u32 s78, s54, 0x40000
	s_addc_u32 s79, s55, 0
	s_add_i32 s77, s72, s58
	global_load_lds_dwordx4 v190, s[54:55]
	s_mov_b32 m0, s77
	s_nop 0
	global_load_lds_dwordx4 v186, s[78:79]
	s_add_i32 m0, s77, 0x2000
	s_nop 0
	global_load_lds_dwordx4 v190, s[78:79]
	s_mov_b32 m0, s53
	s_nop 0
	global_load_lds_dwordx4 v184, s[56:57]
	s_mov_b32 m0, s59
	s_nop 0
	global_load_lds_dwordx4 v188, s[56:57]
	s_waitcnt vmcnt(8)
	s_waitcnt lgkmcnt(0)
	s_barrier
; #define PG8_STAGE(bufoff, gbase, voff) do { _Pragma("unroll") for (int _i = 0; _i < 2; ++_i) \
;         __builtin_amdgcn_global_load_lds((const unsigned*)((const char*)(gbase) + (voff)[_i]), (PG8_LAS unsigned*)(lds + (bufoff) + ldsw + _i * 8192), 16, 0, 0); } while (0)
; #define PG8_LDA(dst, b, h) do { _Pragma("unroll") for (int m = 0; m < 4; ++m) _Pragma("unroll") for (int k = 0; k < 2; ++k) dst[m][k] = *(const PG8_LAS bf16x8*)(lds + PG8_SA(b, h) + aoff + m * 2048 + k * 1024); } while (0)
; #define PG8_LDB(dst, b, h) do { _Pragma("unroll") for (int n = 0; n < 2; ++n) _Pragma("unroll") for (int k = 0; k < 2; ++k) dst[n][k] = *(const PG8_LAS bf16x8*)(lds + PG8_SB(b, h) + boff + n * 2048 + k * 1024); } while (0)
; #define PG8_MMA(ai, bj, At, Bt) do { __builtin_amdgcn_s_setprio(1); _Pragma("unroll") for (int m = 0; m < 4; ++m) _Pragma("unroll") for (int n = 0; n < 2; ++n) _Pragma("unroll") for (int k = 0; k < 2; ++k) \
;         acc[ai][bj][m][n] = __builtin_amdgcn_mfma_f32_16x16x32_bf16(Bt[n][k], At[m][k], acc[ai][bj][m][n], 0, 0, 0); __builtin_amdgcn_s_setprio(0); } while (0)
; #define PG8_WAIT_V(n) asm volatile("s_waitcnt vmcnt(" #n ")" ::: "memory")
; #define PG8_WAIT_L(n) asm volatile("s_waitcnt lgkmcnt(" #n ")" ::: "memory")
; #define PG8_BAR __builtin_amdgcn_s_barrier()
; #define PG8_SCHED __builtin_amdgcn_sched_barrier(0)
; template <class Epi, class Sched, bool ALIGN_EPI = false, bool SP2 = false>
; __device__ __forceinline__ void gemm_phase(PG8_LAS unsigned char* lds, const Gemm g, const Sched& S, const Epi& E) {
;     ...
;             PG8_WAIT_V(8); PG8_WAIT_L(0); PG8_BAR; PG8_MMA(0, 0, At, B0); PG8_MMA(0, 1, At, B1); PG8_BAR; PG8_SCHED;
;             PG8_LDA(At, 0, 1); PG8_STAGE(PG8_SB(0, 0), b2, voffB); PG8_STAGE(PG8_SB(0, 1), b2 + hstep, voffB); PG8_STAGE(PG8_SA(0, 0), a2, voffA);
;             PG8_WAIT_V(8); PG8_WAIT_L(0); PG8_BAR; PG8_MMA(1, 0, At, B0); PG8_MMA(1, 1, At, B1); PG8_BAR; PG8_SCHED;
;             PG8_LDB(B0, 1, 0); PG8_LDB(B1, 1, 1); PG8_SCHED; PG8_LDA(At, 1, 0); PG8_STAGE(PG8_SA(0, 1), a2 + hstep, voffA);
;             PG8_WAIT_V(8); PG8_WAIT_L(0); PG8_BAR; PG8_MMA(0, 0, At, B0); PG8_MMA(0, 1, At, B1); PG8_BAR; PG8_SCHED;
	v_mfma_f32_16x16x32_bf16 v[60:63], v[96:99], v[160:163], 0
	v_mfma_f32_16x16x32_bf16 v[56:59], v[120:123], v[160:163], 0
	v_mfma_f32_16x16x32_bf16 v[44:47], v[96:99], v[168:171], 0
	v_mfma_f32_16x16x32_bf16 v[40:43], v[120:123], v[168:171], 0
	v_mfma_f32_16x16x32_bf16 v[28:31], v[96:99], v[176:179], 0
	v_mfma_f32_16x16x32_bf16 v[24:27], v[120:123], v[176:179], 0
	v_mfma_f32_16x16x32_bf16 v[12:15], v[96:99], v[202:205], 0
	v_mfma_f32_16x16x32_bf16 v[8:11], v[120:123], v[202:205], 0
	v_mfma_f32_16x16x32_bf16 v[60:63], v[108:111], v[164:167], v[60:63]
	v_mfma_f32_16x16x32_bf16 v[56:59], v[128:131], v[164:167], v[56:59]
	v_mfma_f32_16x16x32_bf16 v[44:47], v[108:111], v[172:175], v[44:47]
	v_mfma_f32_16x16x32_bf16 v[40:43], v[128:131], v[172:175], v[40:43]
	v_mfma_f32_16x16x32_bf16 v[28:31], v[108:111], v[180:183], v[28:31]
	v_mfma_f32_16x16x32_bf16 v[24:27], v[128:131], v[180:183], v[24:27]
	v_mfma_f32_16x16x32_bf16 v[12:15], v[108:111], v[206:209], v[12:15]
	v_mfma_f32_16x16x32_bf16 v[8:11], v[128:131], v[206:209], v[8:11]
	v_mfma_f32_16x16x32_bf16 v[52:55], v[144:147], v[160:163], 0
	v_mfma_f32_16x16x32_bf16 v[48:51], v[152:155], v[160:163], 0
	v_mfma_f32_16x16x32_bf16 v[36:39], v[144:147], v[168:171], 0
	v_mfma_f32_16x16x32_bf16 v[32:35], v[152:155], v[168:171], 0
	v_mfma_f32_16x16x32_bf16 v[20:23], v[144:147], v[176:179], 0
	v_mfma_f32_16x16x32_bf16 v[16:19], v[152:155], v[176:179], 0
	v_mfma_f32_16x16x32_bf16 v[4:7], v[144:147], v[202:205], 0
	v_mfma_f32_16x16x32_bf16 v[0:3], v[152:155], v[202:205], 0
	v_mfma_f32_16x16x32_bf16 v[52:55], v[148:151], v[164:167], v[52:55]
	v_mfma_f32_16x16x32_bf16 v[48:51], v[156:159], v[164:167], v[48:51]
	v_mfma_f32_16x16x32_bf16 v[36:39], v[148:151], v[172:175], v[36:39]
	v_mfma_f32_16x16x32_bf16 v[32:35], v[156:159], v[172:175], v[32:35]
	v_mfma_f32_16x16x32_bf16 v[20:23], v[148:151], v[180:183], v[20:23]
	v_mfma_f32_16x16x32_bf16 v[16:19], v[156:159], v[180:183], v[16:19]
	v_mfma_f32_16x16x32_bf16 v[4:7], v[148:151], v[206:209], v[4:7]
	v_mfma_f32_16x16x32_bf16 v[0:3], v[156:159], v[206:209], v[0:3]
	s_barrier
	s_add_i32 s77, 0, 0x18000
	s_add_i32 s78, 0, 0x1c000
	v_add_u32_e32 v128, s77, v221
	v_add_u32_e32 v156, s78, v221
	ds_read_b128 v[96:99], v128
	ds_read_b128 v[108:111], v128 offset:1024
	ds_read_b128 v[120:123], v128 offset:2048
	ds_read_b128 v[128:131], v128 offset:3072
	ds_read_b128 v[144:147], v156
	ds_read_b128 v[148:151], v156 offset:1024
	ds_read_b128 v[152:155], v156 offset:2048
	ds_read_b128 v[156:159], v156 offset:3072
	s_add_u32 s56, s56, 0x40000
	s_addc_u32 s57, s57, 0
	s_mov_b32 m0, s60
	ds_read_b128 v[160:163], v225 offset:32768
	ds_read_b128 v[164:167], v225 offset:33792
	ds_read_b128 v[168:171], v225 offset:34816
	ds_read_b128 v[172:175], v225 offset:35840
	ds_read_b128 v[176:179], v225 offset:36864
	ds_read_b128 v[180:183], v225 offset:37888
	ds_read_b128 v[202:205], v225 offset:38912
	ds_read_b128 v[206:209], v225 offset:39936
	global_load_lds_dwordx4 v184, s[56:57]
	s_mov_b32 m0, s61
	s_nop 0
	global_load_lds_dwordx4 v188, s[56:57]
	s_waitcnt vmcnt(8)
	s_waitcnt lgkmcnt(0)
	s_barrier
	v_mfma_f32_16x16x32_bf16 v[140:143], v[96:99], v[160:163], v[140:143]
	v_mfma_f32_16x16x32_bf16 v[136:139], v[120:123], v[160:163], v[136:139]
	v_mfma_f32_16x16x32_bf16 v[116:119], v[96:99], v[168:171], v[116:119]
	v_mfma_f32_16x16x32_bf16 v[112:115], v[120:123], v[168:171], v[112:115]
	v_mfma_f32_16x16x32_bf16 v[92:95], v[96:99], v[176:179], v[92:95]
	v_mfma_f32_16x16x32_bf16 v[88:91], v[120:123], v[176:179], v[88:91]
	v_mfma_f32_16x16x32_bf16 v[76:79], v[96:99], v[202:205], v[76:79]
	v_mfma_f32_16x16x32_bf16 v[72:75], v[120:123], v[202:205], v[72:75]
	v_mfma_f32_16x16x32_bf16 v[140:143], v[108:111], v[164:167], v[140:143]
	v_mfma_f32_16x16x32_bf16 v[136:139], v[128:131], v[164:167], v[136:139]
	v_mfma_f32_16x16x32_bf16 v[116:119], v[108:111], v[172:175], v[116:119]
	v_mfma_f32_16x16x32_bf16 v[112:115], v[128:131], v[172:175], v[112:115]
	v_mfma_f32_16x16x32_bf16 v[92:95], v[108:111], v[180:183], v[92:95]
	v_mfma_f32_16x16x32_bf16 v[88:91], v[128:131], v[180:183], v[88:91]
	v_mfma_f32_16x16x32_bf16 v[76:79], v[108:111], v[206:209], v[76:79]
	v_mfma_f32_16x16x32_bf16 v[72:75], v[128:131], v[206:209], v[72:75]
	v_mfma_f32_16x16x32_bf16 v[132:135], v[144:147], v[160:163], v[132:135]
	v_mfma_f32_16x16x32_bf16 v[124:127], v[152:155], v[160:163], v[124:127]
	v_mfma_f32_16x16x32_bf16 v[104:107], v[144:147], v[168:171], v[104:107]
	v_mfma_f32_16x16x32_bf16 v[100:103], v[152:155], v[168:171], v[100:103]
	v_mfma_f32_16x16x32_bf16 v[84:87], v[144:147], v[176:179], v[84:87]
	v_mfma_f32_16x16x32_bf16 v[80:83], v[152:155], v[176:179], v[80:83]
	v_mfma_f32_16x16x32_bf16 v[68:71], v[144:147], v[202:205], v[68:71]
	v_mfma_f32_16x16x32_bf16 v[64:67], v[152:155], v[202:205], v[64:67]
	v_mfma_f32_16x16x32_bf16 v[132:135], v[148:151], v[164:167], v[132:135]
	v_mfma_f32_16x16x32_bf16 v[124:127], v[156:159], v[164:167], v[124:127]
	v_mfma_f32_16x16x32_bf16 v[104:107], v[148:151], v[172:175], v[104:107]
	v_mfma_f32_16x16x32_bf16 v[100:103], v[156:159], v[172:175], v[100:103]
	v_mfma_f32_16x16x32_bf16 v[84:87], v[148:151], v[180:183], v[84:87]
	v_mfma_f32_16x16x32_bf16 v[80:83], v[156:159], v[180:183], v[80:83]
	v_mfma_f32_16x16x32_bf16 v[68:71], v[148:151], v[206:209], v[68:71]
	v_mfma_f32_16x16x32_bf16 v[64:67], v[156:159], v[206:209], v[64:67]
	s_barrier
; #define PG8_STAGE(bufoff, gbase, voff) do { _Pragma("unroll") for (int _i = 0; _i < 2; ++_i) \
;         __builtin_amdgcn_global_load_lds((const unsigned*)((const char*)(gbase) + (voff)[_i]), (PG8_LAS unsigned*)(lds + (bufoff) + ldsw + _i * 8192), 16, 0, 0); } while (0)
; #define PG8_LDA(dst, b, h) do { _Pragma("unroll") for (int m = 0; m < 4; ++m) _Pragma("unroll") for (int k = 0; k < 2; ++k) dst[m][k] = *(const PG8_LAS bf16x8*)(lds + PG8_SA(b, h) + aoff + m * 2048 + k * 1024); } while (0)
; #define PG8_MMA(ai, bj, At, Bt) do { __builtin_amdgcn_s_setprio(1); _Pragma("unroll") for (int m = 0; m < 4; ++m) _Pragma("unroll") for (int n = 0; n < 2; ++n) _Pragma("unroll") for (int k = 0; k < 2; ++k) \
;         acc[ai][bj][m][n] = __builtin_amdgcn_mfma_f32_16x16x32_bf16(Bt[n][k], At[m][k], acc[ai][bj][m][n], 0, 0, 0); __builtin_amdgcn_s_setprio(0); } while (0)
; #define PG8_WAIT_V(n) asm volatile("s_waitcnt vmcnt(" #n ")" ::: "memory")
; #define PG8_WAIT_L(n) asm volatile("s_waitcnt lgkmcnt(" #n ")" ::: "memory")
; #define PG8_BAR __builtin_amdgcn_s_barrier()
; #define PG8_SCHED __builtin_amdgcn_sched_barrier(0)
; template <class Epi, class Sched, bool ALIGN_EPI = false, bool SP2 = false>
; __device__ __forceinline__ void gemm_phase(PG8_LAS unsigned char* lds, const Gemm g, const Sched& S, const Epi& E) {
;     ...
;         for (int t = 0; t < nt; t += 2) {
;     ...
;             PG8_WAIT_V(8); PG8_WAIT_L(0); PG8_BAR; PG8_MMA(0, 0, At, B0); PG8_MMA(0, 1, At, B1); PG8_BAR; PG8_SCHED;
;             PG8_LDA(At, 1, 1); PG8_STAGE(PG8_SB(1, 0), b3, voffB); PG8_STAGE(PG8_SB(1, 1), b3 + hstep, voffB); PG8_STAGE(PG8_SA(1, 0), a3, voffA);
;             PG8_WAIT_V(8); PG8_WAIT_L(0); PG8_BAR; PG8_MMA(1, 0, At, B0); PG8_MMA(1, 1, At, B1); PG8_BAR; PG8_SCHED;
	s_add_i32 s56, s77, s58
	s_mov_b32 m0, s56
	ds_read_b128 v[160:163], v225 offset:49152
	ds_read_b128 v[164:167], v225 offset:50176
	ds_read_b128 v[168:171], v225 offset:51200
	ds_read_b128 v[172:175], v225 offset:52224
	ds_read_b128 v[176:179], v225 offset:53248
	ds_read_b128 v[180:183], v225 offset:54272
	ds_read_b128 v[202:205], v225 offset:55296
	ds_read_b128 v[206:209], v225 offset:56320
	global_load_lds_dwordx4 v186, s[98:99]
	s_add_i32 m0, s56, 0x2000
	s_add_u32 s54, s54, 0x40080
	s_addc_u32 s55, s55, 0
	s_add_i32 s56, s78, s58
	global_load_lds_dwordx4 v190, s[98:99]
	s_mov_b32 m0, s56
	s_nop 0
	global_load_lds_dwordx4 v186, s[54:55]
	s_add_i32 m0, s56, 0x2000
	s_nop 0
	global_load_lds_dwordx4 v190, s[54:55]
	s_mov_b32 m0, s66
	s_nop 0
	global_load_lds_dwordx4 v184, s[100:101]
	s_mov_b32 m0, s67
	s_nop 0
	global_load_lds_dwordx4 v188, s[100:101]
	s_waitcnt vmcnt(8)
	s_waitcnt lgkmcnt(0)
	s_barrier
	v_mfma_f32_16x16x32_bf16 v[60:63], v[96:99], v[160:163], v[60:63]
	v_mfma_f32_16x16x32_bf16 v[56:59], v[120:123], v[160:163], v[56:59]
	v_mfma_f32_16x16x32_bf16 v[44:47], v[96:99], v[168:171], v[44:47]
	v_mfma_f32_16x16x32_bf16 v[40:43], v[120:123], v[168:171], v[40:43]
	v_mfma_f32_16x16x32_bf16 v[28:31], v[96:99], v[176:179], v[28:31]
	v_mfma_f32_16x16x32_bf16 v[24:27], v[120:123], v[176:179], v[24:27]
	v_mfma_f32_16x16x32_bf16 v[12:15], v[96:99], v[202:205], v[12:15]
	v_mfma_f32_16x16x32_bf16 v[8:11], v[120:123], v[202:205], v[8:11]
	v_mfma_f32_16x16x32_bf16 v[60:63], v[108:111], v[164:167], v[60:63]
	v_mfma_f32_16x16x32_bf16 v[56:59], v[128:131], v[164:167], v[56:59]
	v_mfma_f32_16x16x32_bf16 v[44:47], v[108:111], v[172:175], v[44:47]
	v_mfma_f32_16x16x32_bf16 v[40:43], v[128:131], v[172:175], v[40:43]
	v_mfma_f32_16x16x32_bf16 v[28:31], v[108:111], v[180:183], v[28:31]
	v_mfma_f32_16x16x32_bf16 v[24:27], v[128:131], v[180:183], v[24:27]
	v_mfma_f32_16x16x32_bf16 v[12:15], v[108:111], v[206:209], v[12:15]
	v_mfma_f32_16x16x32_bf16 v[8:11], v[128:131], v[206:209], v[8:11]
	v_mfma_f32_16x16x32_bf16 v[52:55], v[144:147], v[160:163], v[52:55]
	v_mfma_f32_16x16x32_bf16 v[48:51], v[152:155], v[160:163], v[48:51]
	v_mfma_f32_16x16x32_bf16 v[36:39], v[144:147], v[168:171], v[36:39]
	v_mfma_f32_16x16x32_bf16 v[32:35], v[152:155], v[168:171], v[32:35]
	v_mfma_f32_16x16x32_bf16 v[20:23], v[144:147], v[176:179], v[20:23]
	v_mfma_f32_16x16x32_bf16 v[16:19], v[152:155], v[176:179], v[16:19]
	v_mfma_f32_16x16x32_bf16 v[4:7], v[144:147], v[202:205], v[4:7]
	v_mfma_f32_16x16x32_bf16 v[0:3], v[152:155], v[202:205], v[0:3]
	v_mfma_f32_16x16x32_bf16 v[52:55], v[148:151], v[164:167], v[52:55]
	v_mfma_f32_16x16x32_bf16 v[48:51], v[156:159], v[164:167], v[48:51]
	v_mfma_f32_16x16x32_bf16 v[36:39], v[148:151], v[172:175], v[36:39]
	v_mfma_f32_16x16x32_bf16 v[32:35], v[156:159], v[172:175], v[32:35]
	v_mfma_f32_16x16x32_bf16 v[20:23], v[148:151], v[180:183], v[20:23]
	v_mfma_f32_16x16x32_bf16 v[16:19], v[156:159], v[180:183], v[16:19]
	v_mfma_f32_16x16x32_bf16 v[4:7], v[148:151], v[206:209], v[4:7]
	v_mfma_f32_16x16x32_bf16 v[0:3], v[156:159], v[206:209], v[0:3]
	s_barrier
	s_add_i32 s76, s76, 2
	s_add_u32 s20, s20, 0x100
	s_addc_u32 s21, s21, 0
	s_add_u32 s74, s74, 0x100
	s_addc_u32 s75, s75, 0
	s_cmp_gt_u32 s76, 13

; #define PG8_STAGE(bufoff, gbase, voff) do { _Pragma("unroll") for (int _i = 0; _i < 2; ++_i) \
;         __builtin_amdgcn_global_load_lds((const unsigned*)((const char*)(gbase) + (voff)[_i]), (PG8_LAS unsigned*)(lds + (bufoff) + ldsw + _i * 8192), 16, 0, 0); } while (0)
; #define PG8_LDA(dst, b, h) do { _Pragma("unroll") for (int m = 0; m < 4; ++m) _Pragma("unroll") for (int k = 0; k < 2; ++k) dst[m][k] = *(const PG8_LAS bf16x8*)(lds + PG8_SA(b, h) + aoff + m * 2048 + k * 1024); } while (0)
; #define PG8_WAIT_V(n) asm volatile("s_waitcnt vmcnt(" #n ")" ::: "memory")
; #define PG8_BAR __builtin_amdgcn_s_barrier()
;     __host__ __device__ bool next(int i, Unit& u) const {
;         const long L = (long)i * G + c; if (L >= nwg) return false;
;         int wgid = (int)L; { const int q = nwg / NXCD, r = nwg % NXCD, xcd = wgid % NXCD, off = wgid / NXCD; wgid = (xcd < r ? xcd * (q + 1) : r * (q + 1) + (xcd - r) * q) + off; }
;         const int nig = WGM * nN, gid = wgid / nig, fm = gid * WGM, gsz = (nM - fm) < WGM ? (nM - fm) : WGM;
;         u.pm = fm + ((wgid % nig) % gsz); u.pn = (wgid % nig) / gsz; return true;
; template <class Epi, class Sched, bool ALIGN_EPI = false, bool SP2 = false>
; __device__ __forceinline__ void gemm_phase(PG8_LAS unsigned char* lds, const Gemm g, const Sched& S, const Epi& E) {
;     ...
;         const bool has_next = S.next(ui + 1, nxt);
;         const char* nA = has_next ? (const char*)g.A + (size_t)nxt.pm * tstep : cA; const char* nB = has_next ? (const char*)g.Bt + (size_t)nxt.pn * tstep : cB;
;         for (int t = 0; t < nt; t += 2) {
;             const bool last = (t == nt - 2);
;             const char* a1 = cA + (size_t)(t + 1) * kstep;
;             const char* a2 = last ? nA : cA + (size_t)(t + 2) * kstep; const char* b2 = last ? nB : cB + (size_t)(t + 2) * kstep;
;             const char* a3 = a2 + kstep; const char* b3 = b2 + kstep;
;             if (last && has_next) S.a_ready(nxt);
;             if constexpr (SP2) {
;             PG8_LDB(B0, 0, 0); PG8_LDB(B1, 0, 1); PG8_SCHED; PG8_LDA(At, 0, 0); PG8_STAGE(PG8_SA(1, 1), a1 + hstep, voffA);
;             PG8_WAIT_V(8); PG8_WAIT_L(0); PG8_BAR; PG8_MMA(0, 0, At, B0); PG8_MMA(0, 1, At, B1); PG8_BAR; PG8_SCHED;
;             PG8_LDA(At, 0, 1); PG8_STAGE(PG8_SB(0, 0), b2, voffB); PG8_STAGE(PG8_SB(0, 1), b2 + hstep, voffB); PG8_STAGE(PG8_SA(0, 0), a2, voffA);
.LBB0_1737:
	ds_read_b128 v[154:157], v150
	ds_read_b128 v[158:161], v150 offset:1024
	ds_read_b128 v[162:165], v150 offset:2048
	ds_read_b128 v[166:169], v150 offset:3072
	ds_read_b128 v[170:173], v151
	ds_read_b128 v[174:177], v151 offset:1024
	ds_read_b128 v[178:181], v151 offset:2048
	ds_read_b128 v[182:185], v151 offset:3072
	ds_read_b128 v[186:189], v152
	ds_read_b128 v[190:193], v152 offset:1024
	ds_read_b128 v[198:201], v152 offset:2048
	ds_read_b128 v[202:205], v152 offset:3072
	ds_read_b128 v[206:209], v152 offset:4096
	ds_read_b128 v[210:213], v152 offset:5120
	ds_read_b128 v[214:217], v152 offset:6144
	ds_read_b128 v[218:221], v152 offset:7168
	s_add_i32 s55, s55, 1
	s_mul_i32 s4, s55, s33
	s_mul_hi_u32 s5, s55, s44
	s_add_i32 s5, s5, s4
	s_mul_i32 s4, s55, s44
	s_add_u32 s16, s4, s2
	s_addc_u32 s17, s5, s3
	v_cmp_gt_i64_e32 vcc, s[16:17], v[142:143]
	v_cmp_lt_i64_e64 s[4:5], s[16:17], v[140:141]
	s_cbranch_vccnz .LBB0_1739
	s_ashr_i32 s12, s16, 31
	s_lshr_b32 s12, s12, 29
	s_add_i32 s12, s16, s12
	s_ashr_i32 s13, s12, 3
	s_and_b32 s12, s12, -8
	s_sub_i32 s12, s16, s12
	s_cmp_lt_i32 s12, 0
	s_cselect_b32 s14, s51, 0x160
	s_mul_i32 s12, s14, s12
	s_add_i32 s12, s12, s13
	s_mul_hi_i32 s13, s12, 0x2e8ba2e9
	s_lshr_b32 s14, s13, 31
	s_ashr_i32 s13, s13, 5
	s_add_i32 s13, s13, s14
	s_lshl_b32 s14, s13, 3
	s_sub_i32 s15, 0x80, s14
	s_min_i32 s15, s15, 8
	s_mulk_i32 s13, 0xb0
	s_sub_i32 s13, s12, s13
	s_lshr_b32 s12, s13, 3
	s_mul_i32 s15, s12, s15
	s_sub_i32 s13, s13, s15
	s_add_i32 s14, s13, s14
.LBB0_1739:
	s_ashr_i32 s15, s14, 31
	s_lshl_b64 s[16:17], s[14:15], 19
	s_add_u32 s16, s36, s16
	s_addc_u32 s17, s37, s17
	s_and_b64 s[18:19], s[4:5], exec
	s_cselect_b32 s15, s17, s21
	s_cselect_b32 s63, s16, s20
	s_ashr_i32 s13, s12, 31
	s_lshl_b64 s[18:19], s[12:13], 19
	s_add_u32 s18, s48, s18
	s_addc_u32 s19, s49, s19
	s_and_b64 s[42:43], s[4:5], exec
	s_cselect_b32 s13, s19, s39
	s_cselect_b32 s64, s18, s38
	s_add_u32 s20, s20, 0x40080
	s_addc_u32 s21, s21, 0
	s_add_u32 s65, s38, 0x100
	s_addc_u32 s66, s39, 0
	s_mov_b32 s67, -2
	s_add_u32 s38, s20, 0xfffc0080
	s_addc_u32 s39, s21, -1
	s_cmp_eq_u32 s67, 12
	s_cselect_b32 s43, s15, s39
	s_cselect_b32 s42, s63, s38
	s_cselect_b32 s39, s13, s66
	s_cselect_b32 s38, s64, s65
	s_add_i32 m0, s35, 0xc000
	global_load_lds_dwordx4 v136, s[20:21]
	s_add_i32 m0, s35, 0xe000
	s_nop 0
	global_load_lds_dwordx4 v138, s[20:21]
	s_waitcnt vmcnt(8)
	s_waitcnt lgkmcnt(0)
	s_barrier
	v_mfma_f32_16x16x32_bf16 v[124:127], v[154:157], v[186:189], 0
	v_mfma_f32_16x16x32_bf16 v[116:119], v[162:165], v[186:189], 0
	v_mfma_f32_16x16x32_bf16 v[108:111], v[154:157], v[198:201], 0
	v_mfma_f32_16x16x32_bf16 v[100:103], v[162:165], v[198:201], 0
	v_mfma_f32_16x16x32_bf16 v[92:95], v[154:157], v[206:209], 0
	v_mfma_f32_16x16x32_bf16 v[84:87], v[162:165], v[206:209], 0
	v_mfma_f32_16x16x32_bf16 v[76:79], v[154:157], v[214:217], 0
	v_mfma_f32_16x16x32_bf16 v[68:71], v[162:165], v[214:217], 0
	v_mfma_f32_16x16x32_bf16 v[124:127], v[158:161], v[190:193], v[124:127]
	v_mfma_f32_16x16x32_bf16 v[116:119], v[166:169], v[190:193], v[116:119]
	v_mfma_f32_16x16x32_bf16 v[108:111], v[158:161], v[202:205], v[108:111]
	v_mfma_f32_16x16x32_bf16 v[100:103], v[166:169], v[202:205], v[100:103]
	v_mfma_f32_16x16x32_bf16 v[92:95], v[158:161], v[210:213], v[92:95]
	v_mfma_f32_16x16x32_bf16 v[84:87], v[166:169], v[210:213], v[84:87]
	v_mfma_f32_16x16x32_bf16 v[76:79], v[158:161], v[218:221], v[76:79]
	v_mfma_f32_16x16x32_bf16 v[68:71], v[166:169], v[218:221], v[68:71]
	v_mfma_f32_16x16x32_bf16 v[120:123], v[170:173], v[186:189], 0
	v_mfma_f32_16x16x32_bf16 v[112:115], v[178:181], v[186:189], 0
	v_mfma_f32_16x16x32_bf16 v[104:107], v[170:173], v[198:201], 0
	v_mfma_f32_16x16x32_bf16 v[96:99], v[178:181], v[198:201], 0
	v_mfma_f32_16x16x32_bf16 v[88:91], v[170:173], v[206:209], 0
	v_mfma_f32_16x16x32_bf16 v[80:83], v[178:181], v[206:209], 0
	v_mfma_f32_16x16x32_bf16 v[72:75], v[170:173], v[214:217], 0
	v_mfma_f32_16x16x32_bf16 v[64:67], v[178:181], v[214:217], 0
	v_mfma_f32_16x16x32_bf16 v[120:123], v[174:177], v[190:193], v[120:123]
	v_mfma_f32_16x16x32_bf16 v[112:115], v[182:185], v[190:193], v[112:115]
	v_mfma_f32_16x16x32_bf16 v[104:107], v[174:177], v[202:205], v[104:107]
	v_mfma_f32_16x16x32_bf16 v[96:99], v[182:185], v[202:205], v[96:99]
	v_mfma_f32_16x16x32_bf16 v[88:91], v[174:177], v[210:213], v[88:91]
	v_mfma_f32_16x16x32_bf16 v[80:83], v[182:185], v[210:213], v[80:83]
	v_mfma_f32_16x16x32_bf16 v[72:75], v[174:177], v[218:221], v[72:75]
	v_mfma_f32_16x16x32_bf16 v[64:67], v[182:185], v[218:221], v[64:67]
	s_barrier
	s_add_i32 s68, s58, s50
	s_add_u32 s98, s38, s8
	s_addc_u32 s99, s39, s9
	s_add_u32 s100, s42, s8
	s_addc_u32 s101, s43, s9
	s_mov_b32 m0, s68
	ds_read_b128 v[186:189], v152 offset:16384
	ds_read_b128 v[190:193], v152 offset:17408
	ds_read_b128 v[198:201], v152 offset:18432
	ds_read_b128 v[202:205], v152 offset:19456
	ds_read_b128 v[206:209], v152 offset:20480
	ds_read_b128 v[210:213], v152 offset:21504
	ds_read_b128 v[214:217], v152 offset:22528
	ds_read_b128 v[218:221], v152 offset:23552
	global_load_lds_dwordx4 v132, s[38:39]
	s_add_i32 m0, s68, 0x2000
	s_add_u32 s68, s38, 0x40000
	s_addc_u32 s69, s39, 0
	s_add_i32 s70, s59, s50
	global_load_lds_dwordx4 v128, s[38:39]
	s_mov_b32 m0, s70
	s_nop 0
	global_load_lds_dwordx4 v132, s[68:69]
	s_add_i32 m0, s70, 0x2000
	s_nop 0
	global_load_lds_dwordx4 v128, s[68:69]
	s_mov_b32 m0, s35
	s_nop 0
	global_load_lds_dwordx4 v134, s[42:43]
	s_mov_b32 m0, s52
	s_nop 0
	global_load_lds_dwordx4 v130, s[42:43]
	s_waitcnt vmcnt(8)
	s_waitcnt lgkmcnt(0)
	s_barrier
; #define PG8_STAGE(bufoff, gbase, voff) do { _Pragma("unroll") for (int _i = 0; _i < 2; ++_i) \
;         __builtin_amdgcn_global_load_lds((const unsigned*)((const char*)(gbase) + (voff)[_i]), (PG8_LAS unsigned*)(lds + (bufoff) + ldsw + _i * 8192), 16, 0, 0); } while (0)
; #define PG8_LDA(dst, b, h) do { _Pragma("unroll") for (int m = 0; m < 4; ++m) _Pragma("unroll") for (int k = 0; k < 2; ++k) dst[m][k] = *(const PG8_LAS bf16x8*)(lds + PG8_SA(b, h) + aoff + m * 2048 + k * 1024); } while (0)
; #define PG8_LDB(dst, b, h) do { _Pragma("unroll") for (int n = 0; n < 2; ++n) _Pragma("unroll") for (int k = 0; k < 2; ++k) dst[n][k] = *(const PG8_LAS bf16x8*)(lds + PG8_SB(b, h) + boff + n * 2048 + k * 1024); } while (0)
; #define PG8_MMA(ai, bj, At, Bt) do { __builtin_amdgcn_s_setprio(1); _Pragma("unroll") for (int m = 0; m < 4; ++m) _Pragma("unroll") for (int n = 0; n < 2; ++n) _Pragma("unroll") for (int k = 0; k < 2; ++k) \
;         acc[ai][bj][m][n] = __builtin_amdgcn_mfma_f32_16x16x32_bf16(Bt[n][k], At[m][k], acc[ai][bj][m][n], 0, 0, 0); __builtin_amdgcn_s_setprio(0); } while (0)
; #define PG8_WAIT_V(n) asm volatile("s_waitcnt vmcnt(" #n ")" ::: "memory")
; #define PG8_WAIT_L(n) asm volatile("s_waitcnt lgkmcnt(" #n ")" ::: "memory")
; #define PG8_BAR __builtin_amdgcn_s_barrier()
; #define PG8_SCHED __builtin_amdgcn_sched_barrier(0)
; template <class Epi, class Sched, bool ALIGN_EPI = false, bool SP2 = false>
; __device__ __forceinline__ void gemm_phase(PG8_LAS unsigned char* lds, const Gemm g, const Sched& S, const Epi& E) {
;     ...
;             PG8_WAIT_V(8); PG8_WAIT_L(0); PG8_BAR; PG8_MMA(0, 0, At, B0); PG8_MMA(0, 1, At, B1); PG8_BAR; PG8_SCHED;
;             PG8_LDA(At, 0, 1); PG8_STAGE(PG8_SB(0, 0), b2, voffB); PG8_STAGE(PG8_SB(0, 1), b2 + hstep, voffB); PG8_STAGE(PG8_SA(0, 0), a2, voffA);
;             PG8_WAIT_V(8); PG8_WAIT_L(0); PG8_BAR; PG8_MMA(1, 0, At, B0); PG8_MMA(1, 1, At, B1); PG8_BAR; PG8_SCHED;
;             PG8_LDB(B0, 1, 0); PG8_LDB(B1, 1, 1); PG8_SCHED; PG8_LDA(At, 1, 0); PG8_STAGE(PG8_SA(0, 1), a2 + hstep, voffA);
;             PG8_WAIT_V(8); PG8_WAIT_L(0); PG8_BAR; PG8_MMA(0, 0, At, B0); PG8_MMA(0, 1, At, B1); PG8_BAR; PG8_SCHED;
	v_mfma_f32_16x16x32_bf16 v[60:63], v[154:157], v[186:189], 0
	v_mfma_f32_16x16x32_bf16 v[52:55], v[162:165], v[186:189], 0
	v_mfma_f32_16x16x32_bf16 v[44:47], v[154:157], v[198:201], 0
	v_mfma_f32_16x16x32_bf16 v[36:39], v[162:165], v[198:201], 0
	v_mfma_f32_16x16x32_bf16 v[28:31], v[154:157], v[206:209], 0
	v_mfma_f32_16x16x32_bf16 v[20:23], v[162:165], v[206:209], 0
	v_mfma_f32_16x16x32_bf16 v[12:15], v[154:157], v[214:217], 0
	v_mfma_f32_16x16x32_bf16 v[4:7], v[162:165], v[214:217], 0
	v_mfma_f32_16x16x32_bf16 v[60:63], v[158:161], v[190:193], v[60:63]
	v_mfma_f32_16x16x32_bf16 v[52:55], v[166:169], v[190:193], v[52:55]
	v_mfma_f32_16x16x32_bf16 v[44:47], v[158:161], v[202:205], v[44:47]
	v_mfma_f32_16x16x32_bf16 v[36:39], v[166:169], v[202:205], v[36:39]
	v_mfma_f32_16x16x32_bf16 v[28:31], v[158:161], v[210:213], v[28:31]
	v_mfma_f32_16x16x32_bf16 v[20:23], v[166:169], v[210:213], v[20:23]
	v_mfma_f32_16x16x32_bf16 v[12:15], v[158:161], v[218:221], v[12:15]
	v_mfma_f32_16x16x32_bf16 v[4:7], v[166:169], v[218:221], v[4:7]
	v_mfma_f32_16x16x32_bf16 v[56:59], v[170:173], v[186:189], 0
	v_mfma_f32_16x16x32_bf16 v[48:51], v[178:181], v[186:189], 0
	v_mfma_f32_16x16x32_bf16 v[40:43], v[170:173], v[198:201], 0
	v_mfma_f32_16x16x32_bf16 v[32:35], v[178:181], v[198:201], 0
	v_mfma_f32_16x16x32_bf16 v[24:27], v[170:173], v[206:209], 0
	v_mfma_f32_16x16x32_bf16 v[16:19], v[178:181], v[206:209], 0
	v_mfma_f32_16x16x32_bf16 v[8:11], v[170:173], v[214:217], 0
	v_mfma_f32_16x16x32_bf16 v[0:3], v[178:181], v[214:217], 0
	v_mfma_f32_16x16x32_bf16 v[56:59], v[174:177], v[190:193], v[56:59]
	v_mfma_f32_16x16x32_bf16 v[48:51], v[182:185], v[190:193], v[48:51]
	v_mfma_f32_16x16x32_bf16 v[40:43], v[174:177], v[202:205], v[40:43]
	v_mfma_f32_16x16x32_bf16 v[32:35], v[182:185], v[202:205], v[32:35]
	v_mfma_f32_16x16x32_bf16 v[24:27], v[174:177], v[210:213], v[24:27]
	v_mfma_f32_16x16x32_bf16 v[16:19], v[182:185], v[210:213], v[16:19]
	v_mfma_f32_16x16x32_bf16 v[8:11], v[174:177], v[218:221], v[8:11]
	v_mfma_f32_16x16x32_bf16 v[0:3], v[182:185], v[218:221], v[0:3]
	s_barrier
	s_add_i32 s68, 0, 0x18000
	v_add_u32_e32 v153, s68, v147
	s_add_i32 s69, 0, 0x1c000
	ds_read_b128 v[154:157], v153
	ds_read_b128 v[158:161], v153 offset:1024
	ds_read_b128 v[162:165], v153 offset:2048
	ds_read_b128 v[166:169], v153 offset:3072
	v_add_u32_e32 v153, s69, v147
	ds_read_b128 v[170:173], v153
	ds_read_b128 v[174:177], v153 offset:1024
	ds_read_b128 v[178:181], v153 offset:2048
	ds_read_b128 v[182:185], v153 offset:3072
	s_add_u32 s42, s42, 0x40000
	s_addc_u32 s43, s43, 0
	s_mov_b32 m0, s53
	ds_read_b128 v[186:189], v152 offset:32768
	ds_read_b128 v[190:193], v152 offset:33792
	ds_read_b128 v[198:201], v152 offset:34816
	ds_read_b128 v[202:205], v152 offset:35840
	ds_read_b128 v[206:209], v152 offset:36864
	ds_read_b128 v[210:213], v152 offset:37888
	ds_read_b128 v[214:217], v152 offset:38912
	ds_read_b128 v[218:221], v152 offset:39936
	global_load_lds_dwordx4 v134, s[42:43]
	s_mov_b32 m0, s54
	s_nop 0
	global_load_lds_dwordx4 v130, s[42:43]
	s_waitcnt vmcnt(8)
	s_waitcnt lgkmcnt(0)
	s_barrier
	v_mfma_f32_16x16x32_bf16 v[124:127], v[154:157], v[186:189], v[124:127]
	v_mfma_f32_16x16x32_bf16 v[116:119], v[162:165], v[186:189], v[116:119]
	v_mfma_f32_16x16x32_bf16 v[108:111], v[154:157], v[198:201], v[108:111]
	v_mfma_f32_16x16x32_bf16 v[100:103], v[162:165], v[198:201], v[100:103]
	v_mfma_f32_16x16x32_bf16 v[92:95], v[154:157], v[206:209], v[92:95]
	v_mfma_f32_16x16x32_bf16 v[84:87], v[162:165], v[206:209], v[84:87]
	v_mfma_f32_16x16x32_bf16 v[76:79], v[154:157], v[214:217], v[76:79]
	v_mfma_f32_16x16x32_bf16 v[68:71], v[162:165], v[214:217], v[68:71]
	v_mfma_f32_16x16x32_bf16 v[124:127], v[158:161], v[190:193], v[124:127]
	v_mfma_f32_16x16x32_bf16 v[116:119], v[166:169], v[190:193], v[116:119]
	v_mfma_f32_16x16x32_bf16 v[108:111], v[158:161], v[202:205], v[108:111]
	v_mfma_f32_16x16x32_bf16 v[100:103], v[166:169], v[202:205], v[100:103]
	v_mfma_f32_16x16x32_bf16 v[92:95], v[158:161], v[210:213], v[92:95]
	v_mfma_f32_16x16x32_bf16 v[84:87], v[166:169], v[210:213], v[84:87]
	v_mfma_f32_16x16x32_bf16 v[76:79], v[158:161], v[218:221], v[76:79]
	v_mfma_f32_16x16x32_bf16 v[68:71], v[166:169], v[218:221], v[68:71]
	v_mfma_f32_16x16x32_bf16 v[120:123], v[170:173], v[186:189], v[120:123]
	v_mfma_f32_16x16x32_bf16 v[112:115], v[178:181], v[186:189], v[112:115]
	v_mfma_f32_16x16x32_bf16 v[104:107], v[170:173], v[198:201], v[104:107]
	v_mfma_f32_16x16x32_bf16 v[96:99], v[178:181], v[198:201], v[96:99]
	v_mfma_f32_16x16x32_bf16 v[88:91], v[170:173], v[206:209], v[88:91]
	v_mfma_f32_16x16x32_bf16 v[80:83], v[178:181], v[206:209], v[80:83]
	v_mfma_f32_16x16x32_bf16 v[72:75], v[170:173], v[214:217], v[72:75]
	v_mfma_f32_16x16x32_bf16 v[64:67], v[178:181], v[214:217], v[64:67]
	v_mfma_f32_16x16x32_bf16 v[120:123], v[174:177], v[190:193], v[120:123]
	v_mfma_f32_16x16x32_bf16 v[112:115], v[182:185], v[190:193], v[112:115]
	v_mfma_f32_16x16x32_bf16 v[104:107], v[174:177], v[202:205], v[104:107]
	v_mfma_f32_16x16x32_bf16 v[96:99], v[182:185], v[202:205], v[96:99]
	v_mfma_f32_16x16x32_bf16 v[88:91], v[174:177], v[210:213], v[88:91]
	v_mfma_f32_16x16x32_bf16 v[80:83], v[182:185], v[210:213], v[80:83]
	v_mfma_f32_16x16x32_bf16 v[72:75], v[174:177], v[218:221], v[72:75]
	v_mfma_f32_16x16x32_bf16 v[64:67], v[182:185], v[218:221], v[64:67]
	s_barrier
; #define PG8_STAGE(bufoff, gbase, voff) do { _Pragma("unroll") for (int _i = 0; _i < 2; ++_i) \
;         __builtin_amdgcn_global_load_lds((const unsigned*)((const char*)(gbase) + (voff)[_i]), (PG8_LAS unsigned*)(lds + (bufoff) + ldsw + _i * 8192), 16, 0, 0); } while (0)
; #define PG8_LDA(dst, b, h) do { _Pragma("unroll") for (int m = 0; m < 4; ++m) _Pragma("unroll") for (int k = 0; k < 2; ++k) dst[m][k] = *(const PG8_LAS bf16x8*)(lds + PG8_SA(b, h) + aoff + m * 2048 + k * 1024); } while (0)
; #define PG8_MMA(ai, bj, At, Bt) do { __builtin_amdgcn_s_setprio(1); _Pragma("unroll") for (int m = 0; m < 4; ++m) _Pragma("unroll") for (int n = 0; n < 2; ++n) _Pragma("unroll") for (int k = 0; k < 2; ++k) \
;         acc[ai][bj][m][n] = __builtin_amdgcn_mfma_f32_16x16x32_bf16(Bt[n][k], At[m][k], acc[ai][bj][m][n], 0, 0, 0); __builtin_amdgcn_s_setprio(0); } while (0)
; #define PG8_WAIT_V(n) asm volatile("s_waitcnt vmcnt(" #n ")" ::: "memory")
; #define PG8_WAIT_L(n) asm volatile("s_waitcnt lgkmcnt(" #n ")" ::: "memory")
; #define PG8_BAR __builtin_amdgcn_s_barrier()
; #define PG8_SCHED __builtin_amdgcn_sched_barrier(0)
; template <class Epi, class Sched, bool ALIGN_EPI = false, bool SP2 = false>
; __device__ __forceinline__ void gemm_phase(PG8_LAS unsigned char* lds, const Gemm g, const Sched& S, const Epi& E) {
;     ...
;             PG8_WAIT_V(8); PG8_WAIT_L(0); PG8_BAR; PG8_MMA(0, 0, At, B0); PG8_MMA(0, 1, At, B1); PG8_BAR; PG8_SCHED;
;             PG8_LDA(At, 1, 1); PG8_STAGE(PG8_SB(1, 0), b3, voffB); PG8_STAGE(PG8_SB(1, 1), b3 + hstep, voffB); PG8_STAGE(PG8_SA(1, 0), a3, voffA);
;             PG8_WAIT_V(8); PG8_WAIT_L(0); PG8_BAR; PG8_MMA(1, 0, At, B0); PG8_MMA(1, 1, At, B1); PG8_BAR; PG8_SCHED;
	s_add_i32 s42, s68, s50
	s_mov_b32 m0, s42
	ds_read_b128 v[186:189], v152 offset:49152
	ds_read_b128 v[190:193], v152 offset:50176
	ds_read_b128 v[198:201], v152 offset:51200
	ds_read_b128 v[202:205], v152 offset:52224
	ds_read_b128 v[206:209], v152 offset:53248
	ds_read_b128 v[210:213], v152 offset:54272
	ds_read_b128 v[214:217], v152 offset:55296
	ds_read_b128 v[218:221], v152 offset:56320
	global_load_lds_dwordx4 v132, s[98:99]
	s_add_i32 m0, s42, 0x2000
	s_add_u32 s38, s38, 0x40080
	s_addc_u32 s39, s39, 0
	s_add_i32 s42, s69, s50
	global_load_lds_dwordx4 v128, s[98:99]
	s_mov_b32 m0, s42
	s_nop 0
	global_load_lds_dwordx4 v132, s[38:39]
	s_add_i32 m0, s42, 0x2000
	s_nop 0
	global_load_lds_dwordx4 v128, s[38:39]
	s_mov_b32 m0, s56
	s_nop 0
	global_load_lds_dwordx4 v134, s[100:101]
	s_mov_b32 m0, s57
	s_nop 0
	global_load_lds_dwordx4 v130, s[100:101]
	s_waitcnt vmcnt(8)
	s_waitcnt lgkmcnt(0)
	s_barrier
	v_mfma_f32_16x16x32_bf16 v[60:63], v[154:157], v[186:189], v[60:63]
	v_mfma_f32_16x16x32_bf16 v[52:55], v[162:165], v[186:189], v[52:55]
	v_mfma_f32_16x16x32_bf16 v[44:47], v[154:157], v[198:201], v[44:47]
	v_mfma_f32_16x16x32_bf16 v[36:39], v[162:165], v[198:201], v[36:39]
	v_mfma_f32_16x16x32_bf16 v[28:31], v[154:157], v[206:209], v[28:31]
	v_mfma_f32_16x16x32_bf16 v[20:23], v[162:165], v[206:209], v[20:23]
	v_mfma_f32_16x16x32_bf16 v[12:15], v[154:157], v[214:217], v[12:15]
	v_mfma_f32_16x16x32_bf16 v[4:7], v[162:165], v[214:217], v[4:7]
	v_mfma_f32_16x16x32_bf16 v[60:63], v[158:161], v[190:193], v[60:63]
	v_mfma_f32_16x16x32_bf16 v[52:55], v[166:169], v[190:193], v[52:55]
	v_mfma_f32_16x16x32_bf16 v[44:47], v[158:161], v[202:205], v[44:47]
	v_mfma_f32_16x16x32_bf16 v[36:39], v[166:169], v[202:205], v[36:39]
	v_mfma_f32_16x16x32_bf16 v[28:31], v[158:161], v[210:213], v[28:31]
	v_mfma_f32_16x16x32_bf16 v[20:23], v[166:169], v[210:213], v[20:23]
	v_mfma_f32_16x16x32_bf16 v[12:15], v[158:161], v[218:221], v[12:15]
	v_mfma_f32_16x16x32_bf16 v[4:7], v[166:169], v[218:221], v[4:7]
	v_mfma_f32_16x16x32_bf16 v[56:59], v[170:173], v[186:189], v[56:59]
	v_mfma_f32_16x16x32_bf16 v[48:51], v[178:181], v[186:189], v[48:51]
	v_mfma_f32_16x16x32_bf16 v[40:43], v[170:173], v[198:201], v[40:43]
	v_mfma_f32_16x16x32_bf16 v[32:35], v[178:181], v[198:201], v[32:35]
	v_mfma_f32_16x16x32_bf16 v[24:27], v[170:173], v[206:209], v[24:27]
	v_mfma_f32_16x16x32_bf16 v[16:19], v[178:181], v[206:209], v[16:19]
	v_mfma_f32_16x16x32_bf16 v[8:11], v[170:173], v[214:217], v[8:11]
	v_mfma_f32_16x16x32_bf16 v[0:3], v[178:181], v[214:217], v[0:3]
	v_mfma_f32_16x16x32_bf16 v[56:59], v[174:177], v[190:193], v[56:59]
	v_mfma_f32_16x16x32_bf16 v[48:51], v[182:185], v[190:193], v[48:51]
	v_mfma_f32_16x16x32_bf16 v[40:43], v[174:177], v[202:205], v[40:43]
	v_mfma_f32_16x16x32_bf16 v[32:35], v[182:185], v[202:205], v[32:35]
	v_mfma_f32_16x16x32_bf16 v[24:27], v[174:177], v[210:213], v[24:27]
	v_mfma_f32_16x16x32_bf16 v[16:19], v[182:185], v[210:213], v[16:19]
	v_mfma_f32_16x16x32_bf16 v[8:11], v[174:177], v[218:221], v[8:11]
	v_mfma_f32_16x16x32_bf16 v[0:3], v[182:185], v[218:221], v[0:3]
	s_barrier
	s_add_i32 s67, s67, 2
	s_add_u32 s20, s20, 0x100
	s_addc_u32 s21, s21, 0
	s_add_u32 s65, s65, 0x100
	s_addc_u32 s66, s66, 0
	s_cmp_gt_u32 s67, 13

; #define PG8_STAGE(bufoff, gbase, voff) do { _Pragma("unroll") for (int _i = 0; _i < 2; ++_i) \
;         __builtin_amdgcn_global_load_lds((const unsigned*)((const char*)(gbase) + (voff)[_i]), (PG8_LAS unsigned*)(lds + (bufoff) + ldsw + _i * 8192), 16, 0, 0); } while (0)
; #define PG8_LDA(dst, b, h) do { _Pragma("unroll") for (int m = 0; m < 4; ++m) _Pragma("unroll") for (int k = 0; k < 2; ++k) dst[m][k] = *(const PG8_LAS bf16x8*)(lds + PG8_SA(b, h) + aoff + m * 2048 + k * 1024); } while (0)
; #define PG8_LDB(dst, b, h) do { _Pragma("unroll") for (int n = 0; n < 2; ++n) _Pragma("unroll") for (int k = 0; k < 2; ++k) dst[n][k] = *(const PG8_LAS bf16x8*)(lds + PG8_SB(b, h) + boff + n * 2048 + k * 1024); } while (0)
; #define PG8_MMA(ai, bj, At, Bt) do { __builtin_amdgcn_s_setprio(1); _Pragma("unroll") for (int m = 0; m < 4; ++m) _Pragma("unroll") for (int n = 0; n < 2; ++n) _Pragma("unroll") for (int k = 0; k < 2; ++k) \
;         acc[ai][bj][m][n] = __builtin_amdgcn_mfma_f32_16x16x32_bf16(Bt[n][k], At[m][k], acc[ai][bj][m][n], 0, 0, 0); __builtin_amdgcn_s_setprio(0); } while (0)
; #define PG8_WAIT_V(n) asm volatile("s_waitcnt vmcnt(" #n ")" ::: "memory")
; template <class Epi, class Sched, bool ALIGN_EPI = false, bool SP2 = false>
; __device__ __forceinline__ void gemm_phase(PG8_LAS unsigned char* lds, const Gemm g, const Sched& S, const Epi& E) {
;     ...
;         const char* nA = has_next ? (const char*)g.A + (size_t)nxt.pm * tstep : cA; const char* nB = has_next ? (const char*)g.Bt + (size_t)nxt.pn * tstep : cB;
;         for (int t = 0; t < nt; t += 2) {
;             const bool last = (t == nt - 2);
;             const char* a1 = cA + (size_t)(t + 1) * kstep;
;             const char* a2 = last ? nA : cA + (size_t)(t + 2) * kstep; const char* b2 = last ? nB : cB + (size_t)(t + 2) * kstep;
;             const char* a3 = a2 + kstep; const char* b3 = b2 + kstep;
;             if (last && has_next) S.a_ready(nxt);
;             if constexpr (SP2) {
;             PG8_LDB(B0, 0, 0); PG8_LDB(B1, 0, 1); PG8_SCHED; PG8_LDA(At, 0, 0); PG8_STAGE(PG8_SA(1, 1), a1 + hstep, voffA);
;             PG8_WAIT_V(8); PG8_WAIT_L(0); PG8_BAR; PG8_MMA(0, 0, At, B0); PG8_MMA(0, 1, At, B1); PG8_BAR; PG8_SCHED;
;             PG8_LDA(At, 0, 1); PG8_STAGE(PG8_SB(0, 0), b2, voffB); PG8_STAGE(PG8_SB(0, 1), b2 + hstep, voffB); PG8_STAGE(PG8_SA(0, 0), a2, voffA);
.LBB0_1824:
	s_add_u32 s20, s20, 0xb0080
	s_addc_u32 s21, s21, 0
	s_add_u32 s68, s34, 0x100
	s_addc_u32 s69, s35, 0
	s_mov_b32 s70, -2
	s_waitcnt lgkmcnt(0)
	ds_read_b128 v[96:99], v222
	ds_read_b128 v[108:111], v222 offset:1024
	ds_read_b128 v[120:123], v222 offset:2048
	ds_read_b128 v[128:131], v222 offset:3072
	ds_read_b128 v[144:147], v223
	ds_read_b128 v[148:151], v223 offset:1024
	ds_read_b128 v[152:155], v223 offset:2048
	ds_read_b128 v[156:159], v223 offset:3072
	ds_read_b128 v[160:163], v224
	ds_read_b128 v[164:167], v224 offset:1024
	ds_read_b128 v[168:171], v224 offset:2048
	ds_read_b128 v[172:175], v224 offset:3072
	ds_read_b128 v[176:179], v224 offset:4096
	ds_read_b128 v[180:183], v224 offset:5120
	ds_read_b128 v[202:205], v224 offset:6144
	ds_read_b128 v[206:209], v224 offset:7168
	s_add_u32 s34, s20, 0xfff50080
	s_addc_u32 s35, s21, -1
	s_cmp_eq_u32 s70, 40
	s_cselect_b32 s47, s1, s35
	s_cselect_b32 s46, s0, s34
	s_cselect_b32 s35, s45, s69
	s_cselect_b32 s34, s44, s68
	s_add_i32 m0, s49, 0xc000
	global_load_lds_dwordx4 v192, s[20:21]
	s_add_i32 m0, s49, 0xe000
	s_nop 0
	global_load_lds_dwordx4 v194, s[20:21]
	s_waitcnt vmcnt(8)
	s_waitcnt lgkmcnt(0)
	s_barrier
	v_mfma_f32_16x16x32_bf16 v[140:143], v[96:99], v[160:163], 0
	v_mfma_f32_16x16x32_bf16 v[136:139], v[120:123], v[160:163], 0
	v_mfma_f32_16x16x32_bf16 v[116:119], v[96:99], v[168:171], 0
	v_mfma_f32_16x16x32_bf16 v[112:115], v[120:123], v[168:171], 0
	v_mfma_f32_16x16x32_bf16 v[92:95], v[96:99], v[176:179], 0
	v_mfma_f32_16x16x32_bf16 v[88:91], v[120:123], v[176:179], 0
	v_mfma_f32_16x16x32_bf16 v[76:79], v[96:99], v[202:205], 0
	v_mfma_f32_16x16x32_bf16 v[72:75], v[120:123], v[202:205], 0
	v_mfma_f32_16x16x32_bf16 v[140:143], v[108:111], v[164:167], v[140:143]
	v_mfma_f32_16x16x32_bf16 v[136:139], v[128:131], v[164:167], v[136:139]
	v_mfma_f32_16x16x32_bf16 v[116:119], v[108:111], v[172:175], v[116:119]
	v_mfma_f32_16x16x32_bf16 v[112:115], v[128:131], v[172:175], v[112:115]
	v_mfma_f32_16x16x32_bf16 v[92:95], v[108:111], v[180:183], v[92:95]
	v_mfma_f32_16x16x32_bf16 v[88:91], v[128:131], v[180:183], v[88:91]
	v_mfma_f32_16x16x32_bf16 v[76:79], v[108:111], v[206:209], v[76:79]
	v_mfma_f32_16x16x32_bf16 v[72:75], v[128:131], v[206:209], v[72:75]
	v_mfma_f32_16x16x32_bf16 v[132:135], v[144:147], v[160:163], 0
	v_mfma_f32_16x16x32_bf16 v[124:127], v[152:155], v[160:163], 0
	v_mfma_f32_16x16x32_bf16 v[104:107], v[144:147], v[168:171], 0
	v_mfma_f32_16x16x32_bf16 v[100:103], v[152:155], v[168:171], 0
	v_mfma_f32_16x16x32_bf16 v[84:87], v[144:147], v[176:179], 0
	v_mfma_f32_16x16x32_bf16 v[80:83], v[152:155], v[176:179], 0
	v_mfma_f32_16x16x32_bf16 v[68:71], v[144:147], v[202:205], 0
	v_mfma_f32_16x16x32_bf16 v[64:67], v[152:155], v[202:205], 0
	v_mfma_f32_16x16x32_bf16 v[132:135], v[148:151], v[164:167], v[132:135]
	v_mfma_f32_16x16x32_bf16 v[124:127], v[156:159], v[164:167], v[124:127]
	v_mfma_f32_16x16x32_bf16 v[104:107], v[148:151], v[172:175], v[104:107]
	v_mfma_f32_16x16x32_bf16 v[100:103], v[156:159], v[172:175], v[100:103]
	v_mfma_f32_16x16x32_bf16 v[84:87], v[148:151], v[180:183], v[84:87]
	v_mfma_f32_16x16x32_bf16 v[80:83], v[156:159], v[180:183], v[80:83]
	v_mfma_f32_16x16x32_bf16 v[68:71], v[148:151], v[206:209], v[68:71]
	v_mfma_f32_16x16x32_bf16 v[64:67], v[156:159], v[206:209], v[64:67]
	s_barrier
	s_add_i32 s71, s62, s48
	s_add_u32 s98, s34, s12
	s_addc_u32 s99, s35, s13
	s_add_u32 s100, s46, s12
	s_addc_u32 s101, s47, s13
	s_mov_b32 m0, s71
	ds_read_b128 v[160:163], v224 offset:16384
	ds_read_b128 v[164:167], v224 offset:17408
	ds_read_b128 v[168:171], v224 offset:18432
	ds_read_b128 v[172:175], v224 offset:19456
	ds_read_b128 v[176:179], v224 offset:20480
	ds_read_b128 v[180:183], v224 offset:21504
	ds_read_b128 v[202:205], v224 offset:22528
	ds_read_b128 v[206:209], v224 offset:23552
	global_load_lds_dwordx4 v186, s[34:35]
	s_add_i32 m0, s71, 0x2000
	s_add_u32 s72, s34, 0xb0000
	s_addc_u32 s73, s35, 0
	s_add_i32 s71, s63, s48
	global_load_lds_dwordx4 v190, s[34:35]
	s_mov_b32 m0, s71
	s_nop 0
	global_load_lds_dwordx4 v186, s[72:73]
	s_add_i32 m0, s71, 0x2000
	s_nop 0
	global_load_lds_dwordx4 v190, s[72:73]
	s_mov_b32 m0, s49
	s_nop 0
	global_load_lds_dwordx4 v184, s[46:47]
	s_mov_b32 m0, s50
	s_nop 0
	global_load_lds_dwordx4 v188, s[46:47]
	s_waitcnt vmcnt(8)
	s_waitcnt lgkmcnt(0)
	s_barrier
	v_mfma_f32_16x16x32_bf16 v[60:63], v[96:99], v[160:163], 0
	v_mfma_f32_16x16x32_bf16 v[56:59], v[120:123], v[160:163], 0
	v_mfma_f32_16x16x32_bf16 v[44:47], v[96:99], v[168:171], 0
	v_mfma_f32_16x16x32_bf16 v[40:43], v[120:123], v[168:171], 0
	v_mfma_f32_16x16x32_bf16 v[28:31], v[96:99], v[176:179], 0
	v_mfma_f32_16x16x32_bf16 v[24:27], v[120:123], v[176:179], 0
	v_mfma_f32_16x16x32_bf16 v[12:15], v[96:99], v[202:205], 0
	v_mfma_f32_16x16x32_bf16 v[8:11], v[120:123], v[202:205], 0
	v_mfma_f32_16x16x32_bf16 v[60:63], v[108:111], v[164:167], v[60:63]
	v_mfma_f32_16x16x32_bf16 v[56:59], v[128:131], v[164:167], v[56:59]
	v_mfma_f32_16x16x32_bf16 v[44:47], v[108:111], v[172:175], v[44:47]
	v_mfma_f32_16x16x32_bf16 v[40:43], v[128:131], v[172:175], v[40:43]
	v_mfma_f32_16x16x32_bf16 v[28:31], v[108:111], v[180:183], v[28:31]
	v_mfma_f32_16x16x32_bf16 v[24:27], v[128:131], v[180:183], v[24:27]
	v_mfma_f32_16x16x32_bf16 v[12:15], v[108:111], v[206:209], v[12:15]
	v_mfma_f32_16x16x32_bf16 v[8:11], v[128:131], v[206:209], v[8:11]
	v_mfma_f32_16x16x32_bf16 v[52:55], v[144:147], v[160:163], 0
	v_mfma_f32_16x16x32_bf16 v[48:51], v[152:155], v[160:163], 0
	v_mfma_f32_16x16x32_bf16 v[36:39], v[144:147], v[168:171], 0
	v_mfma_f32_16x16x32_bf16 v[32:35], v[152:155], v[168:171], 0
	v_mfma_f32_16x16x32_bf16 v[20:23], v[144:147], v[176:179], 0
	v_mfma_f32_16x16x32_bf16 v[16:19], v[152:155], v[176:179], 0
	v_mfma_f32_16x16x32_bf16 v[4:7], v[144:147], v[202:205], 0
	v_mfma_f32_16x16x32_bf16 v[0:3], v[152:155], v[202:205], 0
	v_mfma_f32_16x16x32_bf16 v[52:55], v[148:151], v[164:167], v[52:55]
	v_mfma_f32_16x16x32_bf16 v[48:51], v[156:159], v[164:167], v[48:51]
	v_mfma_f32_16x16x32_bf16 v[36:39], v[148:151], v[172:175], v[36:39]
	v_mfma_f32_16x16x32_bf16 v[32:35], v[156:159], v[172:175], v[32:35]
	v_mfma_f32_16x16x32_bf16 v[20:23], v[148:151], v[180:183], v[20:23]
	v_mfma_f32_16x16x32_bf16 v[16:19], v[156:159], v[180:183], v[16:19]
	v_mfma_f32_16x16x32_bf16 v[4:7], v[148:151], v[206:209], v[4:7]
	v_mfma_f32_16x16x32_bf16 v[0:3], v[156:159], v[206:209], v[0:3]
	s_barrier
; #define PG8_STAGE(bufoff, gbase, voff) do { _Pragma("unroll") for (int _i = 0; _i < 2; ++_i) \
;         __builtin_amdgcn_global_load_lds((const unsigned*)((const char*)(gbase) + (voff)[_i]), (PG8_LAS unsigned*)(lds + (bufoff) + ldsw + _i * 8192), 16, 0, 0); } while (0)
; #define PG8_LDA(dst, b, h) do { _Pragma("unroll") for (int m = 0; m < 4; ++m) _Pragma("unroll") for (int k = 0; k < 2; ++k) dst[m][k] = *(const PG8_LAS bf16x8*)(lds + PG8_SA(b, h) + aoff + m * 2048 + k * 1024); } while (0)
; #define PG8_LDB(dst, b, h) do { _Pragma("unroll") for (int n = 0; n < 2; ++n) _Pragma("unroll") for (int k = 0; k < 2; ++k) dst[n][k] = *(const PG8_LAS bf16x8*)(lds + PG8_SB(b, h) + boff + n * 2048 + k * 1024); } while (0)
; #define PG8_MMA(ai, bj, At, Bt) do { __builtin_amdgcn_s_setprio(1); _Pragma("unroll") for (int m = 0; m < 4; ++m) _Pragma("unroll") for (int n = 0; n < 2; ++n) _Pragma("unroll") for (int k = 0; k < 2; ++k) \
;         acc[ai][bj][m][n] = __builtin_amdgcn_mfma_f32_16x16x32_bf16(Bt[n][k], At[m][k], acc[ai][bj][m][n], 0, 0, 0); __builtin_amdgcn_s_setprio(0); } while (0)
; #define PG8_WAIT_V(n) asm volatile("s_waitcnt vmcnt(" #n ")" ::: "memory")
; #define PG8_WAIT_L(n) asm volatile("s_waitcnt lgkmcnt(" #n ")" ::: "memory")
; #define PG8_BAR __builtin_amdgcn_s_barrier()
; #define PG8_SCHED __builtin_amdgcn_sched_barrier(0)
; template <class Epi, class Sched, bool ALIGN_EPI = false, bool SP2 = false>
; __device__ __forceinline__ void gemm_phase(PG8_LAS unsigned char* lds, const Gemm g, const Sched& S, const Epi& E) {
;     ...
;             PG8_LDA(At, 0, 1); PG8_STAGE(PG8_SB(0, 0), b2, voffB); PG8_STAGE(PG8_SB(0, 1), b2 + hstep, voffB); PG8_STAGE(PG8_SA(0, 0), a2, voffA);
;             PG8_WAIT_V(8); PG8_WAIT_L(0); PG8_BAR; PG8_MMA(1, 0, At, B0); PG8_MMA(1, 1, At, B1); PG8_BAR; PG8_SCHED;
;             PG8_LDB(B0, 1, 0); PG8_LDB(B1, 1, 1); PG8_SCHED; PG8_LDA(At, 1, 0); PG8_STAGE(PG8_SA(0, 1), a2 + hstep, voffA);
;             PG8_WAIT_V(8); PG8_WAIT_L(0); PG8_BAR; PG8_MMA(0, 0, At, B0); PG8_MMA(0, 1, At, B1); PG8_BAR; PG8_SCHED;
;             PG8_LDA(At, 1, 1); PG8_STAGE(PG8_SB(1, 0), b3, voffB); PG8_STAGE(PG8_SB(1, 1), b3 + hstep, voffB); PG8_STAGE(PG8_SA(1, 0), a3, voffA);
;             PG8_WAIT_V(8); PG8_WAIT_L(0); PG8_BAR; PG8_MMA(1, 0, At, B0); PG8_MMA(1, 1, At, B1); PG8_BAR; PG8_SCHED;
	s_add_i32 s71, 0, 0x18000
	s_add_i32 s72, 0, 0x1c000
	v_add_u32_e32 v128, s71, v197
	v_add_u32_e32 v156, s72, v197
	ds_read_b128 v[96:99], v128
	ds_read_b128 v[108:111], v128 offset:1024
	ds_read_b128 v[120:123], v128 offset:2048
	ds_read_b128 v[128:131], v128 offset:3072
	ds_read_b128 v[144:147], v156
	ds_read_b128 v[148:151], v156 offset:1024
	ds_read_b128 v[152:155], v156 offset:2048
	ds_read_b128 v[156:159], v156 offset:3072
	s_add_u32 s46, s46, 0xb0000
	s_addc_u32 s47, s47, 0
	s_mov_b32 m0, s51
	ds_read_b128 v[160:163], v224 offset:32768
	ds_read_b128 v[164:167], v224 offset:33792
	ds_read_b128 v[168:171], v224 offset:34816
	ds_read_b128 v[172:175], v224 offset:35840
	ds_read_b128 v[176:179], v224 offset:36864
	ds_read_b128 v[180:183], v224 offset:37888
	ds_read_b128 v[202:205], v224 offset:38912
	ds_read_b128 v[206:209], v224 offset:39936
	global_load_lds_dwordx4 v184, s[46:47]
	s_mov_b32 m0, s52
	s_nop 0
	global_load_lds_dwordx4 v188, s[46:47]
	s_waitcnt vmcnt(8)
	s_waitcnt lgkmcnt(0)
	s_barrier
	v_mfma_f32_16x16x32_bf16 v[140:143], v[96:99], v[160:163], v[140:143]
	v_mfma_f32_16x16x32_bf16 v[136:139], v[120:123], v[160:163], v[136:139]
	v_mfma_f32_16x16x32_bf16 v[116:119], v[96:99], v[168:171], v[116:119]
	v_mfma_f32_16x16x32_bf16 v[112:115], v[120:123], v[168:171], v[112:115]
	v_mfma_f32_16x16x32_bf16 v[92:95], v[96:99], v[176:179], v[92:95]
	v_mfma_f32_16x16x32_bf16 v[88:91], v[120:123], v[176:179], v[88:91]
	v_mfma_f32_16x16x32_bf16 v[76:79], v[96:99], v[202:205], v[76:79]
	v_mfma_f32_16x16x32_bf16 v[72:75], v[120:123], v[202:205], v[72:75]
	v_mfma_f32_16x16x32_bf16 v[140:143], v[108:111], v[164:167], v[140:143]
	v_mfma_f32_16x16x32_bf16 v[136:139], v[128:131], v[164:167], v[136:139]
	v_mfma_f32_16x16x32_bf16 v[116:119], v[108:111], v[172:175], v[116:119]
	v_mfma_f32_16x16x32_bf16 v[112:115], v[128:131], v[172:175], v[112:115]
	v_mfma_f32_16x16x32_bf16 v[92:95], v[108:111], v[180:183], v[92:95]
	v_mfma_f32_16x16x32_bf16 v[88:91], v[128:131], v[180:183], v[88:91]
	v_mfma_f32_16x16x32_bf16 v[76:79], v[108:111], v[206:209], v[76:79]
	v_mfma_f32_16x16x32_bf16 v[72:75], v[128:131], v[206:209], v[72:75]
	v_mfma_f32_16x16x32_bf16 v[132:135], v[144:147], v[160:163], v[132:135]
	v_mfma_f32_16x16x32_bf16 v[124:127], v[152:155], v[160:163], v[124:127]
	v_mfma_f32_16x16x32_bf16 v[104:107], v[144:147], v[168:171], v[104:107]
	v_mfma_f32_16x16x32_bf16 v[100:103], v[152:155], v[168:171], v[100:103]
	v_mfma_f32_16x16x32_bf16 v[84:87], v[144:147], v[176:179], v[84:87]
	v_mfma_f32_16x16x32_bf16 v[80:83], v[152:155], v[176:179], v[80:83]
	v_mfma_f32_16x16x32_bf16 v[68:71], v[144:147], v[202:205], v[68:71]
	v_mfma_f32_16x16x32_bf16 v[64:67], v[152:155], v[202:205], v[64:67]
	v_mfma_f32_16x16x32_bf16 v[132:135], v[148:151], v[164:167], v[132:135]
	v_mfma_f32_16x16x32_bf16 v[124:127], v[156:159], v[164:167], v[124:127]
	v_mfma_f32_16x16x32_bf16 v[104:107], v[148:151], v[172:175], v[104:107]
	v_mfma_f32_16x16x32_bf16 v[100:103], v[156:159], v[172:175], v[100:103]
	v_mfma_f32_16x16x32_bf16 v[84:87], v[148:151], v[180:183], v[84:87]
	v_mfma_f32_16x16x32_bf16 v[80:83], v[156:159], v[180:183], v[80:83]
	v_mfma_f32_16x16x32_bf16 v[68:71], v[148:151], v[206:209], v[68:71]
	v_mfma_f32_16x16x32_bf16 v[64:67], v[156:159], v[206:209], v[64:67]
	s_barrier
	s_add_i32 s46, s71, s48
	s_mov_b32 m0, s46
	ds_read_b128 v[160:163], v224 offset:49152
	ds_read_b128 v[164:167], v224 offset:50176
	ds_read_b128 v[168:171], v224 offset:51200
	ds_read_b128 v[172:175], v224 offset:52224
	ds_read_b128 v[176:179], v224 offset:53248
	ds_read_b128 v[180:183], v224 offset:54272
	ds_read_b128 v[202:205], v224 offset:55296
	ds_read_b128 v[206:209], v224 offset:56320
	global_load_lds_dwordx4 v186, s[98:99]
	s_add_i32 m0, s46, 0x2000
	s_add_u32 s34, s34, 0xb0080
	s_addc_u32 s35, s35, 0
	s_add_i32 s46, s72, s48
	global_load_lds_dwordx4 v190, s[98:99]
	s_mov_b32 m0, s46
	s_nop 0
	global_load_lds_dwordx4 v186, s[34:35]
	s_add_i32 m0, s46, 0x2000
	s_nop 0
	global_load_lds_dwordx4 v190, s[34:35]
	s_mov_b32 m0, s57
	s_nop 0
	global_load_lds_dwordx4 v184, s[100:101]
	s_mov_b32 m0, s58
	s_nop 0
	global_load_lds_dwordx4 v188, s[100:101]
	s_waitcnt vmcnt(8)
	s_waitcnt lgkmcnt(0)
	s_barrier
	v_mfma_f32_16x16x32_bf16 v[60:63], v[96:99], v[160:163], v[60:63]
	v_mfma_f32_16x16x32_bf16 v[56:59], v[120:123], v[160:163], v[56:59]
	v_mfma_f32_16x16x32_bf16 v[44:47], v[96:99], v[168:171], v[44:47]
	v_mfma_f32_16x16x32_bf16 v[40:43], v[120:123], v[168:171], v[40:43]
	v_mfma_f32_16x16x32_bf16 v[28:31], v[96:99], v[176:179], v[28:31]
	v_mfma_f32_16x16x32_bf16 v[24:27], v[120:123], v[176:179], v[24:27]
	v_mfma_f32_16x16x32_bf16 v[12:15], v[96:99], v[202:205], v[12:15]
	v_mfma_f32_16x16x32_bf16 v[8:11], v[120:123], v[202:205], v[8:11]
	v_mfma_f32_16x16x32_bf16 v[60:63], v[108:111], v[164:167], v[60:63]
	v_mfma_f32_16x16x32_bf16 v[56:59], v[128:131], v[164:167], v[56:59]
	v_mfma_f32_16x16x32_bf16 v[44:47], v[108:111], v[172:175], v[44:47]
	v_mfma_f32_16x16x32_bf16 v[40:43], v[128:131], v[172:175], v[40:43]
	v_mfma_f32_16x16x32_bf16 v[28:31], v[108:111], v[180:183], v[28:31]
	v_mfma_f32_16x16x32_bf16 v[24:27], v[128:131], v[180:183], v[24:27]
	v_mfma_f32_16x16x32_bf16 v[12:15], v[108:111], v[206:209], v[12:15]
	v_mfma_f32_16x16x32_bf16 v[8:11], v[128:131], v[206:209], v[8:11]
	v_mfma_f32_16x16x32_bf16 v[52:55], v[144:147], v[160:163], v[52:55]
	v_mfma_f32_16x16x32_bf16 v[48:51], v[152:155], v[160:163], v[48:51]
	v_mfma_f32_16x16x32_bf16 v[36:39], v[144:147], v[168:171], v[36:39]
	v_mfma_f32_16x16x32_bf16 v[32:35], v[152:155], v[168:171], v[32:35]
	v_mfma_f32_16x16x32_bf16 v[20:23], v[144:147], v[176:179], v[20:23]
	v_mfma_f32_16x16x32_bf16 v[16:19], v[152:155], v[176:179], v[16:19]
	v_mfma_f32_16x16x32_bf16 v[4:7], v[144:147], v[202:205], v[4:7]
	v_mfma_f32_16x16x32_bf16 v[0:3], v[152:155], v[202:205], v[0:3]
	v_mfma_f32_16x16x32_bf16 v[52:55], v[148:151], v[164:167], v[52:55]
	v_mfma_f32_16x16x32_bf16 v[48:51], v[156:159], v[164:167], v[48:51]
	v_mfma_f32_16x16x32_bf16 v[36:39], v[148:151], v[172:175], v[36:39]
	v_mfma_f32_16x16x32_bf16 v[32:35], v[156:159], v[172:175], v[32:35]
	v_mfma_f32_16x16x32_bf16 v[20:23], v[148:151], v[180:183], v[20:23]
	v_mfma_f32_16x16x32_bf16 v[16:19], v[156:159], v[180:183], v[16:19]
	v_mfma_f32_16x16x32_bf16 v[4:7], v[148:151], v[206:209], v[4:7]
	v_mfma_f32_16x16x32_bf16 v[0:3], v[156:159], v[206:209], v[0:3]
	s_barrier
	s_add_i32 s70, s70, 2
	s_add_u32 s20, s20, 0x100
	s_addc_u32 s21, s21, 0
	s_add_u32 s68, s68, 0x100
	s_addc_u32 s69, s69, 0
	s_cmp_gt_u32 s70, 41
